# K-loop load parts: M0-to-DMA wait state covered by the last ds_read or the counted vmcnt wait instead of s_nop
# baseline (speedup 1.0000x reference)
; #define PG8_STAGE(bufoff, gbase, voff) do { _Pragma("unroll") for (int _i = 0; _i < 2; ++_i) \
;         __builtin_amdgcn_global_load_lds((const unsigned*)((const char*)(gbase) + (voff)[_i]), (LAS unsigned*)(lds + (bufoff) + ldsw + _i * 8192), 16, 0, 0); } while (0)
; #define PG8_LDA(dst, b, h) do { _Pragma("unroll") for (int m = 0; m < 4; ++m) _Pragma("unroll") for (int k = 0; k < 2; ++k) dst[m][k] = *(const LAS bf16x8*)(lds + PG8_SA(b, h) + aoff + m * 2048 + k * 1024); } while (0)
; #define PG8_LDB(dst, b, h) do { _Pragma("unroll") for (int n = 0; n < 2; ++n) _Pragma("unroll") for (int k = 0; k < 2; ++k) dst[n][k] = *(const LAS bf16x8*)(lds + PG8_SB(b, h) + boff + n * 2048 + k * 1024); } while (0)
; template <class Epi>
; DI void gemm_phase(LAS unsigned char* lds, const Gemm g, const StaticOrder& S, const Epi& E) {
;     ...
;         const bool has_next = S.next(ui + 1, nxt);
;         const char* nA = has_next ? (const char*)g.A + (size_t)nxt.pm * tstep : cA; const char* nB = has_next ? (const char*)g.Bt + (size_t)nxt.pn * tstep : cB;
;         for (int t = 0; t < nt; t += 2) {
;             const bool last = (t == nt - 2);
;             const char* a1 = cA + (size_t)(t + 1) * kstep;
;             const char* a2 = last ? nA : cA + (size_t)(t + 2) * kstep; const char* b2 = last ? nB : cB + (size_t)(t + 2) * kstep;
;             const char* a3 = a2 + kstep; const char* b3 = b2 + kstep;
;             PG8_LDB(B0, 0, 0); PG8_SCHED; PG8_LDA(At, 0, 0); PG8_STAGE(PG8_SA(1, 1), a1 + hstep, voffA);
;             PG8_WAIT_L(8); PG8_BAR; PG8_WAIT_L(0); PG8_MMA(0, 0, At, B0); PG8_BAR; PG8_SCHED;
;             PG8_LDB(B1, 0, 1); PG8_STAGE(PG8_SB(0, 0), b2, voffB);
;             PG8_BAR; PG8_WAIT_L(0); PG8_MMA(0, 1, At, B1); PG8_BAR;
;             PG8_LDA(At, 0, 1); PG8_STAGE(PG8_SA(0, 0), a2, voffA);
;             PG8_BAR; PG8_WAIT_L(0); PG8_MMA(1, 0, At, B0); PG8_BAR; PG8_SCHED;
;             PG8_STAGE(PG8_SB(0, 1), b2 + hstep, voffB);
;             PG8_WAIT_V(6); PG8_BAR; PG8_MMA(1, 1, At, B1); PG8_BAR;
;             PG8_LDB(B0, 1, 0); PG8_SCHED; PG8_LDA(At, 1, 0); PG8_STAGE(PG8_SA(0, 1), a2 + hstep, voffA);
;             PG8_WAIT_L(8); PG8_BAR; PG8_WAIT_L(0); PG8_MMA(0, 0, At, B0); PG8_BAR; PG8_SCHED;
;             PG8_LDB(B1, 1, 1); PG8_STAGE(PG8_SB(1, 0), b3, voffB);
;             PG8_BAR; PG8_WAIT_L(0); PG8_MMA(0, 1, At, B1); PG8_BAR;
.LBB0_210:
	s_ashr_i32 s17, s16, 31
	v_cmp_lt_i64_e32 vcc, s[18:19], v[140:141]
	s_lshl_b64 s[18:19], s[16:17], 19
	s_add_u32 s18, s43, s18
	s_addc_u32 s19, s44, s19
	s_and_b64 s[22:23], vcc, exec
	s_cselect_b32 s17, s19, s25
	s_cselect_b32 s76, s18, s24
	s_ashr_i32 s15, s14, 31
	s_lshl_b64 s[22:23], s[14:15], 19
	s_add_u32 s22, s30, s22
	s_addc_u32 s23, s31, s23
	s_and_b64 s[40:41], vcc, exec
	s_cselect_b32 s15, s23, s39
	s_cselect_b32 s77, s22, s38
	s_add_u32 s24, s24, 0x40080
	s_addc_u32 s25, s25, 0
	s_add_u32 s78, s38, 0x100
	s_addc_u32 s79, s39, 0
	s_mov_b32 s80, -2
	v_add_u32_e32 v253, 0x18000, v145
	v_add_u32_e32 v252, 0x1c000, v145
	ds_read_b128 v[150:153], v147
	ds_read_b128 v[154:157], v147 offset:1024
	ds_read_b128 v[158:161], v147 offset:2048
	ds_read_b128 v[162:165], v147 offset:3072
	s_add_u32 s38, s24, 0xfffc0080
	s_addc_u32 s39, s25, -1
	s_cmp_eq_u32 s80, 12
	s_cselect_b32 s41, s17, s39
	s_cselect_b32 s40, s76, s38
	s_cselect_b32 s39, s15, s79
	s_cselect_b32 s38, s77, s78
	s_add_i32 m0, s13, 0xc000
	ds_read_b128 v[166:169], v148
	ds_read_b128 v[170:173], v148 offset:1024
	ds_read_b128 v[174:177], v148 offset:2048
	ds_read_b128 v[182:185], v148 offset:3072
	ds_read_b128 v[186:189], v148 offset:4096
	ds_read_b128 v[190:193], v148 offset:5120
	ds_read_b128 v[194:197], v148 offset:6144
	global_load_lds_dwordx4 v136, s[24:25]
	s_add_i32 m0, s13, 0xe000
	ds_read_b128 v[198:201], v148 offset:7168
	global_load_lds_dwordx4 v138, s[24:25]
	s_waitcnt lgkmcnt(8)
	s_barrier
	s_waitcnt lgkmcnt(7)
	v_mfma_f32_16x16x32_bf16 v[124:127], v[150:153], v[166:169], 0
	v_mfma_f32_16x16x32_bf16 v[120:123], v[158:161], v[166:169], 0
	s_waitcnt lgkmcnt(5)
	v_mfma_f32_16x16x32_bf16 v[116:119], v[150:153], v[174:177], 0
	v_mfma_f32_16x16x32_bf16 v[112:115], v[158:161], v[174:177], 0
	s_waitcnt lgkmcnt(3)
	v_mfma_f32_16x16x32_bf16 v[100:103], v[150:153], v[186:189], 0
	v_mfma_f32_16x16x32_bf16 v[96:99], v[158:161], v[186:189], 0
	s_waitcnt lgkmcnt(1)
	v_mfma_f32_16x16x32_bf16 v[84:87], v[150:153], v[194:197], 0
	v_mfma_f32_16x16x32_bf16 v[80:83], v[158:161], v[194:197], 0
	v_mfma_f32_16x16x32_bf16 v[124:127], v[154:157], v[170:173], v[124:127]
	v_mfma_f32_16x16x32_bf16 v[120:123], v[162:165], v[170:173], v[120:123]
	v_mfma_f32_16x16x32_bf16 v[116:119], v[154:157], v[182:185], v[116:119]
	v_mfma_f32_16x16x32_bf16 v[112:115], v[162:165], v[182:185], v[112:115]
	v_mfma_f32_16x16x32_bf16 v[100:103], v[154:157], v[190:193], v[100:103]
	v_mfma_f32_16x16x32_bf16 v[96:99], v[162:165], v[190:193], v[96:99]
	s_add_i32 s81, s71, s45
	s_add_u32 s86, s38, s8
	s_waitcnt lgkmcnt(0)
	v_mfma_f32_16x16x32_bf16 v[84:87], v[154:157], v[198:201], v[84:87]
	s_addc_u32 s87, s39, s9
	s_mov_b32 m0, s81
	v_mfma_f32_16x16x32_bf16 v[80:83], v[162:165], v[198:201], v[80:83]
	s_barrier
	ds_read_b128 v[202:205], v149
	ds_read_b128 v[206:209], v149 offset:1024
	ds_read_b128 v[210:213], v149 offset:2048
	global_load_lds_dwordx4 v132, s[38:39]
	s_add_i32 m0, s81, 0x2000
	ds_read_b128 v[214:217], v149 offset:3072
	global_load_lds_dwordx4 v128, s[38:39]
	s_barrier
	s_waitcnt lgkmcnt(3)
	v_mfma_f32_16x16x32_bf16 v[108:111], v[202:205], v[166:169], 0
	s_waitcnt lgkmcnt(1)
	v_mfma_f32_16x16x32_bf16 v[104:107], v[210:213], v[166:169], 0
	v_mfma_f32_16x16x32_bf16 v[92:95], v[202:205], v[174:177], 0
	v_mfma_f32_16x16x32_bf16 v[88:91], v[210:213], v[174:177], 0
	v_mfma_f32_16x16x32_bf16 v[76:79], v[202:205], v[186:189], 0
	v_mfma_f32_16x16x32_bf16 v[72:75], v[210:213], v[186:189], 0
	v_mfma_f32_16x16x32_bf16 v[68:71], v[202:205], v[194:197], 0
	v_mfma_f32_16x16x32_bf16 v[64:67], v[210:213], v[194:197], 0
	v_mfma_f32_16x16x32_bf16 v[108:111], v[206:209], v[170:173], v[108:111]
	s_waitcnt lgkmcnt(0)
	v_mfma_f32_16x16x32_bf16 v[104:107], v[214:217], v[170:173], v[104:107]
	v_mfma_f32_16x16x32_bf16 v[92:95], v[206:209], v[182:185], v[92:95]
	v_mfma_f32_16x16x32_bf16 v[88:91], v[214:217], v[182:185], v[88:91]
	v_mfma_f32_16x16x32_bf16 v[76:79], v[206:209], v[190:193], v[76:79]
	v_mfma_f32_16x16x32_bf16 v[72:75], v[214:217], v[190:193], v[72:75]
	s_mov_b32 m0, s13
	s_add_u32 s88, s40, s8
	v_mfma_f32_16x16x32_bf16 v[68:71], v[206:209], v[198:201], v[68:71]
	s_addc_u32 s89, s41, s9
	v_mfma_f32_16x16x32_bf16 v[64:67], v[214:217], v[198:201], v[64:67]
	s_barrier
	ds_read_b128 v[166:169], v148 offset:16384
	ds_read_b128 v[170:173], v148 offset:17408
	ds_read_b128 v[174:177], v148 offset:18432
	ds_read_b128 v[182:185], v148 offset:19456
	ds_read_b128 v[186:189], v148 offset:20480
	ds_read_b128 v[190:193], v148 offset:21504
	ds_read_b128 v[194:197], v148 offset:22528
	global_load_lds_dwordx4 v134, s[40:41]
	s_mov_b32 m0, s48
	ds_read_b128 v[198:201], v148 offset:23552
	global_load_lds_dwordx4 v130, s[40:41]
	s_barrier
	s_waitcnt lgkmcnt(7)
	v_mfma_f32_16x16x32_bf16 v[60:63], v[150:153], v[166:169], 0
	v_mfma_f32_16x16x32_bf16 v[56:59], v[158:161], v[166:169], 0
	s_waitcnt lgkmcnt(5)
	v_mfma_f32_16x16x32_bf16 v[52:55], v[150:153], v[174:177], 0
	v_mfma_f32_16x16x32_bf16 v[48:51], v[158:161], v[174:177], 0
	s_waitcnt lgkmcnt(3)
	v_mfma_f32_16x16x32_bf16 v[36:39], v[150:153], v[186:189], 0
	v_mfma_f32_16x16x32_bf16 v[32:35], v[158:161], v[186:189], 0
	s_waitcnt lgkmcnt(1)
	v_mfma_f32_16x16x32_bf16 v[20:23], v[150:153], v[194:197], 0
	v_mfma_f32_16x16x32_bf16 v[16:19], v[158:161], v[194:197], 0
	v_mfma_f32_16x16x32_bf16 v[60:63], v[154:157], v[170:173], v[60:63]
	v_mfma_f32_16x16x32_bf16 v[56:59], v[162:165], v[170:173], v[56:59]
	v_mfma_f32_16x16x32_bf16 v[52:55], v[154:157], v[182:185], v[52:55]
	v_mfma_f32_16x16x32_bf16 v[48:51], v[162:165], v[182:185], v[48:51]
	v_mfma_f32_16x16x32_bf16 v[36:39], v[154:157], v[190:193], v[36:39]
	v_mfma_f32_16x16x32_bf16 v[32:35], v[162:165], v[190:193], v[32:35]
	s_add_u32 s82, s38, 0x40000
	s_addc_u32 s83, s39, 0
	s_waitcnt lgkmcnt(0)
	v_mfma_f32_16x16x32_bf16 v[20:23], v[154:157], v[198:201], v[20:23]
	s_add_i32 s81, s72, s45
	s_mov_b32 m0, s81
	v_mfma_f32_16x16x32_bf16 v[16:19], v[162:165], v[198:201], v[16:19]
	s_barrier
; #define PG8_STAGE(bufoff, gbase, voff) do { _Pragma("unroll") for (int _i = 0; _i < 2; ++_i) \
;         __builtin_amdgcn_global_load_lds((const unsigned*)((const char*)(gbase) + (voff)[_i]), (LAS unsigned*)(lds + (bufoff) + ldsw + _i * 8192), 16, 0, 0); } while (0)
; #define PG8_LDA(dst, b, h) do { _Pragma("unroll") for (int m = 0; m < 4; ++m) _Pragma("unroll") for (int k = 0; k < 2; ++k) dst[m][k] = *(const LAS bf16x8*)(lds + PG8_SA(b, h) + aoff + m * 2048 + k * 1024); } while (0)
; #define PG8_LDB(dst, b, h) do { _Pragma("unroll") for (int n = 0; n < 2; ++n) _Pragma("unroll") for (int k = 0; k < 2; ++k) dst[n][k] = *(const LAS bf16x8*)(lds + PG8_SB(b, h) + boff + n * 2048 + k * 1024); } while (0)
; #define PG8_MMA(ai, bj, At, Bt) do { __builtin_amdgcn_s_setprio(1); _Pragma("unroll") for (int m = 0; m < 4; ++m) _Pragma("unroll") for (int n = 0; n < 2; ++n) _Pragma("unroll") for (int k = 0; k < 2; ++k) \
;         acc[ai][bj][m][n] = __builtin_amdgcn_mfma_f32_16x16x32_bf16(Bt[n][k], At[m][k], acc[ai][bj][m][n], 0, 0, 0); __builtin_amdgcn_s_setprio(0); } while (0)
; #define PG8_WAIT_V(n) asm volatile("s_waitcnt vmcnt(" #n ")" ::: "memory")
; #define PG8_WAIT_L(n) asm volatile("s_waitcnt lgkmcnt(" #n ")" ::: "memory")
; #define PG8_BAR __builtin_amdgcn_s_barrier()
; #define PG8_SCHED __builtin_amdgcn_sched_barrier(0)
; template <class Epi>
; DI void gemm_phase(LAS unsigned char* lds, const Gemm g, const StaticOrder& S, const Epi& E) {
;     ...
;             PG8_LDA(At, 0, 1); PG8_STAGE(PG8_SA(0, 0), a2, voffA);
;             PG8_BAR; PG8_WAIT_L(0); PG8_MMA(1, 0, At, B0); PG8_BAR; PG8_SCHED;
;             PG8_STAGE(PG8_SB(0, 1), b2 + hstep, voffB);
;             PG8_WAIT_V(6); PG8_BAR; PG8_MMA(1, 1, At, B1); PG8_BAR;
;             PG8_LDB(B0, 1, 0); PG8_SCHED; PG8_LDA(At, 1, 0); PG8_STAGE(PG8_SA(0, 1), a2 + hstep, voffA);
;             PG8_WAIT_L(8); PG8_BAR; PG8_WAIT_L(0); PG8_MMA(0, 0, At, B0); PG8_BAR; PG8_SCHED;
;             PG8_LDB(B1, 1, 1); PG8_STAGE(PG8_SB(1, 0), b3, voffB);
;             PG8_BAR; PG8_WAIT_L(0); PG8_MMA(0, 1, At, B1); PG8_BAR;
	global_load_lds_dwordx4 v132, s[82:83]
	s_add_i32 m0, s81, 0x2000
	s_waitcnt vmcnt(5)
	global_load_lds_dwordx4 v128, s[82:83]
	s_barrier
	v_mfma_f32_16x16x32_bf16 v[44:47], v[202:205], v[166:169], 0
	v_mfma_f32_16x16x32_bf16 v[40:43], v[210:213], v[166:169], 0
	v_mfma_f32_16x16x32_bf16 v[28:31], v[202:205], v[174:177], 0
	v_mfma_f32_16x16x32_bf16 v[24:27], v[210:213], v[174:177], 0
	v_mfma_f32_16x16x32_bf16 v[12:15], v[202:205], v[186:189], 0
	v_mfma_f32_16x16x32_bf16 v[8:11], v[210:213], v[186:189], 0
	v_mfma_f32_16x16x32_bf16 v[4:7], v[202:205], v[194:197], 0
	v_mfma_f32_16x16x32_bf16 v[0:3], v[210:213], v[194:197], 0
	v_mfma_f32_16x16x32_bf16 v[44:47], v[206:209], v[170:173], v[44:47]
	v_mfma_f32_16x16x32_bf16 v[40:43], v[214:217], v[170:173], v[40:43]
	v_mfma_f32_16x16x32_bf16 v[28:31], v[206:209], v[182:185], v[28:31]
	v_mfma_f32_16x16x32_bf16 v[24:27], v[214:217], v[182:185], v[24:27]
	v_mfma_f32_16x16x32_bf16 v[12:15], v[206:209], v[190:193], v[12:15]
	v_mfma_f32_16x16x32_bf16 v[8:11], v[214:217], v[190:193], v[8:11]
	v_mfma_f32_16x16x32_bf16 v[4:7], v[206:209], v[198:201], v[4:7]
	s_add_i32 s81, 0, 0x18000
	v_mfma_f32_16x16x32_bf16 v[0:3], v[214:217], v[198:201], v[0:3]
	s_barrier
	ds_read_b128 v[150:153], v253
	ds_read_b128 v[154:157], v253 offset:1024
	ds_read_b128 v[158:161], v253 offset:2048
	ds_read_b128 v[162:165], v253 offset:3072
	s_add_u32 s40, s40, 0x40000
	s_addc_u32 s41, s41, 0
	s_mov_b32 m0, s49
	ds_read_b128 v[166:169], v148 offset:32768
	ds_read_b128 v[170:173], v148 offset:33792
	ds_read_b128 v[174:177], v148 offset:34816
	ds_read_b128 v[182:185], v148 offset:35840
	ds_read_b128 v[186:189], v148 offset:36864
	ds_read_b128 v[190:193], v148 offset:37888
	ds_read_b128 v[194:197], v148 offset:38912
	global_load_lds_dwordx4 v134, s[40:41]
	s_mov_b32 m0, s50
	ds_read_b128 v[198:201], v148 offset:39936
	global_load_lds_dwordx4 v130, s[40:41]
	s_waitcnt lgkmcnt(8)
	s_barrier
	s_waitcnt lgkmcnt(7)
	v_mfma_f32_16x16x32_bf16 v[124:127], v[150:153], v[166:169], v[124:127]
	v_mfma_f32_16x16x32_bf16 v[120:123], v[158:161], v[166:169], v[120:123]
	s_waitcnt lgkmcnt(5)
	v_mfma_f32_16x16x32_bf16 v[116:119], v[150:153], v[174:177], v[116:119]
	v_mfma_f32_16x16x32_bf16 v[112:115], v[158:161], v[174:177], v[112:115]
	s_waitcnt lgkmcnt(3)
	v_mfma_f32_16x16x32_bf16 v[100:103], v[150:153], v[186:189], v[100:103]
	v_mfma_f32_16x16x32_bf16 v[96:99], v[158:161], v[186:189], v[96:99]
	s_waitcnt lgkmcnt(1)
	v_mfma_f32_16x16x32_bf16 v[84:87], v[150:153], v[194:197], v[84:87]
	v_mfma_f32_16x16x32_bf16 v[80:83], v[158:161], v[194:197], v[80:83]
	v_mfma_f32_16x16x32_bf16 v[124:127], v[154:157], v[170:173], v[124:127]
	v_mfma_f32_16x16x32_bf16 v[120:123], v[162:165], v[170:173], v[120:123]
	v_mfma_f32_16x16x32_bf16 v[116:119], v[154:157], v[182:185], v[116:119]
	v_mfma_f32_16x16x32_bf16 v[112:115], v[162:165], v[182:185], v[112:115]
	v_mfma_f32_16x16x32_bf16 v[100:103], v[154:157], v[190:193], v[100:103]
	v_mfma_f32_16x16x32_bf16 v[96:99], v[162:165], v[190:193], v[96:99]
	s_add_i32 s40, 0, 0x1c000
	s_add_i32 s41, s81, s45
	s_waitcnt lgkmcnt(0)
	v_mfma_f32_16x16x32_bf16 v[84:87], v[154:157], v[198:201], v[84:87]
	s_mov_b32 m0, s41
	v_mfma_f32_16x16x32_bf16 v[80:83], v[162:165], v[198:201], v[80:83]
	s_barrier
	ds_read_b128 v[202:205], v252
	ds_read_b128 v[206:209], v252 offset:1024
	ds_read_b128 v[210:213], v252 offset:2048
	global_load_lds_dwordx4 v132, s[86:87]
	s_add_i32 m0, s41, 0x2000
	ds_read_b128 v[214:217], v252 offset:3072
	global_load_lds_dwordx4 v128, s[86:87]
	s_barrier
	s_waitcnt lgkmcnt(3)
	v_mfma_f32_16x16x32_bf16 v[108:111], v[202:205], v[166:169], v[108:111]
	s_waitcnt lgkmcnt(1)
	v_mfma_f32_16x16x32_bf16 v[104:107], v[210:213], v[166:169], v[104:107]
	v_mfma_f32_16x16x32_bf16 v[92:95], v[202:205], v[174:177], v[92:95]
	v_mfma_f32_16x16x32_bf16 v[88:91], v[210:213], v[174:177], v[88:91]
	v_mfma_f32_16x16x32_bf16 v[76:79], v[202:205], v[186:189], v[76:79]
	v_mfma_f32_16x16x32_bf16 v[72:75], v[210:213], v[186:189], v[72:75]
	v_mfma_f32_16x16x32_bf16 v[68:71], v[202:205], v[194:197], v[68:71]
	v_mfma_f32_16x16x32_bf16 v[64:67], v[210:213], v[194:197], v[64:67]
	v_mfma_f32_16x16x32_bf16 v[108:111], v[206:209], v[170:173], v[108:111]
	s_waitcnt lgkmcnt(0)
	v_mfma_f32_16x16x32_bf16 v[104:107], v[214:217], v[170:173], v[104:107]
	v_mfma_f32_16x16x32_bf16 v[92:95], v[206:209], v[182:185], v[92:95]
	v_mfma_f32_16x16x32_bf16 v[88:91], v[214:217], v[182:185], v[88:91]
	v_mfma_f32_16x16x32_bf16 v[76:79], v[206:209], v[190:193], v[76:79]
	v_mfma_f32_16x16x32_bf16 v[72:75], v[214:217], v[190:193], v[72:75]
	v_mfma_f32_16x16x32_bf16 v[68:71], v[206:209], v[198:201], v[68:71]
	s_mov_b32 m0, s66
	v_mfma_f32_16x16x32_bf16 v[64:67], v[214:217], v[198:201], v[64:67]
	s_barrier
	ds_read_b128 v[166:169], v148 offset:49152
	ds_read_b128 v[170:173], v148 offset:50176
	ds_read_b128 v[174:177], v148 offset:51200
	ds_read_b128 v[182:185], v148 offset:52224
	ds_read_b128 v[186:189], v148 offset:53248
	ds_read_b128 v[190:193], v148 offset:54272
	ds_read_b128 v[194:197], v148 offset:55296
	global_load_lds_dwordx4 v134, s[88:89]
	s_mov_b32 m0, s67
	ds_read_b128 v[198:201], v148 offset:56320
	global_load_lds_dwordx4 v130, s[88:89]
	s_barrier
; #define PG8_STAGE(bufoff, gbase, voff) do { _Pragma("unroll") for (int _i = 0; _i < 2; ++_i) \
;         __builtin_amdgcn_global_load_lds((const unsigned*)((const char*)(gbase) + (voff)[_i]), (LAS unsigned*)(lds + (bufoff) + ldsw + _i * 8192), 16, 0, 0); } while (0)
; #define PG8_LDA(dst, b, h) do { _Pragma("unroll") for (int m = 0; m < 4; ++m) _Pragma("unroll") for (int k = 0; k < 2; ++k) dst[m][k] = *(const LAS bf16x8*)(lds + PG8_SA(b, h) + aoff + m * 2048 + k * 1024); } while (0)
; #define PG8_LDB(dst, b, h) do { _Pragma("unroll") for (int n = 0; n < 2; ++n) _Pragma("unroll") for (int k = 0; k < 2; ++k) dst[n][k] = *(const LAS bf16x8*)(lds + PG8_SB(b, h) + boff + n * 2048 + k * 1024); } while (0)
; #define PG8_MMA(ai, bj, At, Bt) do { __builtin_amdgcn_s_setprio(1); _Pragma("unroll") for (int m = 0; m < 4; ++m) _Pragma("unroll") for (int n = 0; n < 2; ++n) _Pragma("unroll") for (int k = 0; k < 2; ++k) \
;         acc[ai][bj][m][n] = __builtin_amdgcn_mfma_f32_16x16x32_bf16(Bt[n][k], At[m][k], acc[ai][bj][m][n], 0, 0, 0); __builtin_amdgcn_s_setprio(0); } while (0)
; #define PG8_WAIT_V(n) asm volatile("s_waitcnt vmcnt(" #n ")" ::: "memory")
; #define PG8_WAIT_L(n) asm volatile("s_waitcnt lgkmcnt(" #n ")" ::: "memory")
; #define PG8_BAR __builtin_amdgcn_s_barrier()
; #define PG8_SCHED __builtin_amdgcn_sched_barrier(0)
; template <class Epi>
; DI void gemm_phase(LAS unsigned char* lds, const Gemm g, const StaticOrder& S, const Epi& E) {
;     ...
;             PG8_LDB(B0, 0, 0); PG8_SCHED; PG8_LDA(At, 0, 0); PG8_STAGE(PG8_SA(1, 1), a1 + hstep, voffA);
;             PG8_WAIT_L(8); PG8_BAR; PG8_WAIT_L(0); PG8_MMA(0, 0, At, B0); PG8_BAR; PG8_SCHED;
;     ...
;             PG8_WAIT_V(6); PG8_BAR; PG8_MMA(1, 1, At, B1); PG8_BAR;
;             PG8_LDB(B0, 1, 0); PG8_SCHED; PG8_LDA(At, 1, 0); PG8_STAGE(PG8_SA(0, 1), a2 + hstep, voffA);
;             PG8_WAIT_L(8); PG8_BAR; PG8_WAIT_L(0); PG8_MMA(0, 0, At, B0); PG8_BAR; PG8_SCHED;
;             PG8_LDB(B1, 1, 1); PG8_STAGE(PG8_SB(1, 0), b3, voffB);
;             PG8_BAR; PG8_WAIT_L(0); PG8_MMA(0, 1, At, B1); PG8_BAR;
;             PG8_LDA(At, 1, 1); PG8_STAGE(PG8_SA(1, 0), a3, voffA);
;             PG8_BAR; PG8_WAIT_L(0); PG8_MMA(1, 0, At, B0); PG8_BAR; PG8_SCHED;
;             PG8_STAGE(PG8_SB(1, 1), b3 + hstep, voffB);
;             PG8_WAIT_V(6); PG8_BAR; PG8_MMA(1, 1, At, B1); PG8_BAR;
	s_waitcnt lgkmcnt(7)
	v_mfma_f32_16x16x32_bf16 v[60:63], v[150:153], v[166:169], v[60:63]
	v_mfma_f32_16x16x32_bf16 v[56:59], v[158:161], v[166:169], v[56:59]
	s_waitcnt lgkmcnt(5)
	v_mfma_f32_16x16x32_bf16 v[52:55], v[150:153], v[174:177], v[52:55]
	v_mfma_f32_16x16x32_bf16 v[48:51], v[158:161], v[174:177], v[48:51]
	s_waitcnt lgkmcnt(3)
	v_mfma_f32_16x16x32_bf16 v[36:39], v[150:153], v[186:189], v[36:39]
	v_mfma_f32_16x16x32_bf16 v[32:35], v[158:161], v[186:189], v[32:35]
	s_waitcnt lgkmcnt(1)
	v_mfma_f32_16x16x32_bf16 v[20:23], v[150:153], v[194:197], v[20:23]
	v_mfma_f32_16x16x32_bf16 v[16:19], v[158:161], v[194:197], v[16:19]
	v_mfma_f32_16x16x32_bf16 v[60:63], v[154:157], v[170:173], v[60:63]
	v_mfma_f32_16x16x32_bf16 v[56:59], v[162:165], v[170:173], v[56:59]
	v_mfma_f32_16x16x32_bf16 v[52:55], v[154:157], v[182:185], v[52:55]
	v_mfma_f32_16x16x32_bf16 v[48:51], v[162:165], v[182:185], v[48:51]
	v_mfma_f32_16x16x32_bf16 v[36:39], v[154:157], v[190:193], v[36:39]
	v_mfma_f32_16x16x32_bf16 v[32:35], v[162:165], v[190:193], v[32:35]
	s_add_u32 s38, s38, 0x40080
	s_addc_u32 s39, s39, 0
	s_waitcnt lgkmcnt(0)
	v_mfma_f32_16x16x32_bf16 v[20:23], v[154:157], v[198:201], v[20:23]
	s_add_i32 s40, s40, s45
	s_mov_b32 m0, s40
	v_mfma_f32_16x16x32_bf16 v[16:19], v[162:165], v[198:201], v[16:19]
	s_barrier
	global_load_lds_dwordx4 v132, s[38:39]
	s_add_i32 m0, s40, 0x2000
	s_waitcnt vmcnt(5)
	global_load_lds_dwordx4 v128, s[38:39]
	s_barrier
	v_mfma_f32_16x16x32_bf16 v[44:47], v[202:205], v[166:169], v[44:47]
	v_mfma_f32_16x16x32_bf16 v[40:43], v[210:213], v[166:169], v[40:43]
	v_mfma_f32_16x16x32_bf16 v[28:31], v[202:205], v[174:177], v[28:31]
	v_mfma_f32_16x16x32_bf16 v[24:27], v[210:213], v[174:177], v[24:27]
	v_mfma_f32_16x16x32_bf16 v[12:15], v[202:205], v[186:189], v[12:15]
	v_mfma_f32_16x16x32_bf16 v[8:11], v[210:213], v[186:189], v[8:11]
	v_mfma_f32_16x16x32_bf16 v[4:7], v[202:205], v[194:197], v[4:7]
	v_mfma_f32_16x16x32_bf16 v[0:3], v[210:213], v[194:197], v[0:3]
	v_mfma_f32_16x16x32_bf16 v[44:47], v[206:209], v[170:173], v[44:47]
	s_add_i32 s80, s80, 2
	s_add_u32 s24, s24, 0x100
	v_mfma_f32_16x16x32_bf16 v[40:43], v[214:217], v[170:173], v[40:43]
	s_addc_u32 s25, s25, 0
	s_add_u32 s78, s78, 0x100
	v_mfma_f32_16x16x32_bf16 v[28:31], v[206:209], v[182:185], v[28:31]
	s_addc_u32 s79, s79, 0
	s_add_u32 s38, s24, 0xfffc0080
	v_mfma_f32_16x16x32_bf16 v[24:27], v[214:217], v[182:185], v[24:27]
	s_addc_u32 s39, s25, -1
	s_cmp_eq_u32 s80, 12
	v_mfma_f32_16x16x32_bf16 v[12:15], v[206:209], v[190:193], v[12:15]
	s_cselect_b32 s41, s17, s39
	s_cselect_b32 s40, s76, s38
	v_mfma_f32_16x16x32_bf16 v[8:11], v[214:217], v[190:193], v[8:11]
	s_cselect_b32 s39, s15, s79
	s_cselect_b32 s38, s77, s78
	v_mfma_f32_16x16x32_bf16 v[4:7], v[206:209], v[198:201], v[4:7]
	s_add_i32 m0, s13, 0xc000
	v_mfma_f32_16x16x32_bf16 v[0:3], v[214:217], v[198:201], v[0:3]
	s_cmp_gt_u32 s80, 13
	s_barrier
.LBB0_211:
	ds_read_b128 v[150:153], v147
	ds_read_b128 v[154:157], v147 offset:1024
	ds_read_b128 v[158:161], v147 offset:2048
	ds_read_b128 v[162:165], v147 offset:3072
	ds_read_b128 v[166:169], v148
	ds_read_b128 v[170:173], v148 offset:1024
	ds_read_b128 v[174:177], v148 offset:2048
	ds_read_b128 v[182:185], v148 offset:3072
	ds_read_b128 v[186:189], v148 offset:4096
	ds_read_b128 v[190:193], v148 offset:5120
	ds_read_b128 v[194:197], v148 offset:6144
	global_load_lds_dwordx4 v136, s[24:25]
	s_add_i32 m0, s13, 0xe000
	ds_read_b128 v[198:201], v148 offset:7168
	global_load_lds_dwordx4 v138, s[24:25]
	s_waitcnt lgkmcnt(8)
	s_barrier
	s_waitcnt lgkmcnt(7)
	v_mfma_f32_16x16x32_bf16 v[124:127], v[150:153], v[166:169], v[124:127]
	v_mfma_f32_16x16x32_bf16 v[120:123], v[158:161], v[166:169], v[120:123]
	s_waitcnt lgkmcnt(5)
	v_mfma_f32_16x16x32_bf16 v[116:119], v[150:153], v[174:177], v[116:119]
	v_mfma_f32_16x16x32_bf16 v[112:115], v[158:161], v[174:177], v[112:115]
	s_waitcnt lgkmcnt(3)
	v_mfma_f32_16x16x32_bf16 v[100:103], v[150:153], v[186:189], v[100:103]
	v_mfma_f32_16x16x32_bf16 v[96:99], v[158:161], v[186:189], v[96:99]
	s_waitcnt lgkmcnt(1)
	v_mfma_f32_16x16x32_bf16 v[84:87], v[150:153], v[194:197], v[84:87]
	v_mfma_f32_16x16x32_bf16 v[80:83], v[158:161], v[194:197], v[80:83]
	v_mfma_f32_16x16x32_bf16 v[124:127], v[154:157], v[170:173], v[124:127]
	v_mfma_f32_16x16x32_bf16 v[120:123], v[162:165], v[170:173], v[120:123]
	v_mfma_f32_16x16x32_bf16 v[116:119], v[154:157], v[182:185], v[116:119]
	v_mfma_f32_16x16x32_bf16 v[112:115], v[162:165], v[182:185], v[112:115]
	v_mfma_f32_16x16x32_bf16 v[100:103], v[154:157], v[190:193], v[100:103]
	v_mfma_f32_16x16x32_bf16 v[96:99], v[162:165], v[190:193], v[96:99]
	s_add_i32 s81, s71, s45
	s_add_u32 s86, s38, s8
	s_waitcnt lgkmcnt(0)
	v_mfma_f32_16x16x32_bf16 v[84:87], v[154:157], v[198:201], v[84:87]
	s_addc_u32 s87, s39, s9
	s_mov_b32 m0, s81
	v_mfma_f32_16x16x32_bf16 v[80:83], v[162:165], v[198:201], v[80:83]
	s_barrier
	ds_read_b128 v[202:205], v149
	ds_read_b128 v[206:209], v149 offset:1024
	ds_read_b128 v[210:213], v149 offset:2048
	global_load_lds_dwordx4 v132, s[38:39]
	s_add_i32 m0, s81, 0x2000
	ds_read_b128 v[214:217], v149 offset:3072
	global_load_lds_dwordx4 v128, s[38:39]
	s_barrier
; #define PG8_STAGE(bufoff, gbase, voff) do { _Pragma("unroll") for (int _i = 0; _i < 2; ++_i) \
;         __builtin_amdgcn_global_load_lds((const unsigned*)((const char*)(gbase) + (voff)[_i]), (LAS unsigned*)(lds + (bufoff) + ldsw + _i * 8192), 16, 0, 0); } while (0)
; #define PG8_LDA(dst, b, h) do { _Pragma("unroll") for (int m = 0; m < 4; ++m) _Pragma("unroll") for (int k = 0; k < 2; ++k) dst[m][k] = *(const LAS bf16x8*)(lds + PG8_SA(b, h) + aoff + m * 2048 + k * 1024); } while (0)
; #define PG8_LDB(dst, b, h) do { _Pragma("unroll") for (int n = 0; n < 2; ++n) _Pragma("unroll") for (int k = 0; k < 2; ++k) dst[n][k] = *(const LAS bf16x8*)(lds + PG8_SB(b, h) + boff + n * 2048 + k * 1024); } while (0)
; #define PG8_MMA(ai, bj, At, Bt) do { __builtin_amdgcn_s_setprio(1); _Pragma("unroll") for (int m = 0; m < 4; ++m) _Pragma("unroll") for (int n = 0; n < 2; ++n) _Pragma("unroll") for (int k = 0; k < 2; ++k) \
;         acc[ai][bj][m][n] = __builtin_amdgcn_mfma_f32_16x16x32_bf16(Bt[n][k], At[m][k], acc[ai][bj][m][n], 0, 0, 0); __builtin_amdgcn_s_setprio(0); } while (0)
; #define PG8_WAIT_V(n) asm volatile("s_waitcnt vmcnt(" #n ")" ::: "memory")
; #define PG8_WAIT_L(n) asm volatile("s_waitcnt lgkmcnt(" #n ")" ::: "memory")
; #define PG8_BAR __builtin_amdgcn_s_barrier()
; #define PG8_SCHED __builtin_amdgcn_sched_barrier(0)
; template <class Epi>
; DI void gemm_phase(LAS unsigned char* lds, const Gemm g, const StaticOrder& S, const Epi& E) {
;     ...
;             PG8_LDB(B1, 0, 1); PG8_STAGE(PG8_SB(0, 0), b2, voffB);
;             PG8_BAR; PG8_WAIT_L(0); PG8_MMA(0, 1, At, B1); PG8_BAR;
;             PG8_LDA(At, 0, 1); PG8_STAGE(PG8_SA(0, 0), a2, voffA);
;             PG8_BAR; PG8_WAIT_L(0); PG8_MMA(1, 0, At, B0); PG8_BAR; PG8_SCHED;
;             PG8_STAGE(PG8_SB(0, 1), b2 + hstep, voffB);
;             PG8_WAIT_V(6); PG8_BAR; PG8_MMA(1, 1, At, B1); PG8_BAR;
;             PG8_LDB(B0, 1, 0); PG8_SCHED; PG8_LDA(At, 1, 0); PG8_STAGE(PG8_SA(0, 1), a2 + hstep, voffA);
;             PG8_WAIT_L(8); PG8_BAR; PG8_WAIT_L(0); PG8_MMA(0, 0, At, B0); PG8_BAR; PG8_SCHED;
;             PG8_LDB(B1, 1, 1); PG8_STAGE(PG8_SB(1, 0), b3, voffB);
;             PG8_BAR; PG8_WAIT_L(0); PG8_MMA(0, 1, At, B1); PG8_BAR;
	s_waitcnt lgkmcnt(3)
	v_mfma_f32_16x16x32_bf16 v[108:111], v[202:205], v[166:169], v[108:111]
	s_waitcnt lgkmcnt(1)
	v_mfma_f32_16x16x32_bf16 v[104:107], v[210:213], v[166:169], v[104:107]
	v_mfma_f32_16x16x32_bf16 v[92:95], v[202:205], v[174:177], v[92:95]
	v_mfma_f32_16x16x32_bf16 v[88:91], v[210:213], v[174:177], v[88:91]
	v_mfma_f32_16x16x32_bf16 v[76:79], v[202:205], v[186:189], v[76:79]
	v_mfma_f32_16x16x32_bf16 v[72:75], v[210:213], v[186:189], v[72:75]
	v_mfma_f32_16x16x32_bf16 v[68:71], v[202:205], v[194:197], v[68:71]
	v_mfma_f32_16x16x32_bf16 v[64:67], v[210:213], v[194:197], v[64:67]
	v_mfma_f32_16x16x32_bf16 v[108:111], v[206:209], v[170:173], v[108:111]
	s_waitcnt lgkmcnt(0)
	v_mfma_f32_16x16x32_bf16 v[104:107], v[214:217], v[170:173], v[104:107]
	v_mfma_f32_16x16x32_bf16 v[92:95], v[206:209], v[182:185], v[92:95]
	v_mfma_f32_16x16x32_bf16 v[88:91], v[214:217], v[182:185], v[88:91]
	v_mfma_f32_16x16x32_bf16 v[76:79], v[206:209], v[190:193], v[76:79]
	v_mfma_f32_16x16x32_bf16 v[72:75], v[214:217], v[190:193], v[72:75]
	s_mov_b32 m0, s13
	s_add_u32 s88, s40, s8
	v_mfma_f32_16x16x32_bf16 v[68:71], v[206:209], v[198:201], v[68:71]
	s_addc_u32 s89, s41, s9
	v_mfma_f32_16x16x32_bf16 v[64:67], v[214:217], v[198:201], v[64:67]
	s_barrier
	ds_read_b128 v[166:169], v148 offset:16384
	ds_read_b128 v[170:173], v148 offset:17408
	ds_read_b128 v[174:177], v148 offset:18432
	ds_read_b128 v[182:185], v148 offset:19456
	ds_read_b128 v[186:189], v148 offset:20480
	ds_read_b128 v[190:193], v148 offset:21504
	ds_read_b128 v[194:197], v148 offset:22528
	global_load_lds_dwordx4 v134, s[40:41]
	s_mov_b32 m0, s48
	ds_read_b128 v[198:201], v148 offset:23552
	global_load_lds_dwordx4 v130, s[40:41]
	s_barrier
	s_waitcnt lgkmcnt(7)
	v_mfma_f32_16x16x32_bf16 v[60:63], v[150:153], v[166:169], v[60:63]
	v_mfma_f32_16x16x32_bf16 v[56:59], v[158:161], v[166:169], v[56:59]
	s_waitcnt lgkmcnt(5)
	v_mfma_f32_16x16x32_bf16 v[52:55], v[150:153], v[174:177], v[52:55]
	v_mfma_f32_16x16x32_bf16 v[48:51], v[158:161], v[174:177], v[48:51]
	s_waitcnt lgkmcnt(3)
	v_mfma_f32_16x16x32_bf16 v[36:39], v[150:153], v[186:189], v[36:39]
	v_mfma_f32_16x16x32_bf16 v[32:35], v[158:161], v[186:189], v[32:35]
	s_waitcnt lgkmcnt(1)
	v_mfma_f32_16x16x32_bf16 v[20:23], v[150:153], v[194:197], v[20:23]
	v_mfma_f32_16x16x32_bf16 v[16:19], v[158:161], v[194:197], v[16:19]
	v_mfma_f32_16x16x32_bf16 v[60:63], v[154:157], v[170:173], v[60:63]
	v_mfma_f32_16x16x32_bf16 v[56:59], v[162:165], v[170:173], v[56:59]
	v_mfma_f32_16x16x32_bf16 v[52:55], v[154:157], v[182:185], v[52:55]
	v_mfma_f32_16x16x32_bf16 v[48:51], v[162:165], v[182:185], v[48:51]
	v_mfma_f32_16x16x32_bf16 v[36:39], v[154:157], v[190:193], v[36:39]
	v_mfma_f32_16x16x32_bf16 v[32:35], v[162:165], v[190:193], v[32:35]
	s_add_u32 s82, s38, 0x40000
	s_addc_u32 s83, s39, 0
	s_waitcnt lgkmcnt(0)
	v_mfma_f32_16x16x32_bf16 v[20:23], v[154:157], v[198:201], v[20:23]
	s_add_i32 s81, s72, s45
	s_mov_b32 m0, s81
	v_mfma_f32_16x16x32_bf16 v[16:19], v[162:165], v[198:201], v[16:19]
	s_barrier
	global_load_lds_dwordx4 v132, s[82:83]
	s_add_i32 m0, s81, 0x2000
	s_waitcnt vmcnt(5)
	global_load_lds_dwordx4 v128, s[82:83]
	s_barrier
	v_mfma_f32_16x16x32_bf16 v[44:47], v[202:205], v[166:169], v[44:47]
	v_mfma_f32_16x16x32_bf16 v[40:43], v[210:213], v[166:169], v[40:43]
	v_mfma_f32_16x16x32_bf16 v[28:31], v[202:205], v[174:177], v[28:31]
	v_mfma_f32_16x16x32_bf16 v[24:27], v[210:213], v[174:177], v[24:27]
	v_mfma_f32_16x16x32_bf16 v[12:15], v[202:205], v[186:189], v[12:15]
	v_mfma_f32_16x16x32_bf16 v[8:11], v[210:213], v[186:189], v[8:11]
	v_mfma_f32_16x16x32_bf16 v[4:7], v[202:205], v[194:197], v[4:7]
	v_mfma_f32_16x16x32_bf16 v[0:3], v[210:213], v[194:197], v[0:3]
	v_mfma_f32_16x16x32_bf16 v[44:47], v[206:209], v[170:173], v[44:47]
	v_mfma_f32_16x16x32_bf16 v[40:43], v[214:217], v[170:173], v[40:43]
	v_mfma_f32_16x16x32_bf16 v[28:31], v[206:209], v[182:185], v[28:31]
	v_mfma_f32_16x16x32_bf16 v[24:27], v[214:217], v[182:185], v[24:27]
	v_mfma_f32_16x16x32_bf16 v[12:15], v[206:209], v[190:193], v[12:15]
	v_mfma_f32_16x16x32_bf16 v[8:11], v[214:217], v[190:193], v[8:11]
	v_mfma_f32_16x16x32_bf16 v[4:7], v[206:209], v[198:201], v[4:7]
	s_add_i32 s81, 0, 0x18000
	v_mfma_f32_16x16x32_bf16 v[0:3], v[214:217], v[198:201], v[0:3]
	s_barrier
	ds_read_b128 v[150:153], v253
	ds_read_b128 v[154:157], v253 offset:1024
	ds_read_b128 v[158:161], v253 offset:2048
	ds_read_b128 v[162:165], v253 offset:3072
	s_add_u32 s40, s40, 0x40000
	s_addc_u32 s41, s41, 0
	s_mov_b32 m0, s49
	ds_read_b128 v[166:169], v148 offset:32768
	ds_read_b128 v[170:173], v148 offset:33792
	ds_read_b128 v[174:177], v148 offset:34816
	ds_read_b128 v[182:185], v148 offset:35840
	ds_read_b128 v[186:189], v148 offset:36864
	ds_read_b128 v[190:193], v148 offset:37888
	ds_read_b128 v[194:197], v148 offset:38912
	global_load_lds_dwordx4 v134, s[40:41]
	s_mov_b32 m0, s50
	ds_read_b128 v[198:201], v148 offset:39936
	global_load_lds_dwordx4 v130, s[40:41]
	s_waitcnt lgkmcnt(8)
	s_barrier
; #define PG8_STAGE(bufoff, gbase, voff) do { _Pragma("unroll") for (int _i = 0; _i < 2; ++_i) \
;         __builtin_amdgcn_global_load_lds((const unsigned*)((const char*)(gbase) + (voff)[_i]), (LAS unsigned*)(lds + (bufoff) + ldsw + _i * 8192), 16, 0, 0); } while (0)
; #define PG8_LDA(dst, b, h) do { _Pragma("unroll") for (int m = 0; m < 4; ++m) _Pragma("unroll") for (int k = 0; k < 2; ++k) dst[m][k] = *(const LAS bf16x8*)(lds + PG8_SA(b, h) + aoff + m * 2048 + k * 1024); } while (0)
; #define PG8_LDB(dst, b, h) do { _Pragma("unroll") for (int n = 0; n < 2; ++n) _Pragma("unroll") for (int k = 0; k < 2; ++k) dst[n][k] = *(const LAS bf16x8*)(lds + PG8_SB(b, h) + boff + n * 2048 + k * 1024); } while (0)
; #define PG8_MMA(ai, bj, At, Bt) do { __builtin_amdgcn_s_setprio(1); _Pragma("unroll") for (int m = 0; m < 4; ++m) _Pragma("unroll") for (int n = 0; n < 2; ++n) _Pragma("unroll") for (int k = 0; k < 2; ++k) \
;         acc[ai][bj][m][n] = __builtin_amdgcn_mfma_f32_16x16x32_bf16(Bt[n][k], At[m][k], acc[ai][bj][m][n], 0, 0, 0); __builtin_amdgcn_s_setprio(0); } while (0)
; #define PG8_WAIT_V(n) asm volatile("s_waitcnt vmcnt(" #n ")" ::: "memory")
; #define PG8_WAIT_L(n) asm volatile("s_waitcnt lgkmcnt(" #n ")" ::: "memory")
; #define PG8_BAR __builtin_amdgcn_s_barrier()
; #define PG8_SCHED __builtin_amdgcn_sched_barrier(0)
; template <class Epi>
; DI void gemm_phase(LAS unsigned char* lds, const Gemm g, const StaticOrder& S, const Epi& E) {
;     ...
;             PG8_LDB(B0, 1, 0); PG8_SCHED; PG8_LDA(At, 1, 0); PG8_STAGE(PG8_SA(0, 1), a2 + hstep, voffA);
;             PG8_WAIT_L(8); PG8_BAR; PG8_WAIT_L(0); PG8_MMA(0, 0, At, B0); PG8_BAR; PG8_SCHED;
;             PG8_LDB(B1, 1, 1); PG8_STAGE(PG8_SB(1, 0), b3, voffB);
;             PG8_BAR; PG8_WAIT_L(0); PG8_MMA(0, 1, At, B1); PG8_BAR;
;             PG8_LDA(At, 1, 1); PG8_STAGE(PG8_SA(1, 0), a3, voffA);
;             PG8_BAR; PG8_WAIT_L(0); PG8_MMA(1, 0, At, B0); PG8_BAR; PG8_SCHED;
;             PG8_STAGE(PG8_SB(1, 1), b3 + hstep, voffB);
;             PG8_WAIT_V(6); PG8_BAR; PG8_MMA(1, 1, At, B1); PG8_BAR;
	s_waitcnt lgkmcnt(7)
	v_mfma_f32_16x16x32_bf16 v[124:127], v[150:153], v[166:169], v[124:127]
	v_mfma_f32_16x16x32_bf16 v[120:123], v[158:161], v[166:169], v[120:123]
	s_waitcnt lgkmcnt(5)
	v_mfma_f32_16x16x32_bf16 v[116:119], v[150:153], v[174:177], v[116:119]
	v_mfma_f32_16x16x32_bf16 v[112:115], v[158:161], v[174:177], v[112:115]
	s_waitcnt lgkmcnt(3)
	v_mfma_f32_16x16x32_bf16 v[100:103], v[150:153], v[186:189], v[100:103]
	v_mfma_f32_16x16x32_bf16 v[96:99], v[158:161], v[186:189], v[96:99]
	s_waitcnt lgkmcnt(1)
	v_mfma_f32_16x16x32_bf16 v[84:87], v[150:153], v[194:197], v[84:87]
	v_mfma_f32_16x16x32_bf16 v[80:83], v[158:161], v[194:197], v[80:83]
	v_mfma_f32_16x16x32_bf16 v[124:127], v[154:157], v[170:173], v[124:127]
	v_mfma_f32_16x16x32_bf16 v[120:123], v[162:165], v[170:173], v[120:123]
	v_mfma_f32_16x16x32_bf16 v[116:119], v[154:157], v[182:185], v[116:119]
	v_mfma_f32_16x16x32_bf16 v[112:115], v[162:165], v[182:185], v[112:115]
	v_mfma_f32_16x16x32_bf16 v[100:103], v[154:157], v[190:193], v[100:103]
	v_mfma_f32_16x16x32_bf16 v[96:99], v[162:165], v[190:193], v[96:99]
	s_add_i32 s40, 0, 0x1c000
	s_add_i32 s41, s81, s45
	s_waitcnt lgkmcnt(0)
	v_mfma_f32_16x16x32_bf16 v[84:87], v[154:157], v[198:201], v[84:87]
	s_mov_b32 m0, s41
	v_mfma_f32_16x16x32_bf16 v[80:83], v[162:165], v[198:201], v[80:83]
	s_barrier
	ds_read_b128 v[202:205], v252
	ds_read_b128 v[206:209], v252 offset:1024
	ds_read_b128 v[210:213], v252 offset:2048
	global_load_lds_dwordx4 v132, s[86:87]
	s_add_i32 m0, s41, 0x2000
	ds_read_b128 v[214:217], v252 offset:3072
	global_load_lds_dwordx4 v128, s[86:87]
	s_barrier
	s_waitcnt lgkmcnt(3)
	v_mfma_f32_16x16x32_bf16 v[108:111], v[202:205], v[166:169], v[108:111]
	s_waitcnt lgkmcnt(1)
	v_mfma_f32_16x16x32_bf16 v[104:107], v[210:213], v[166:169], v[104:107]
	v_mfma_f32_16x16x32_bf16 v[92:95], v[202:205], v[174:177], v[92:95]
	v_mfma_f32_16x16x32_bf16 v[88:91], v[210:213], v[174:177], v[88:91]
	v_mfma_f32_16x16x32_bf16 v[76:79], v[202:205], v[186:189], v[76:79]
	v_mfma_f32_16x16x32_bf16 v[72:75], v[210:213], v[186:189], v[72:75]
	v_mfma_f32_16x16x32_bf16 v[68:71], v[202:205], v[194:197], v[68:71]
	v_mfma_f32_16x16x32_bf16 v[64:67], v[210:213], v[194:197], v[64:67]
	v_mfma_f32_16x16x32_bf16 v[108:111], v[206:209], v[170:173], v[108:111]
	s_waitcnt lgkmcnt(0)
	v_mfma_f32_16x16x32_bf16 v[104:107], v[214:217], v[170:173], v[104:107]
	v_mfma_f32_16x16x32_bf16 v[92:95], v[206:209], v[182:185], v[92:95]
	v_mfma_f32_16x16x32_bf16 v[88:91], v[214:217], v[182:185], v[88:91]
	v_mfma_f32_16x16x32_bf16 v[76:79], v[206:209], v[190:193], v[76:79]
	v_mfma_f32_16x16x32_bf16 v[72:75], v[214:217], v[190:193], v[72:75]
	v_mfma_f32_16x16x32_bf16 v[68:71], v[206:209], v[198:201], v[68:71]
	s_mov_b32 m0, s66
	v_mfma_f32_16x16x32_bf16 v[64:67], v[214:217], v[198:201], v[64:67]
	s_barrier
	ds_read_b128 v[166:169], v148 offset:49152
	ds_read_b128 v[170:173], v148 offset:50176
	ds_read_b128 v[174:177], v148 offset:51200
	ds_read_b128 v[182:185], v148 offset:52224
	ds_read_b128 v[186:189], v148 offset:53248
	ds_read_b128 v[190:193], v148 offset:54272
	ds_read_b128 v[194:197], v148 offset:55296
	global_load_lds_dwordx4 v134, s[88:89]
	s_mov_b32 m0, s67
	ds_read_b128 v[198:201], v148 offset:56320
	global_load_lds_dwordx4 v130, s[88:89]
	s_barrier
	s_waitcnt lgkmcnt(7)
	v_mfma_f32_16x16x32_bf16 v[60:63], v[150:153], v[166:169], v[60:63]
	v_mfma_f32_16x16x32_bf16 v[56:59], v[158:161], v[166:169], v[56:59]
	s_waitcnt lgkmcnt(5)
	v_mfma_f32_16x16x32_bf16 v[52:55], v[150:153], v[174:177], v[52:55]
	v_mfma_f32_16x16x32_bf16 v[48:51], v[158:161], v[174:177], v[48:51]
	s_waitcnt lgkmcnt(3)
	v_mfma_f32_16x16x32_bf16 v[36:39], v[150:153], v[186:189], v[36:39]
	v_mfma_f32_16x16x32_bf16 v[32:35], v[158:161], v[186:189], v[32:35]
	s_waitcnt lgkmcnt(1)
	v_mfma_f32_16x16x32_bf16 v[20:23], v[150:153], v[194:197], v[20:23]
	v_mfma_f32_16x16x32_bf16 v[16:19], v[158:161], v[194:197], v[16:19]
	v_mfma_f32_16x16x32_bf16 v[60:63], v[154:157], v[170:173], v[60:63]
	v_mfma_f32_16x16x32_bf16 v[56:59], v[162:165], v[170:173], v[56:59]
	v_mfma_f32_16x16x32_bf16 v[52:55], v[154:157], v[182:185], v[52:55]
	v_mfma_f32_16x16x32_bf16 v[48:51], v[162:165], v[182:185], v[48:51]
	v_mfma_f32_16x16x32_bf16 v[36:39], v[154:157], v[190:193], v[36:39]
	v_mfma_f32_16x16x32_bf16 v[32:35], v[162:165], v[190:193], v[32:35]
	s_add_u32 s38, s38, 0x40080
	s_addc_u32 s39, s39, 0
	s_waitcnt lgkmcnt(0)
	v_mfma_f32_16x16x32_bf16 v[20:23], v[154:157], v[198:201], v[20:23]
	s_add_i32 s40, s40, s45
	s_mov_b32 m0, s40
	v_mfma_f32_16x16x32_bf16 v[16:19], v[162:165], v[198:201], v[16:19]
	s_barrier
	global_load_lds_dwordx4 v132, s[38:39]
	s_add_i32 m0, s40, 0x2000
	s_waitcnt vmcnt(5)
	global_load_lds_dwordx4 v128, s[38:39]
	s_barrier
; DI unsigned pk2(float a, float b) { f32x2 v = {a, b}; bf16x2_t r = __builtin_convertvector(v, bf16x2_t); return __builtin_bit_cast(unsigned, r); }
; #define PG8_MMA(ai, bj, At, Bt) do { __builtin_amdgcn_s_setprio(1); _Pragma("unroll") for (int m = 0; m < 4; ++m) _Pragma("unroll") for (int n = 0; n < 2; ++n) _Pragma("unroll") for (int k = 0; k < 2; ++k) \
;         acc[ai][bj][m][n] = __builtin_amdgcn_mfma_f32_16x16x32_bf16(Bt[n][k], At[m][k], acc[ai][bj][m][n], 0, 0, 0); __builtin_amdgcn_s_setprio(0); } while (0)
; #define PG8_WAIT_V(n) asm volatile("s_waitcnt vmcnt(" #n ")" ::: "memory")
; #define PG8_BAR __builtin_amdgcn_s_barrier()
; template <class Epi>
; DI void gemm_phase(LAS unsigned char* lds, const Gemm g, const StaticOrder& S, const Epi& E) {
;     ...
;             PG8_WAIT_V(6); PG8_BAR; PG8_MMA(1, 1, At, B1); PG8_BAR;
;         }
;         E(acc, cur, wr, wc, fr, fq);
;         if (!has_next) break;
;     DI void operator()(const f32x4 (&acc)[2][2][4][2], const Unit& u, int wr, int wc, int fr, int fq) const {
;         const bool first = u.pn < 6; const int ldc = first ? P1W : P2W;
;         const int row0 = u.pm * BM + wr * 64 + fr, col0 = (first ? u.pn : u.pn - 6) * BM + wc * 32 + 8 * fq;
;         bf16_t* O = first ? O1 : O2;
; #pragma unroll
;         for (int ai = 0; ai < 2; ++ai)
; #pragma unroll
;             for (int m = 0; m < 4; ++m) { bf16_t* rowp = O + (size_t)(row0 + ai * HALF + m * 16) * ldc + col0;
; #pragma unroll
;                 for (int bj = 0; bj < 2; ++bj) { const f32x4 v0 = acc[ai][bj][m][0], v1 = acc[ai][bj][m][1];
;                     u32x4 w; w.x = pk2(v0[0], v0[1]); w.y = pk2(v0[2], v0[3]); w.z = pk2(v1[0], v1[1]); w.w = pk2(v1[2], v1[3]);
;                     *(u32x4*)(rowp + bj * HALF) = w; } }
	v_mfma_f32_16x16x32_bf16 v[44:47], v[202:205], v[166:169], v[44:47]
	v_mfma_f32_16x16x32_bf16 v[40:43], v[210:213], v[166:169], v[40:43]
	v_mfma_f32_16x16x32_bf16 v[28:31], v[202:205], v[174:177], v[28:31]
	v_mfma_f32_16x16x32_bf16 v[24:27], v[210:213], v[174:177], v[24:27]
	v_mfma_f32_16x16x32_bf16 v[12:15], v[202:205], v[186:189], v[12:15]
	v_mfma_f32_16x16x32_bf16 v[8:11], v[210:213], v[186:189], v[8:11]
	v_mfma_f32_16x16x32_bf16 v[4:7], v[202:205], v[194:197], v[4:7]
	v_mfma_f32_16x16x32_bf16 v[0:3], v[210:213], v[194:197], v[0:3]
	v_mfma_f32_16x16x32_bf16 v[44:47], v[206:209], v[170:173], v[44:47]
	s_add_i32 s80, s80, 2
	s_add_u32 s24, s24, 0x100
	v_mfma_f32_16x16x32_bf16 v[40:43], v[214:217], v[170:173], v[40:43]
	s_addc_u32 s25, s25, 0
	s_add_u32 s78, s78, 0x100
	v_mfma_f32_16x16x32_bf16 v[28:31], v[206:209], v[182:185], v[28:31]
	s_addc_u32 s79, s79, 0
	s_add_u32 s38, s24, 0xfffc0080
	v_mfma_f32_16x16x32_bf16 v[24:27], v[214:217], v[182:185], v[24:27]
	s_addc_u32 s39, s25, -1
	s_cmp_eq_u32 s80, 12
	v_mfma_f32_16x16x32_bf16 v[12:15], v[206:209], v[190:193], v[12:15]
	s_cselect_b32 s41, s17, s39
	s_cselect_b32 s40, s76, s38
	v_mfma_f32_16x16x32_bf16 v[8:11], v[214:217], v[190:193], v[8:11]
	s_cselect_b32 s39, s15, s79
	s_cselect_b32 s38, s77, s78
	v_mfma_f32_16x16x32_bf16 v[4:7], v[206:209], v[198:201], v[4:7]
	s_add_i32 m0, s13, 0xc000
	v_mfma_f32_16x16x32_bf16 v[0:3], v[214:217], v[198:201], v[0:3]
	s_cmp_gt_u32 s80, 13
	s_barrier
	s_cbranch_scc0 .LBB0_211
	s_lshl_b32 s15, s75, 8
	s_add_i32 s17, s15, 0xfffffa00
	s_cmp_lt_i32 s75, 6
	v_lshl_add_u32 v154, s12, 8, v144
	s_cselect_b32 s12, s15, s17
	v_or_b32_e32 v150, s12, v146
	s_cselect_b32 s12, s74, 0x1ef76000
	s_cselect_b32 s38, s73, 0xa00
	s_add_u32 s24, s30, s12
	s_addc_u32 s25, s31, 0
	v_ashrrev_i32_e32 v151, 31, v150
	v_lshl_add_u64 v[150:151], v[150:151], 1, s[24:25]
	v_mad_i64_i32 v[152:153], s[24:25], s38, v154, 0
	v_cvt_pk_bf16_f32 v108, v108, v109
	v_cvt_pk_bf16_f32 v109, v110, v111
	v_cvt_pk_bf16_f32 v110, v104, v105
	v_or_b32_e32 v104, 16, v154
	v_lshl_add_u64 v[152:153], v[152:153], 1, v[150:151]
	v_cvt_pk_bf16_f32 v111, v106, v107
	v_mad_i64_i32 v[104:105], s[24:25], s38, v104, 0
	v_cvt_pk_bf16_f32 v92, v92, v93
	v_cvt_pk_bf16_f32 v93, v94, v95
	v_cvt_pk_bf16_f32 v94, v88, v89
	v_or_b32_e32 v88, 32, v154
	v_cvt_pk_bf16_f32 v124, v124, v125
	v_cvt_pk_bf16_f32 v125, v126, v127
	v_cvt_pk_bf16_f32 v126, v120, v121
	v_cvt_pk_bf16_f32 v127, v122, v123
	global_store_dwordx4 v[152:153], v[108:111], off offset:256
	v_cvt_pk_bf16_f32 v95, v90, v91
	v_mad_i64_i32 v[88:89], s[24:25], s38, v88, 0
	v_lshl_add_u64 v[108:109], v[104:105], 1, v[150:151]
	v_cvt_pk_bf16_f32 v76, v76, v77
	v_cvt_pk_bf16_f32 v77, v78, v79
	v_cvt_pk_bf16_f32 v78, v72, v73
	v_or_b32_e32 v72, 48, v154
	v_cvt_pk_bf16_f32 v68, v68, v69
	v_cvt_pk_bf16_f32 v69, v70, v71
	v_cvt_pk_bf16_f32 v70, v64, v65
	v_add_u32_e32 v64, 0x80, v154
	global_store_dwordx4 v[152:153], v[124:127], off
	v_cvt_pk_bf16_f32 v104, v116, v117
	v_cvt_pk_bf16_f32 v105, v118, v119
	v_cvt_pk_bf16_f32 v106, v112, v113
	v_cvt_pk_bf16_f32 v107, v114, v115
	global_store_dwordx4 v[108:109], v[92:95], off offset:256
	v_cvt_pk_bf16_f32 v79, v74, v75
	v_mad_i64_i32 v[72:73], s[24:25], s38, v72, 0
	v_lshl_add_u64 v[92:93], v[88:89], 1, v[150:151]
	v_mad_i64_i32 v[64:65], s[24:25], s38, v64, 0
	v_cvt_pk_bf16_f32 v44, v44, v45
	v_cvt_pk_bf16_f32 v45, v46, v47
	v_cvt_pk_bf16_f32 v46, v40, v41
	v_add_u32_e32 v40, 0x90, v154
	global_store_dwordx4 v[108:109], v[104:107], off
	v_cvt_pk_bf16_f32 v88, v100, v101
	v_cvt_pk_bf16_f32 v89, v102, v103
	v_cvt_pk_bf16_f32 v90, v96, v97
	v_cvt_pk_bf16_f32 v91, v98, v99
	global_store_dwordx4 v[92:93], v[76:79], off offset:256
	v_cvt_pk_bf16_f32 v74, v80, v81
	v_cvt_pk_bf16_f32 v75, v82, v83
	v_lshl_add_u64 v[76:77], v[72:73], 1, v[150:151]
	v_cvt_pk_bf16_f32 v72, v84, v85
	v_cvt_pk_bf16_f32 v73, v86, v87
	v_cvt_pk_bf16_f32 v71, v66, v67
	v_lshl_add_u64 v[64:65], v[64:65], 1, v[150:151]
	v_cvt_pk_bf16_f32 v47, v42, v43
	v_mad_i64_i32 v[40:41], s[24:25], s38, v40, 0
	v_cvt_pk_bf16_f32 v28, v28, v29
	v_cvt_pk_bf16_f32 v29, v30, v31
	v_cvt_pk_bf16_f32 v30, v24, v25
	v_add_u32_e32 v24, 0xa0, v154
	global_store_dwordx4 v[92:93], v[88:91], off
	global_store_dwordx4 v[76:77], v[72:75], off
	global_store_dwordx4 v[76:77], v[68:71], off offset:256
	v_cvt_pk_bf16_f32 v60, v60, v61
	v_cvt_pk_bf16_f32 v61, v62, v63
	v_cvt_pk_bf16_f32 v62, v56, v57
	v_cvt_pk_bf16_f32 v63, v58, v59
	global_store_dwordx4 v[64:65], v[44:47], off offset:256
	v_cvt_pk_bf16_f32 v31, v26, v27
	v_mad_i64_i32 v[24:25], s[24:25], s38, v24, 0
	v_lshl_add_u64 v[44:45], v[40:41], 1, v[150:151]
	v_cvt_pk_bf16_f32 v12, v12, v13
	v_cvt_pk_bf16_f32 v13, v14, v15
	v_cvt_pk_bf16_f32 v14, v8, v9
	v_add_u32_e32 v8, 0xb0, v154
	global_store_dwordx4 v[64:65], v[60:63], off
	v_cvt_pk_bf16_f32 v40, v52, v53
	v_cvt_pk_bf16_f32 v41, v54, v55
	v_cvt_pk_bf16_f32 v42, v48, v49
	v_cvt_pk_bf16_f32 v43, v50, v51
	global_store_dwordx4 v[44:45], v[28:31], off offset:256
	v_cvt_pk_bf16_f32 v15, v10, v11
	v_mad_i64_i32 v[8:9], s[24:25], s38, v8, 0
	v_lshl_add_u64 v[28:29], v[24:25], 1, v[150:151]
	global_store_dwordx4 v[44:45], v[40:43], off
	v_cvt_pk_bf16_f32 v24, v36, v37
	v_cvt_pk_bf16_f32 v25, v38, v39
	v_cvt_pk_bf16_f32 v26, v32, v33
	v_cvt_pk_bf16_f32 v27, v34, v35
	global_store_dwordx4 v[28:29], v[12:15], off offset:256
	v_cvt_pk_bf16_f32 v10, v16, v17
	v_cvt_pk_bf16_f32 v11, v18, v19
	v_lshl_add_u64 v[12:13], v[8:9], 1, v[150:151]
	v_cvt_pk_bf16_f32 v8, v20, v21
	v_cvt_pk_bf16_f32 v9, v22, v23
	v_cvt_pk_bf16_f32 v4, v4, v5
	v_cvt_pk_bf16_f32 v5, v6, v7
	v_cvt_pk_bf16_f32 v6, v0, v1
	v_cvt_pk_bf16_f32 v7, v2, v3
	s_and_b64 vcc, exec, s[4:5]
	s_mov_b32 s75, s14
	s_mov_b32 s12, s16
	s_mov_b64 s[38:39], s[22:23]
	s_mov_b64 s[24:25], s[18:19]
	global_store_dwordx4 v[28:29], v[24:27], off
	global_store_dwordx4 v[12:13], v[8:11], off
	global_store_dwordx4 v[12:13], v[4:7], off offset:256
	s_cbranch_vccz .LBB0_208
	s_waitcnt vmcnt(0)
	s_cmpk_gt_u32 s42, 0xff
	s_cbranch_scc1 .LBB0_215
	s_barrier

; #define PG8_STAGE(bufoff, gbase, voff) do { _Pragma("unroll") for (int _i = 0; _i < 2; ++_i) \
;         __builtin_amdgcn_global_load_lds((const unsigned*)((const char*)(gbase) + (voff)[_i]), (LAS unsigned*)(lds + (bufoff) + ldsw + _i * 8192), 16, 0, 0); } while (0)
; #define PG8_LDA(dst, b, h) do { _Pragma("unroll") for (int m = 0; m < 4; ++m) _Pragma("unroll") for (int k = 0; k < 2; ++k) dst[m][k] = *(const LAS bf16x8*)(lds + PG8_SA(b, h) + aoff + m * 2048 + k * 1024); } while (0)
; #define PG8_LDB(dst, b, h) do { _Pragma("unroll") for (int n = 0; n < 2; ++n) _Pragma("unroll") for (int k = 0; k < 2; ++k) dst[n][k] = *(const LAS bf16x8*)(lds + PG8_SB(b, h) + boff + n * 2048 + k * 1024); } while (0)
; #define PG8_MMA(ai, bj, At, Bt) do { __builtin_amdgcn_s_setprio(1); _Pragma("unroll") for (int m = 0; m < 4; ++m) _Pragma("unroll") for (int n = 0; n < 2; ++n) _Pragma("unroll") for (int k = 0; k < 2; ++k) \
;         acc[ai][bj][m][n] = __builtin_amdgcn_mfma_f32_16x16x32_bf16(Bt[n][k], At[m][k], acc[ai][bj][m][n], 0, 0, 0); __builtin_amdgcn_s_setprio(0); } while (0)
; template <class Epi>
; DI void gemm_phase(LAS unsigned char* lds, const Gemm g, const StaticOrder& S, const Epi& E) {
;     ...
;         const bool has_next = S.next(ui + 1, nxt);
;         const char* nA = has_next ? (const char*)g.A + (size_t)nxt.pm * tstep : cA; const char* nB = has_next ? (const char*)g.Bt + (size_t)nxt.pn * tstep : cB;
;         for (int t = 0; t < nt; t += 2) {
;             const bool last = (t == nt - 2);
;             const char* a1 = cA + (size_t)(t + 1) * kstep;
;             const char* a2 = last ? nA : cA + (size_t)(t + 2) * kstep; const char* b2 = last ? nB : cB + (size_t)(t + 2) * kstep;
;             const char* a3 = a2 + kstep; const char* b3 = b2 + kstep;
;             PG8_LDB(B0, 0, 0); PG8_SCHED; PG8_LDA(At, 0, 0); PG8_STAGE(PG8_SA(1, 1), a1 + hstep, voffA);
;             PG8_WAIT_L(8); PG8_BAR; PG8_WAIT_L(0); PG8_MMA(0, 0, At, B0); PG8_BAR; PG8_SCHED;
;             PG8_LDB(B1, 0, 1); PG8_STAGE(PG8_SB(0, 0), b2, voffB);
;             PG8_BAR; PG8_WAIT_L(0); PG8_MMA(0, 1, At, B1); PG8_BAR;
;             PG8_LDA(At, 0, 1); PG8_STAGE(PG8_SA(0, 0), a2, voffA);
;             PG8_BAR; PG8_WAIT_L(0); PG8_MMA(1, 0, At, B0); PG8_BAR; PG8_SCHED;
;             PG8_STAGE(PG8_SB(0, 1), b2 + hstep, voffB);
;             PG8_WAIT_V(6); PG8_BAR; PG8_MMA(1, 1, At, B1); PG8_BAR;
.LBB0_723:
	s_ashr_i32 s39, s38, 31
	v_cmp_lt_i64_e32 vcc, s[40:41], v[156:157]
	s_lshl_b64 s[40:41], s[38:39], 19
	s_add_u32 s40, s54, s40
	s_addc_u32 s41, s55, s41
	s_and_b64 s[42:43], vcc, exec
	s_cselect_b32 s39, s41, s47
	s_cselect_b32 s73, s40, s46
	s_ashr_i32 s25, s24, 31
	s_lshl_b64 s[42:43], s[24:25], 19
	s_add_u32 s42, s56, s42
	s_addc_u32 s43, s57, s43
	s_and_b64 s[50:51], vcc, exec
	s_cselect_b32 s25, s43, s49
	s_cselect_b32 s74, s42, s48
	s_add_u32 s46, s46, 0x40080
	s_addc_u32 s47, s47, 0
	s_add_u32 s75, s48, 0x100
	s_addc_u32 s76, s49, 0
	s_mov_b32 s77, -2
	v_add_u32_e32 v253, 0x18000, v163
	v_add_u32_e32 v252, 0x1c000, v163
	ds_read_b128 v[128:131], v165
	ds_read_b128 v[132:135], v165 offset:1024
	ds_read_b128 v[136:139], v165 offset:2048
	ds_read_b128 v[140:143], v165 offset:3072
	s_add_u32 s48, s46, 0xfffc0080
	s_addc_u32 s49, s47, -1
	s_cmp_eq_u32 s77, 12
	s_cselect_b32 s51, s39, s49
	s_cselect_b32 s50, s73, s48
	s_cselect_b32 s49, s25, s76
	s_cselect_b32 s48, s74, s75
	s_add_i32 m0, s45, 0xc000
	ds_read_b128 v[168:171], v166
	ds_read_b128 v[172:175], v166 offset:1024
	ds_read_b128 v[176:179], v166 offset:2048
	ds_read_b128 v[182:185], v166 offset:3072
	ds_read_b128 v[186:189], v166 offset:4096
	ds_read_b128 v[190:193], v166 offset:5120
	ds_read_b128 v[194:197], v166 offset:6144
	global_load_lds_dwordx4 v152, s[46:47]
	s_add_i32 m0, s45, 0xe000
	ds_read_b128 v[198:201], v166 offset:7168
	global_load_lds_dwordx4 v154, s[46:47]
	s_waitcnt lgkmcnt(8)
	s_barrier
	s_waitcnt lgkmcnt(7)
	v_mfma_f32_16x16x32_bf16 v[124:127], v[128:131], v[168:171], 0
	v_mfma_f32_16x16x32_bf16 v[120:123], v[136:139], v[168:171], 0
	s_waitcnt lgkmcnt(5)
	v_mfma_f32_16x16x32_bf16 v[108:111], v[128:131], v[176:179], 0
	v_mfma_f32_16x16x32_bf16 v[104:107], v[136:139], v[176:179], 0
	s_waitcnt lgkmcnt(3)
	v_mfma_f32_16x16x32_bf16 v[92:95], v[128:131], v[186:189], 0
	v_mfma_f32_16x16x32_bf16 v[88:91], v[136:139], v[186:189], 0
	s_waitcnt lgkmcnt(1)
	v_mfma_f32_16x16x32_bf16 v[76:79], v[128:131], v[194:197], 0
	v_mfma_f32_16x16x32_bf16 v[72:75], v[136:139], v[194:197], 0
	v_mfma_f32_16x16x32_bf16 v[124:127], v[132:135], v[172:175], v[124:127]
	v_mfma_f32_16x16x32_bf16 v[120:123], v[140:143], v[172:175], v[120:123]
	v_mfma_f32_16x16x32_bf16 v[108:111], v[132:135], v[182:185], v[108:111]
	v_mfma_f32_16x16x32_bf16 v[104:107], v[140:143], v[182:185], v[104:107]
	v_mfma_f32_16x16x32_bf16 v[92:95], v[132:135], v[190:193], v[92:95]
	v_mfma_f32_16x16x32_bf16 v[88:91], v[140:143], v[190:193], v[88:91]
	s_add_i32 s78, s70, s58
	s_add_u32 s86, s48, s12
	s_waitcnt lgkmcnt(0)
	v_mfma_f32_16x16x32_bf16 v[76:79], v[132:135], v[198:201], v[76:79]
	s_addc_u32 s87, s49, s13
	s_mov_b32 m0, s78
	v_mfma_f32_16x16x32_bf16 v[72:75], v[140:143], v[198:201], v[72:75]
	s_barrier
	ds_read_b128 v[202:205], v167
	ds_read_b128 v[206:209], v167 offset:1024
	ds_read_b128 v[210:213], v167 offset:2048
	global_load_lds_dwordx4 v146, s[48:49]
	s_add_i32 m0, s78, 0x2000
	ds_read_b128 v[214:217], v167 offset:3072
	global_load_lds_dwordx4 v150, s[48:49]
	s_barrier
	s_waitcnt lgkmcnt(3)
	v_mfma_f32_16x16x32_bf16 v[116:119], v[202:205], v[168:171], 0
	s_waitcnt lgkmcnt(1)
	v_mfma_f32_16x16x32_bf16 v[112:115], v[210:213], v[168:171], 0
	v_mfma_f32_16x16x32_bf16 v[100:103], v[202:205], v[176:179], 0
	v_mfma_f32_16x16x32_bf16 v[96:99], v[210:213], v[176:179], 0
	v_mfma_f32_16x16x32_bf16 v[84:87], v[202:205], v[186:189], 0
	v_mfma_f32_16x16x32_bf16 v[80:83], v[210:213], v[186:189], 0
	v_mfma_f32_16x16x32_bf16 v[68:71], v[202:205], v[194:197], 0
	v_mfma_f32_16x16x32_bf16 v[64:67], v[210:213], v[194:197], 0
	v_mfma_f32_16x16x32_bf16 v[116:119], v[206:209], v[172:175], v[116:119]
	s_waitcnt lgkmcnt(0)
	v_mfma_f32_16x16x32_bf16 v[112:115], v[214:217], v[172:175], v[112:115]
	v_mfma_f32_16x16x32_bf16 v[100:103], v[206:209], v[182:185], v[100:103]
	v_mfma_f32_16x16x32_bf16 v[96:99], v[214:217], v[182:185], v[96:99]
	v_mfma_f32_16x16x32_bf16 v[84:87], v[206:209], v[190:193], v[84:87]
	v_mfma_f32_16x16x32_bf16 v[80:83], v[214:217], v[190:193], v[80:83]
	s_mov_b32 m0, s45
	s_add_u32 s88, s50, s12
	v_mfma_f32_16x16x32_bf16 v[68:71], v[206:209], v[198:201], v[68:71]
	s_addc_u32 s89, s51, s13
	v_mfma_f32_16x16x32_bf16 v[64:67], v[214:217], v[198:201], v[64:67]
	s_barrier
	ds_read_b128 v[168:171], v166 offset:16384
	ds_read_b128 v[172:175], v166 offset:17408
	ds_read_b128 v[176:179], v166 offset:18432
	ds_read_b128 v[182:185], v166 offset:19456
	ds_read_b128 v[186:189], v166 offset:20480
	ds_read_b128 v[190:193], v166 offset:21504
	ds_read_b128 v[194:197], v166 offset:22528
	global_load_lds_dwordx4 v144, s[50:51]
	s_mov_b32 m0, s59
	ds_read_b128 v[198:201], v166 offset:23552
	global_load_lds_dwordx4 v148, s[50:51]
	s_barrier
	s_waitcnt lgkmcnt(7)
	v_mfma_f32_16x16x32_bf16 v[60:63], v[128:131], v[168:171], 0
	v_mfma_f32_16x16x32_bf16 v[56:59], v[136:139], v[168:171], 0
	s_waitcnt lgkmcnt(5)
	v_mfma_f32_16x16x32_bf16 v[44:47], v[128:131], v[176:179], 0
	v_mfma_f32_16x16x32_bf16 v[40:43], v[136:139], v[176:179], 0
	s_waitcnt lgkmcnt(3)
	v_mfma_f32_16x16x32_bf16 v[28:31], v[128:131], v[186:189], 0
	v_mfma_f32_16x16x32_bf16 v[24:27], v[136:139], v[186:189], 0
	s_waitcnt lgkmcnt(1)
	v_mfma_f32_16x16x32_bf16 v[12:15], v[128:131], v[194:197], 0
	v_mfma_f32_16x16x32_bf16 v[8:11], v[136:139], v[194:197], 0
	v_mfma_f32_16x16x32_bf16 v[60:63], v[132:135], v[172:175], v[60:63]
	v_mfma_f32_16x16x32_bf16 v[56:59], v[140:143], v[172:175], v[56:59]
	s_add_u32 s78, s48, 0x40000
	s_addc_u32 s79, s49, 0
	v_mfma_f32_16x16x32_bf16 v[44:47], v[132:135], v[182:185], v[44:47]
	s_add_i32 s80, s71, s58
	s_mov_b32 m0, s80
	v_mfma_f32_16x16x32_bf16 v[40:43], v[140:143], v[182:185], v[40:43]
	s_lshl_b32 s84, s44, 20
	s_lshl_b32 s85, s72, 10
	v_mfma_f32_16x16x32_bf16 v[28:31], v[132:135], v[190:193], v[28:31]
	s_add_u32 s84, s84, s85
	s_add_i32 s85, s77, 2
	v_mfma_f32_16x16x32_bf16 v[24:27], v[140:143], v[190:193], v[24:27]
	s_lshl_b32 s85, s85, 13
	s_add_u32 s84, s84, s85
	s_waitcnt lgkmcnt(0)
	v_mfma_f32_16x16x32_bf16 v[12:15], v[132:135], v[198:201], v[12:15]
	s_add_u32 s84, s36, s84
	s_addc_u32 s85, s37, 0
	v_mfma_f32_16x16x32_bf16 v[8:11], v[140:143], v[198:201], v[8:11]
	s_barrier
; #define PG8_STAGE(bufoff, gbase, voff) do { _Pragma("unroll") for (int _i = 0; _i < 2; ++_i) \
;         __builtin_amdgcn_global_load_lds((const unsigned*)((const char*)(gbase) + (voff)[_i]), (LAS unsigned*)(lds + (bufoff) + ldsw + _i * 8192), 16, 0, 0); } while (0)
; #define PG8_LDA(dst, b, h) do { _Pragma("unroll") for (int m = 0; m < 4; ++m) _Pragma("unroll") for (int k = 0; k < 2; ++k) dst[m][k] = *(const LAS bf16x8*)(lds + PG8_SA(b, h) + aoff + m * 2048 + k * 1024); } while (0)
; #define PG8_LDB(dst, b, h) do { _Pragma("unroll") for (int n = 0; n < 2; ++n) _Pragma("unroll") for (int k = 0; k < 2; ++k) dst[n][k] = *(const LAS bf16x8*)(lds + PG8_SB(b, h) + boff + n * 2048 + k * 1024); } while (0)
; #define PG8_MMA(ai, bj, At, Bt) do { __builtin_amdgcn_s_setprio(1); _Pragma("unroll") for (int m = 0; m < 4; ++m) _Pragma("unroll") for (int n = 0; n < 2; ++n) _Pragma("unroll") for (int k = 0; k < 2; ++k) \
;         acc[ai][bj][m][n] = __builtin_amdgcn_mfma_f32_16x16x32_bf16(Bt[n][k], At[m][k], acc[ai][bj][m][n], 0, 0, 0); __builtin_amdgcn_s_setprio(0); } while (0)
; #define PG8_WAIT_V(n) asm volatile("s_waitcnt vmcnt(" #n ")" ::: "memory")
; #define PG8_WAIT_L(n) asm volatile("s_waitcnt lgkmcnt(" #n ")" ::: "memory")
; #define PG8_BAR __builtin_amdgcn_s_barrier()
; #define PG8_SCHED __builtin_amdgcn_sched_barrier(0)
; template <class Epi>
; DI void gemm_phase(LAS unsigned char* lds, const Gemm g, const StaticOrder& S, const Epi& E) {
;     ...
;             PG8_WAIT_V(6); PG8_BAR; PG8_MMA(1, 1, At, B1); PG8_BAR;
;             PG8_LDB(B0, 1, 0); PG8_SCHED; PG8_LDA(At, 1, 0); PG8_STAGE(PG8_SA(0, 1), a2 + hstep, voffA);
;             PG8_WAIT_L(8); PG8_BAR; PG8_WAIT_L(0); PG8_MMA(0, 0, At, B0); PG8_BAR; PG8_SCHED;
;             PG8_LDB(B1, 1, 1); PG8_STAGE(PG8_SB(1, 0), b3, voffB);
;             PG8_BAR; PG8_WAIT_L(0); PG8_MMA(0, 1, At, B1); PG8_BAR;
;             PG8_LDA(At, 1, 1); PG8_STAGE(PG8_SA(1, 0), a3, voffA);
;             PG8_BAR; PG8_WAIT_L(0); PG8_MMA(1, 0, At, B0); PG8_BAR; PG8_SCHED;
;             PG8_STAGE(PG8_SB(1, 1), b3 + hstep, voffB);
;             PG8_WAIT_V(6); PG8_BAR; PG8_MMA(1, 1, At, B1); PG8_BAR;
	global_load_lds_dwordx4 v146, s[78:79]
	s_add_i32 m0, s80, 0x2000
	s_waitcnt vmcnt(5)
	global_load_lds_dwordx4 v150, s[78:79]
	global_load_dword v249, v248, s[84:85]
	s_barrier
	v_mfma_f32_16x16x32_bf16 v[52:55], v[202:205], v[168:171], 0
	v_mfma_f32_16x16x32_bf16 v[48:51], v[210:213], v[168:171], 0
	v_mfma_f32_16x16x32_bf16 v[36:39], v[202:205], v[176:179], 0
	v_mfma_f32_16x16x32_bf16 v[32:35], v[210:213], v[176:179], 0
	v_mfma_f32_16x16x32_bf16 v[20:23], v[202:205], v[186:189], 0
	v_mfma_f32_16x16x32_bf16 v[16:19], v[210:213], v[186:189], 0
	v_mfma_f32_16x16x32_bf16 v[4:7], v[202:205], v[194:197], 0
	v_mfma_f32_16x16x32_bf16 v[0:3], v[210:213], v[194:197], 0
	v_mfma_f32_16x16x32_bf16 v[52:55], v[206:209], v[172:175], v[52:55]
	v_mfma_f32_16x16x32_bf16 v[48:51], v[214:217], v[172:175], v[48:51]
	v_mfma_f32_16x16x32_bf16 v[36:39], v[206:209], v[182:185], v[36:39]
	v_mfma_f32_16x16x32_bf16 v[32:35], v[214:217], v[182:185], v[32:35]
	v_mfma_f32_16x16x32_bf16 v[20:23], v[206:209], v[190:193], v[20:23]
	v_mfma_f32_16x16x32_bf16 v[16:19], v[214:217], v[190:193], v[16:19]
	v_mfma_f32_16x16x32_bf16 v[4:7], v[206:209], v[198:201], v[4:7]
	s_add_i32 s78, 0, 0x18000
	v_mfma_f32_16x16x32_bf16 v[0:3], v[214:217], v[198:201], v[0:3]
	s_barrier
	ds_read_b128 v[128:131], v253
	ds_read_b128 v[132:135], v253 offset:1024
	ds_read_b128 v[136:139], v253 offset:2048
	ds_read_b128 v[140:143], v253 offset:3072
	s_add_u32 s50, s50, 0x40000
	s_addc_u32 s51, s51, 0
	s_mov_b32 m0, s60
	ds_read_b128 v[168:171], v166 offset:32768
	ds_read_b128 v[172:175], v166 offset:33792
	ds_read_b128 v[176:179], v166 offset:34816
	ds_read_b128 v[182:185], v166 offset:35840
	ds_read_b128 v[186:189], v166 offset:36864
	ds_read_b128 v[190:193], v166 offset:37888
	ds_read_b128 v[194:197], v166 offset:38912
	global_load_lds_dwordx4 v144, s[50:51]
	s_mov_b32 m0, s61
	ds_read_b128 v[198:201], v166 offset:39936
	global_load_lds_dwordx4 v148, s[50:51]
	s_waitcnt lgkmcnt(8)
	s_barrier
	s_waitcnt lgkmcnt(7)
	v_mfma_f32_16x16x32_bf16 v[124:127], v[128:131], v[168:171], v[124:127]
	v_mfma_f32_16x16x32_bf16 v[120:123], v[136:139], v[168:171], v[120:123]
	s_waitcnt lgkmcnt(5)
	v_mfma_f32_16x16x32_bf16 v[108:111], v[128:131], v[176:179], v[108:111]
	v_mfma_f32_16x16x32_bf16 v[104:107], v[136:139], v[176:179], v[104:107]
	s_waitcnt lgkmcnt(3)
	v_mfma_f32_16x16x32_bf16 v[92:95], v[128:131], v[186:189], v[92:95]
	v_mfma_f32_16x16x32_bf16 v[88:91], v[136:139], v[186:189], v[88:91]
	s_waitcnt lgkmcnt(1)
	v_mfma_f32_16x16x32_bf16 v[76:79], v[128:131], v[194:197], v[76:79]
	v_mfma_f32_16x16x32_bf16 v[72:75], v[136:139], v[194:197], v[72:75]
	v_mfma_f32_16x16x32_bf16 v[124:127], v[132:135], v[172:175], v[124:127]
	v_mfma_f32_16x16x32_bf16 v[120:123], v[140:143], v[172:175], v[120:123]
	v_mfma_f32_16x16x32_bf16 v[108:111], v[132:135], v[182:185], v[108:111]
	v_mfma_f32_16x16x32_bf16 v[104:107], v[140:143], v[182:185], v[104:107]
	v_mfma_f32_16x16x32_bf16 v[92:95], v[132:135], v[190:193], v[92:95]
	v_mfma_f32_16x16x32_bf16 v[88:91], v[140:143], v[190:193], v[88:91]
	s_add_i32 s50, 0, 0x1c000
	s_add_i32 s51, s78, s58
	s_waitcnt lgkmcnt(0)
	v_mfma_f32_16x16x32_bf16 v[76:79], v[132:135], v[198:201], v[76:79]
	s_mov_b32 m0, s51
	v_mfma_f32_16x16x32_bf16 v[72:75], v[140:143], v[198:201], v[72:75]
	s_barrier
	ds_read_b128 v[202:205], v252
	ds_read_b128 v[206:209], v252 offset:1024
	ds_read_b128 v[210:213], v252 offset:2048
	global_load_lds_dwordx4 v146, s[86:87]
	s_add_i32 m0, s51, 0x2000
	ds_read_b128 v[214:217], v252 offset:3072
	global_load_lds_dwordx4 v150, s[86:87]
	s_barrier
	s_waitcnt lgkmcnt(3)
	v_mfma_f32_16x16x32_bf16 v[116:119], v[202:205], v[168:171], v[116:119]
	s_waitcnt lgkmcnt(1)
	v_mfma_f32_16x16x32_bf16 v[112:115], v[210:213], v[168:171], v[112:115]
	v_mfma_f32_16x16x32_bf16 v[100:103], v[202:205], v[176:179], v[100:103]
	v_mfma_f32_16x16x32_bf16 v[96:99], v[210:213], v[176:179], v[96:99]
	v_mfma_f32_16x16x32_bf16 v[84:87], v[202:205], v[186:189], v[84:87]
	v_mfma_f32_16x16x32_bf16 v[80:83], v[210:213], v[186:189], v[80:83]
	v_mfma_f32_16x16x32_bf16 v[68:71], v[202:205], v[194:197], v[68:71]
	v_mfma_f32_16x16x32_bf16 v[64:67], v[210:213], v[194:197], v[64:67]
	v_mfma_f32_16x16x32_bf16 v[116:119], v[206:209], v[172:175], v[116:119]
	s_waitcnt lgkmcnt(0)
	v_mfma_f32_16x16x32_bf16 v[112:115], v[214:217], v[172:175], v[112:115]
	v_mfma_f32_16x16x32_bf16 v[100:103], v[206:209], v[182:185], v[100:103]
	v_mfma_f32_16x16x32_bf16 v[96:99], v[214:217], v[182:185], v[96:99]
	v_mfma_f32_16x16x32_bf16 v[84:87], v[206:209], v[190:193], v[84:87]
	v_mfma_f32_16x16x32_bf16 v[80:83], v[214:217], v[190:193], v[80:83]
	v_mfma_f32_16x16x32_bf16 v[68:71], v[206:209], v[198:201], v[68:71]
	s_mov_b32 m0, s65
	v_mfma_f32_16x16x32_bf16 v[64:67], v[214:217], v[198:201], v[64:67]
	s_barrier
	ds_read_b128 v[168:171], v166 offset:49152
	ds_read_b128 v[172:175], v166 offset:50176
	ds_read_b128 v[176:179], v166 offset:51200
	ds_read_b128 v[182:185], v166 offset:52224
	ds_read_b128 v[186:189], v166 offset:53248
	ds_read_b128 v[190:193], v166 offset:54272
	ds_read_b128 v[194:197], v166 offset:55296
	global_load_lds_dwordx4 v144, s[88:89]
	s_mov_b32 m0, s66
	ds_read_b128 v[198:201], v166 offset:56320
	global_load_lds_dwordx4 v148, s[88:89]
	s_barrier
; #define PG8_STAGE(bufoff, gbase, voff) do { _Pragma("unroll") for (int _i = 0; _i < 2; ++_i) \
;         __builtin_amdgcn_global_load_lds((const unsigned*)((const char*)(gbase) + (voff)[_i]), (LAS unsigned*)(lds + (bufoff) + ldsw + _i * 8192), 16, 0, 0); } while (0)
; #define PG8_LDA(dst, b, h) do { _Pragma("unroll") for (int m = 0; m < 4; ++m) _Pragma("unroll") for (int k = 0; k < 2; ++k) dst[m][k] = *(const LAS bf16x8*)(lds + PG8_SA(b, h) + aoff + m * 2048 + k * 1024); } while (0)
; #define PG8_LDB(dst, b, h) do { _Pragma("unroll") for (int n = 0; n < 2; ++n) _Pragma("unroll") for (int k = 0; k < 2; ++k) dst[n][k] = *(const LAS bf16x8*)(lds + PG8_SB(b, h) + boff + n * 2048 + k * 1024); } while (0)
; #define PG8_MMA(ai, bj, At, Bt) do { __builtin_amdgcn_s_setprio(1); _Pragma("unroll") for (int m = 0; m < 4; ++m) _Pragma("unroll") for (int n = 0; n < 2; ++n) _Pragma("unroll") for (int k = 0; k < 2; ++k) \
;         acc[ai][bj][m][n] = __builtin_amdgcn_mfma_f32_16x16x32_bf16(Bt[n][k], At[m][k], acc[ai][bj][m][n], 0, 0, 0); __builtin_amdgcn_s_setprio(0); } while (0)
; #define PG8_WAIT_V(n) asm volatile("s_waitcnt vmcnt(" #n ")" ::: "memory")
; template <class Epi>
; DI void gemm_phase(LAS unsigned char* lds, const Gemm g, const StaticOrder& S, const Epi& E) {
;     ...
;             PG8_LDB(B0, 0, 0); PG8_SCHED; PG8_LDA(At, 0, 0); PG8_STAGE(PG8_SA(1, 1), a1 + hstep, voffA);
;             PG8_WAIT_L(8); PG8_BAR; PG8_WAIT_L(0); PG8_MMA(0, 0, At, B0); PG8_BAR; PG8_SCHED;
;             PG8_LDB(B1, 0, 1); PG8_STAGE(PG8_SB(0, 0), b2, voffB);
;             PG8_BAR; PG8_WAIT_L(0); PG8_MMA(0, 1, At, B1); PG8_BAR;
;             PG8_LDA(At, 0, 1); PG8_STAGE(PG8_SA(0, 0), a2, voffA);
;     ...
;             PG8_WAIT_V(6); PG8_BAR; PG8_MMA(1, 1, At, B1); PG8_BAR;
;             PG8_LDB(B0, 1, 0); PG8_SCHED; PG8_LDA(At, 1, 0); PG8_STAGE(PG8_SA(0, 1), a2 + hstep, voffA);
;             PG8_WAIT_L(8); PG8_BAR; PG8_WAIT_L(0); PG8_MMA(0, 0, At, B0); PG8_BAR; PG8_SCHED;
;             PG8_LDB(B1, 1, 1); PG8_STAGE(PG8_SB(1, 0), b3, voffB);
;             PG8_BAR; PG8_WAIT_L(0); PG8_MMA(0, 1, At, B1); PG8_BAR;
;             PG8_LDA(At, 1, 1); PG8_STAGE(PG8_SA(1, 0), a3, voffA);
;             PG8_BAR; PG8_WAIT_L(0); PG8_MMA(1, 0, At, B0); PG8_BAR; PG8_SCHED;
;             PG8_STAGE(PG8_SB(1, 1), b3 + hstep, voffB);
;             PG8_WAIT_V(6); PG8_BAR; PG8_MMA(1, 1, At, B1); PG8_BAR;
	s_waitcnt lgkmcnt(7)
	v_mfma_f32_16x16x32_bf16 v[60:63], v[128:131], v[168:171], v[60:63]
	v_mfma_f32_16x16x32_bf16 v[56:59], v[136:139], v[168:171], v[56:59]
	s_waitcnt lgkmcnt(5)
	v_mfma_f32_16x16x32_bf16 v[44:47], v[128:131], v[176:179], v[44:47]
	v_mfma_f32_16x16x32_bf16 v[40:43], v[136:139], v[176:179], v[40:43]
	s_waitcnt lgkmcnt(3)
	v_mfma_f32_16x16x32_bf16 v[28:31], v[128:131], v[186:189], v[28:31]
	v_mfma_f32_16x16x32_bf16 v[24:27], v[136:139], v[186:189], v[24:27]
	s_waitcnt lgkmcnt(1)
	v_mfma_f32_16x16x32_bf16 v[12:15], v[128:131], v[194:197], v[12:15]
	v_mfma_f32_16x16x32_bf16 v[8:11], v[136:139], v[194:197], v[8:11]
	v_mfma_f32_16x16x32_bf16 v[60:63], v[132:135], v[172:175], v[60:63]
	v_mfma_f32_16x16x32_bf16 v[56:59], v[140:143], v[172:175], v[56:59]
	v_mfma_f32_16x16x32_bf16 v[44:47], v[132:135], v[182:185], v[44:47]
	v_mfma_f32_16x16x32_bf16 v[40:43], v[140:143], v[182:185], v[40:43]
	v_mfma_f32_16x16x32_bf16 v[28:31], v[132:135], v[190:193], v[28:31]
	v_mfma_f32_16x16x32_bf16 v[24:27], v[140:143], v[190:193], v[24:27]
	s_add_u32 s48, s48, 0x40080
	s_addc_u32 s49, s49, 0
	s_waitcnt lgkmcnt(0)
	v_mfma_f32_16x16x32_bf16 v[12:15], v[132:135], v[198:201], v[12:15]
	s_add_i32 s50, s50, s58
	s_mov_b32 m0, s50
	v_mfma_f32_16x16x32_bf16 v[8:11], v[140:143], v[198:201], v[8:11]
	s_barrier
	global_load_lds_dwordx4 v146, s[48:49]
	s_add_i32 m0, s50, 0x2000
	s_waitcnt vmcnt(5)
	global_load_lds_dwordx4 v150, s[48:49]
	s_barrier
	v_mfma_f32_16x16x32_bf16 v[52:55], v[202:205], v[168:171], v[52:55]
	v_mfma_f32_16x16x32_bf16 v[48:51], v[210:213], v[168:171], v[48:51]
	v_mfma_f32_16x16x32_bf16 v[36:39], v[202:205], v[176:179], v[36:39]
	v_mfma_f32_16x16x32_bf16 v[32:35], v[210:213], v[176:179], v[32:35]
	v_mfma_f32_16x16x32_bf16 v[20:23], v[202:205], v[186:189], v[20:23]
	v_mfma_f32_16x16x32_bf16 v[16:19], v[210:213], v[186:189], v[16:19]
	v_mfma_f32_16x16x32_bf16 v[4:7], v[202:205], v[194:197], v[4:7]
	v_mfma_f32_16x16x32_bf16 v[0:3], v[210:213], v[194:197], v[0:3]
	v_mfma_f32_16x16x32_bf16 v[52:55], v[206:209], v[172:175], v[52:55]
	s_add_i32 s77, s77, 2
	s_add_u32 s46, s46, 0x100
	v_mfma_f32_16x16x32_bf16 v[48:51], v[214:217], v[172:175], v[48:51]
	s_addc_u32 s47, s47, 0
	s_add_u32 s75, s75, 0x100
	v_mfma_f32_16x16x32_bf16 v[36:39], v[206:209], v[182:185], v[36:39]
	s_addc_u32 s76, s76, 0
	s_add_u32 s48, s46, 0xfffc0080
	v_mfma_f32_16x16x32_bf16 v[32:35], v[214:217], v[182:185], v[32:35]
	s_addc_u32 s49, s47, -1
	s_cmp_eq_u32 s77, 12
	v_mfma_f32_16x16x32_bf16 v[20:23], v[206:209], v[190:193], v[20:23]
	s_cselect_b32 s51, s39, s49
	s_cselect_b32 s50, s73, s48
	v_mfma_f32_16x16x32_bf16 v[16:19], v[214:217], v[190:193], v[16:19]
	s_cselect_b32 s49, s25, s76
	s_cselect_b32 s48, s74, s75
	v_mfma_f32_16x16x32_bf16 v[4:7], v[206:209], v[198:201], v[4:7]
	s_add_i32 m0, s45, 0xc000
	v_mfma_f32_16x16x32_bf16 v[0:3], v[214:217], v[198:201], v[0:3]
	s_cmp_gt_u32 s77, 13
	s_barrier
.LBB0_724:
	ds_read_b128 v[128:131], v165
	ds_read_b128 v[132:135], v165 offset:1024
	ds_read_b128 v[136:139], v165 offset:2048
	ds_read_b128 v[140:143], v165 offset:3072
	ds_read_b128 v[168:171], v166
	ds_read_b128 v[172:175], v166 offset:1024
	ds_read_b128 v[176:179], v166 offset:2048
	ds_read_b128 v[182:185], v166 offset:3072
	ds_read_b128 v[186:189], v166 offset:4096
	ds_read_b128 v[190:193], v166 offset:5120
	ds_read_b128 v[194:197], v166 offset:6144
	global_load_lds_dwordx4 v152, s[46:47]
	s_add_i32 m0, s45, 0xe000
	ds_read_b128 v[198:201], v166 offset:7168
	global_load_lds_dwordx4 v154, s[46:47]
	s_waitcnt lgkmcnt(8)
	s_barrier
	s_waitcnt lgkmcnt(7)
	v_mfma_f32_16x16x32_bf16 v[124:127], v[128:131], v[168:171], v[124:127]
	v_mfma_f32_16x16x32_bf16 v[120:123], v[136:139], v[168:171], v[120:123]
	s_waitcnt lgkmcnt(5)
	v_mfma_f32_16x16x32_bf16 v[108:111], v[128:131], v[176:179], v[108:111]
	v_mfma_f32_16x16x32_bf16 v[104:107], v[136:139], v[176:179], v[104:107]
	s_waitcnt lgkmcnt(3)
	v_mfma_f32_16x16x32_bf16 v[92:95], v[128:131], v[186:189], v[92:95]
	v_mfma_f32_16x16x32_bf16 v[88:91], v[136:139], v[186:189], v[88:91]
	s_waitcnt lgkmcnt(1)
	v_mfma_f32_16x16x32_bf16 v[76:79], v[128:131], v[194:197], v[76:79]
	v_mfma_f32_16x16x32_bf16 v[72:75], v[136:139], v[194:197], v[72:75]
	v_mfma_f32_16x16x32_bf16 v[124:127], v[132:135], v[172:175], v[124:127]
	v_mfma_f32_16x16x32_bf16 v[120:123], v[140:143], v[172:175], v[120:123]
	v_mfma_f32_16x16x32_bf16 v[108:111], v[132:135], v[182:185], v[108:111]
	v_mfma_f32_16x16x32_bf16 v[104:107], v[140:143], v[182:185], v[104:107]
	v_mfma_f32_16x16x32_bf16 v[92:95], v[132:135], v[190:193], v[92:95]
	v_mfma_f32_16x16x32_bf16 v[88:91], v[140:143], v[190:193], v[88:91]
	s_add_i32 s78, s70, s58
	s_add_u32 s86, s48, s12
	s_waitcnt lgkmcnt(0)
	v_mfma_f32_16x16x32_bf16 v[76:79], v[132:135], v[198:201], v[76:79]
	s_addc_u32 s87, s49, s13
	s_mov_b32 m0, s78
	v_mfma_f32_16x16x32_bf16 v[72:75], v[140:143], v[198:201], v[72:75]
	s_barrier
	ds_read_b128 v[202:205], v167
	ds_read_b128 v[206:209], v167 offset:1024
	ds_read_b128 v[210:213], v167 offset:2048
	global_load_lds_dwordx4 v146, s[48:49]
	s_add_i32 m0, s78, 0x2000
	ds_read_b128 v[214:217], v167 offset:3072
	global_load_lds_dwordx4 v150, s[48:49]
	s_barrier
; #define PG8_STAGE(bufoff, gbase, voff) do { _Pragma("unroll") for (int _i = 0; _i < 2; ++_i) \
;         __builtin_amdgcn_global_load_lds((const unsigned*)((const char*)(gbase) + (voff)[_i]), (LAS unsigned*)(lds + (bufoff) + ldsw + _i * 8192), 16, 0, 0); } while (0)
; #define PG8_LDA(dst, b, h) do { _Pragma("unroll") for (int m = 0; m < 4; ++m) _Pragma("unroll") for (int k = 0; k < 2; ++k) dst[m][k] = *(const LAS bf16x8*)(lds + PG8_SA(b, h) + aoff + m * 2048 + k * 1024); } while (0)
; #define PG8_LDB(dst, b, h) do { _Pragma("unroll") for (int n = 0; n < 2; ++n) _Pragma("unroll") for (int k = 0; k < 2; ++k) dst[n][k] = *(const LAS bf16x8*)(lds + PG8_SB(b, h) + boff + n * 2048 + k * 1024); } while (0)
; #define PG8_MMA(ai, bj, At, Bt) do { __builtin_amdgcn_s_setprio(1); _Pragma("unroll") for (int m = 0; m < 4; ++m) _Pragma("unroll") for (int n = 0; n < 2; ++n) _Pragma("unroll") for (int k = 0; k < 2; ++k) \
;         acc[ai][bj][m][n] = __builtin_amdgcn_mfma_f32_16x16x32_bf16(Bt[n][k], At[m][k], acc[ai][bj][m][n], 0, 0, 0); __builtin_amdgcn_s_setprio(0); } while (0)
; #define PG8_WAIT_V(n) asm volatile("s_waitcnt vmcnt(" #n ")" ::: "memory")
; #define PG8_WAIT_L(n) asm volatile("s_waitcnt lgkmcnt(" #n ")" ::: "memory")
; template <class Epi>
; DI void gemm_phase(LAS unsigned char* lds, const Gemm g, const StaticOrder& S, const Epi& E) {
;     ...
;             PG8_LDB(B1, 0, 1); PG8_STAGE(PG8_SB(0, 0), b2, voffB);
;             PG8_BAR; PG8_WAIT_L(0); PG8_MMA(0, 1, At, B1); PG8_BAR;
;             PG8_LDA(At, 0, 1); PG8_STAGE(PG8_SA(0, 0), a2, voffA);
;             PG8_BAR; PG8_WAIT_L(0); PG8_MMA(1, 0, At, B0); PG8_BAR; PG8_SCHED;
;             PG8_STAGE(PG8_SB(0, 1), b2 + hstep, voffB);
;             PG8_WAIT_V(6); PG8_BAR; PG8_MMA(1, 1, At, B1); PG8_BAR;
;             PG8_LDB(B0, 1, 0); PG8_SCHED; PG8_LDA(At, 1, 0); PG8_STAGE(PG8_SA(0, 1), a2 + hstep, voffA);
;             PG8_WAIT_L(8); PG8_BAR; PG8_WAIT_L(0); PG8_MMA(0, 0, At, B0); PG8_BAR; PG8_SCHED;
;             PG8_LDB(B1, 1, 1); PG8_STAGE(PG8_SB(1, 0), b3, voffB);
;             PG8_BAR; PG8_WAIT_L(0); PG8_MMA(0, 1, At, B1); PG8_BAR;
;             PG8_LDA(At, 1, 1); PG8_STAGE(PG8_SA(1, 0), a3, voffA);
;             PG8_BAR; PG8_WAIT_L(0); PG8_MMA(1, 0, At, B0); PG8_BAR; PG8_SCHED;
;             PG8_STAGE(PG8_SB(1, 1), b3 + hstep, voffB);
;             PG8_WAIT_V(6); PG8_BAR; PG8_MMA(1, 1, At, B1); PG8_BAR;
	s_waitcnt lgkmcnt(3)
	v_mfma_f32_16x16x32_bf16 v[116:119], v[202:205], v[168:171], v[116:119]
	s_waitcnt lgkmcnt(1)
	v_mfma_f32_16x16x32_bf16 v[112:115], v[210:213], v[168:171], v[112:115]
	v_mfma_f32_16x16x32_bf16 v[100:103], v[202:205], v[176:179], v[100:103]
	v_mfma_f32_16x16x32_bf16 v[96:99], v[210:213], v[176:179], v[96:99]
	v_mfma_f32_16x16x32_bf16 v[84:87], v[202:205], v[186:189], v[84:87]
	v_mfma_f32_16x16x32_bf16 v[80:83], v[210:213], v[186:189], v[80:83]
	v_mfma_f32_16x16x32_bf16 v[68:71], v[202:205], v[194:197], v[68:71]
	v_mfma_f32_16x16x32_bf16 v[64:67], v[210:213], v[194:197], v[64:67]
	v_mfma_f32_16x16x32_bf16 v[116:119], v[206:209], v[172:175], v[116:119]
	s_waitcnt lgkmcnt(0)
	v_mfma_f32_16x16x32_bf16 v[112:115], v[214:217], v[172:175], v[112:115]
	v_mfma_f32_16x16x32_bf16 v[100:103], v[206:209], v[182:185], v[100:103]
	v_mfma_f32_16x16x32_bf16 v[96:99], v[214:217], v[182:185], v[96:99]
	v_mfma_f32_16x16x32_bf16 v[84:87], v[206:209], v[190:193], v[84:87]
	v_mfma_f32_16x16x32_bf16 v[80:83], v[214:217], v[190:193], v[80:83]
	s_mov_b32 m0, s45
	s_add_u32 s88, s50, s12
	v_mfma_f32_16x16x32_bf16 v[68:71], v[206:209], v[198:201], v[68:71]
	s_addc_u32 s89, s51, s13
	v_mfma_f32_16x16x32_bf16 v[64:67], v[214:217], v[198:201], v[64:67]
	s_barrier
	ds_read_b128 v[168:171], v166 offset:16384
	ds_read_b128 v[172:175], v166 offset:17408
	ds_read_b128 v[176:179], v166 offset:18432
	ds_read_b128 v[182:185], v166 offset:19456
	ds_read_b128 v[186:189], v166 offset:20480
	ds_read_b128 v[190:193], v166 offset:21504
	ds_read_b128 v[194:197], v166 offset:22528
	global_load_lds_dwordx4 v144, s[50:51]
	s_mov_b32 m0, s59
	ds_read_b128 v[198:201], v166 offset:23552
	global_load_lds_dwordx4 v148, s[50:51]
	s_barrier
	s_waitcnt lgkmcnt(7)
	v_mfma_f32_16x16x32_bf16 v[60:63], v[128:131], v[168:171], v[60:63]
	v_mfma_f32_16x16x32_bf16 v[56:59], v[136:139], v[168:171], v[56:59]
	s_waitcnt lgkmcnt(5)
	v_mfma_f32_16x16x32_bf16 v[44:47], v[128:131], v[176:179], v[44:47]
	v_mfma_f32_16x16x32_bf16 v[40:43], v[136:139], v[176:179], v[40:43]
	s_waitcnt lgkmcnt(3)
	v_mfma_f32_16x16x32_bf16 v[28:31], v[128:131], v[186:189], v[28:31]
	v_mfma_f32_16x16x32_bf16 v[24:27], v[136:139], v[186:189], v[24:27]
	s_waitcnt lgkmcnt(1)
	v_mfma_f32_16x16x32_bf16 v[12:15], v[128:131], v[194:197], v[12:15]
	v_mfma_f32_16x16x32_bf16 v[8:11], v[136:139], v[194:197], v[8:11]
	v_mfma_f32_16x16x32_bf16 v[60:63], v[132:135], v[172:175], v[60:63]
	v_mfma_f32_16x16x32_bf16 v[56:59], v[140:143], v[172:175], v[56:59]
	s_add_u32 s78, s48, 0x40000
	s_addc_u32 s79, s49, 0
	v_mfma_f32_16x16x32_bf16 v[44:47], v[132:135], v[182:185], v[44:47]
	s_add_i32 s80, s71, s58
	s_mov_b32 m0, s80
	v_mfma_f32_16x16x32_bf16 v[40:43], v[140:143], v[182:185], v[40:43]
	s_lshl_b32 s84, s44, 20
	s_lshl_b32 s85, s72, 10
	v_mfma_f32_16x16x32_bf16 v[28:31], v[132:135], v[190:193], v[28:31]
	s_add_u32 s84, s84, s85
	s_add_i32 s85, s77, 2
	v_mfma_f32_16x16x32_bf16 v[24:27], v[140:143], v[190:193], v[24:27]
	s_lshl_b32 s85, s85, 13
	s_add_u32 s84, s84, s85
	s_waitcnt lgkmcnt(0)
	v_mfma_f32_16x16x32_bf16 v[12:15], v[132:135], v[198:201], v[12:15]
	s_add_u32 s84, s36, s84
	s_addc_u32 s85, s37, 0
	v_mfma_f32_16x16x32_bf16 v[8:11], v[140:143], v[198:201], v[8:11]
	s_barrier
	global_load_lds_dwordx4 v146, s[78:79]
	s_add_i32 m0, s80, 0x2000
	s_waitcnt vmcnt(5)
	global_load_lds_dwordx4 v150, s[78:79]
	global_load_dword v249, v248, s[84:85]
	s_barrier
	v_mfma_f32_16x16x32_bf16 v[52:55], v[202:205], v[168:171], v[52:55]
	v_mfma_f32_16x16x32_bf16 v[48:51], v[210:213], v[168:171], v[48:51]
	v_mfma_f32_16x16x32_bf16 v[36:39], v[202:205], v[176:179], v[36:39]
	v_mfma_f32_16x16x32_bf16 v[32:35], v[210:213], v[176:179], v[32:35]
	v_mfma_f32_16x16x32_bf16 v[20:23], v[202:205], v[186:189], v[20:23]
	v_mfma_f32_16x16x32_bf16 v[16:19], v[210:213], v[186:189], v[16:19]
	v_mfma_f32_16x16x32_bf16 v[4:7], v[202:205], v[194:197], v[4:7]
	v_mfma_f32_16x16x32_bf16 v[0:3], v[210:213], v[194:197], v[0:3]
	v_mfma_f32_16x16x32_bf16 v[52:55], v[206:209], v[172:175], v[52:55]
	v_mfma_f32_16x16x32_bf16 v[48:51], v[214:217], v[172:175], v[48:51]
	v_mfma_f32_16x16x32_bf16 v[36:39], v[206:209], v[182:185], v[36:39]
	v_mfma_f32_16x16x32_bf16 v[32:35], v[214:217], v[182:185], v[32:35]
	v_mfma_f32_16x16x32_bf16 v[20:23], v[206:209], v[190:193], v[20:23]
	v_mfma_f32_16x16x32_bf16 v[16:19], v[214:217], v[190:193], v[16:19]
	v_mfma_f32_16x16x32_bf16 v[4:7], v[206:209], v[198:201], v[4:7]
	s_add_i32 s78, 0, 0x18000
	v_mfma_f32_16x16x32_bf16 v[0:3], v[214:217], v[198:201], v[0:3]
	s_barrier
	ds_read_b128 v[128:131], v253
	ds_read_b128 v[132:135], v253 offset:1024
	ds_read_b128 v[136:139], v253 offset:2048
	ds_read_b128 v[140:143], v253 offset:3072
	s_add_u32 s50, s50, 0x40000
	s_addc_u32 s51, s51, 0
	s_mov_b32 m0, s60
	ds_read_b128 v[168:171], v166 offset:32768
	ds_read_b128 v[172:175], v166 offset:33792
	ds_read_b128 v[176:179], v166 offset:34816
	ds_read_b128 v[182:185], v166 offset:35840
	ds_read_b128 v[186:189], v166 offset:36864
	ds_read_b128 v[190:193], v166 offset:37888
	ds_read_b128 v[194:197], v166 offset:38912
	global_load_lds_dwordx4 v144, s[50:51]
	s_mov_b32 m0, s61
	ds_read_b128 v[198:201], v166 offset:39936
	global_load_lds_dwordx4 v148, s[50:51]
	s_waitcnt lgkmcnt(8)
	s_barrier
; #define PG8_STAGE(bufoff, gbase, voff) do { _Pragma("unroll") for (int _i = 0; _i < 2; ++_i) \
;         __builtin_amdgcn_global_load_lds((const unsigned*)((const char*)(gbase) + (voff)[_i]), (LAS unsigned*)(lds + (bufoff) + ldsw + _i * 8192), 16, 0, 0); } while (0)
; #define PG8_LDA(dst, b, h) do { _Pragma("unroll") for (int m = 0; m < 4; ++m) _Pragma("unroll") for (int k = 0; k < 2; ++k) dst[m][k] = *(const LAS bf16x8*)(lds + PG8_SA(b, h) + aoff + m * 2048 + k * 1024); } while (0)
; #define PG8_LDB(dst, b, h) do { _Pragma("unroll") for (int n = 0; n < 2; ++n) _Pragma("unroll") for (int k = 0; k < 2; ++k) dst[n][k] = *(const LAS bf16x8*)(lds + PG8_SB(b, h) + boff + n * 2048 + k * 1024); } while (0)
; #define PG8_MMA(ai, bj, At, Bt) do { __builtin_amdgcn_s_setprio(1); _Pragma("unroll") for (int m = 0; m < 4; ++m) _Pragma("unroll") for (int n = 0; n < 2; ++n) _Pragma("unroll") for (int k = 0; k < 2; ++k) \
;         acc[ai][bj][m][n] = __builtin_amdgcn_mfma_f32_16x16x32_bf16(Bt[n][k], At[m][k], acc[ai][bj][m][n], 0, 0, 0); __builtin_amdgcn_s_setprio(0); } while (0)
; #define PG8_WAIT_V(n) asm volatile("s_waitcnt vmcnt(" #n ")" ::: "memory")
; #define PG8_WAIT_L(n) asm volatile("s_waitcnt lgkmcnt(" #n ")" ::: "memory")
; #define PG8_BAR __builtin_amdgcn_s_barrier()
; #define PG8_SCHED __builtin_amdgcn_sched_barrier(0)
; template <class Epi>
; DI void gemm_phase(LAS unsigned char* lds, const Gemm g, const StaticOrder& S, const Epi& E) {
;     ...
;             PG8_LDB(B0, 1, 0); PG8_SCHED; PG8_LDA(At, 1, 0); PG8_STAGE(PG8_SA(0, 1), a2 + hstep, voffA);
;             PG8_WAIT_L(8); PG8_BAR; PG8_WAIT_L(0); PG8_MMA(0, 0, At, B0); PG8_BAR; PG8_SCHED;
;             PG8_LDB(B1, 1, 1); PG8_STAGE(PG8_SB(1, 0), b3, voffB);
;             PG8_BAR; PG8_WAIT_L(0); PG8_MMA(0, 1, At, B1); PG8_BAR;
;             PG8_LDA(At, 1, 1); PG8_STAGE(PG8_SA(1, 0), a3, voffA);
;             PG8_BAR; PG8_WAIT_L(0); PG8_MMA(1, 0, At, B0); PG8_BAR; PG8_SCHED;
;             PG8_STAGE(PG8_SB(1, 1), b3 + hstep, voffB);
;             PG8_WAIT_V(6); PG8_BAR; PG8_MMA(1, 1, At, B1); PG8_BAR;
	s_waitcnt lgkmcnt(7)
	v_mfma_f32_16x16x32_bf16 v[124:127], v[128:131], v[168:171], v[124:127]
	v_mfma_f32_16x16x32_bf16 v[120:123], v[136:139], v[168:171], v[120:123]
	s_waitcnt lgkmcnt(5)
	v_mfma_f32_16x16x32_bf16 v[108:111], v[128:131], v[176:179], v[108:111]
	v_mfma_f32_16x16x32_bf16 v[104:107], v[136:139], v[176:179], v[104:107]
	s_waitcnt lgkmcnt(3)
	v_mfma_f32_16x16x32_bf16 v[92:95], v[128:131], v[186:189], v[92:95]
	v_mfma_f32_16x16x32_bf16 v[88:91], v[136:139], v[186:189], v[88:91]
	s_waitcnt lgkmcnt(1)
	v_mfma_f32_16x16x32_bf16 v[76:79], v[128:131], v[194:197], v[76:79]
	v_mfma_f32_16x16x32_bf16 v[72:75], v[136:139], v[194:197], v[72:75]
	v_mfma_f32_16x16x32_bf16 v[124:127], v[132:135], v[172:175], v[124:127]
	v_mfma_f32_16x16x32_bf16 v[120:123], v[140:143], v[172:175], v[120:123]
	v_mfma_f32_16x16x32_bf16 v[108:111], v[132:135], v[182:185], v[108:111]
	v_mfma_f32_16x16x32_bf16 v[104:107], v[140:143], v[182:185], v[104:107]
	v_mfma_f32_16x16x32_bf16 v[92:95], v[132:135], v[190:193], v[92:95]
	v_mfma_f32_16x16x32_bf16 v[88:91], v[140:143], v[190:193], v[88:91]
	s_add_i32 s50, 0, 0x1c000
	s_add_i32 s51, s78, s58
	s_waitcnt lgkmcnt(0)
	v_mfma_f32_16x16x32_bf16 v[76:79], v[132:135], v[198:201], v[76:79]
	s_mov_b32 m0, s51
	v_mfma_f32_16x16x32_bf16 v[72:75], v[140:143], v[198:201], v[72:75]
	s_barrier
	ds_read_b128 v[202:205], v252
	ds_read_b128 v[206:209], v252 offset:1024
	ds_read_b128 v[210:213], v252 offset:2048
	global_load_lds_dwordx4 v146, s[86:87]
	s_add_i32 m0, s51, 0x2000
	ds_read_b128 v[214:217], v252 offset:3072
	global_load_lds_dwordx4 v150, s[86:87]
	s_barrier
	s_waitcnt lgkmcnt(3)
	v_mfma_f32_16x16x32_bf16 v[116:119], v[202:205], v[168:171], v[116:119]
	s_waitcnt lgkmcnt(1)
	v_mfma_f32_16x16x32_bf16 v[112:115], v[210:213], v[168:171], v[112:115]
	v_mfma_f32_16x16x32_bf16 v[100:103], v[202:205], v[176:179], v[100:103]
	v_mfma_f32_16x16x32_bf16 v[96:99], v[210:213], v[176:179], v[96:99]
	v_mfma_f32_16x16x32_bf16 v[84:87], v[202:205], v[186:189], v[84:87]
	v_mfma_f32_16x16x32_bf16 v[80:83], v[210:213], v[186:189], v[80:83]
	v_mfma_f32_16x16x32_bf16 v[68:71], v[202:205], v[194:197], v[68:71]
	v_mfma_f32_16x16x32_bf16 v[64:67], v[210:213], v[194:197], v[64:67]
	v_mfma_f32_16x16x32_bf16 v[116:119], v[206:209], v[172:175], v[116:119]
	s_waitcnt lgkmcnt(0)
	v_mfma_f32_16x16x32_bf16 v[112:115], v[214:217], v[172:175], v[112:115]
	v_mfma_f32_16x16x32_bf16 v[100:103], v[206:209], v[182:185], v[100:103]
	v_mfma_f32_16x16x32_bf16 v[96:99], v[214:217], v[182:185], v[96:99]
	v_mfma_f32_16x16x32_bf16 v[84:87], v[206:209], v[190:193], v[84:87]
	v_mfma_f32_16x16x32_bf16 v[80:83], v[214:217], v[190:193], v[80:83]
	v_mfma_f32_16x16x32_bf16 v[68:71], v[206:209], v[198:201], v[68:71]
	s_mov_b32 m0, s65
	v_mfma_f32_16x16x32_bf16 v[64:67], v[214:217], v[198:201], v[64:67]
	s_barrier
	ds_read_b128 v[168:171], v166 offset:49152
	ds_read_b128 v[172:175], v166 offset:50176
	ds_read_b128 v[176:179], v166 offset:51200
	ds_read_b128 v[182:185], v166 offset:52224
	ds_read_b128 v[186:189], v166 offset:53248
	ds_read_b128 v[190:193], v166 offset:54272
	ds_read_b128 v[194:197], v166 offset:55296
	global_load_lds_dwordx4 v144, s[88:89]
	s_mov_b32 m0, s66
	ds_read_b128 v[198:201], v166 offset:56320
	global_load_lds_dwordx4 v148, s[88:89]
	s_barrier
	s_waitcnt lgkmcnt(7)
	v_mfma_f32_16x16x32_bf16 v[60:63], v[128:131], v[168:171], v[60:63]
	v_mfma_f32_16x16x32_bf16 v[56:59], v[136:139], v[168:171], v[56:59]
	s_waitcnt lgkmcnt(5)
	v_mfma_f32_16x16x32_bf16 v[44:47], v[128:131], v[176:179], v[44:47]
	v_mfma_f32_16x16x32_bf16 v[40:43], v[136:139], v[176:179], v[40:43]
	s_waitcnt lgkmcnt(3)
	v_mfma_f32_16x16x32_bf16 v[28:31], v[128:131], v[186:189], v[28:31]
	v_mfma_f32_16x16x32_bf16 v[24:27], v[136:139], v[186:189], v[24:27]
	s_waitcnt lgkmcnt(1)
	v_mfma_f32_16x16x32_bf16 v[12:15], v[128:131], v[194:197], v[12:15]
	v_mfma_f32_16x16x32_bf16 v[8:11], v[136:139], v[194:197], v[8:11]
	v_mfma_f32_16x16x32_bf16 v[60:63], v[132:135], v[172:175], v[60:63]
	v_mfma_f32_16x16x32_bf16 v[56:59], v[140:143], v[172:175], v[56:59]
	v_mfma_f32_16x16x32_bf16 v[44:47], v[132:135], v[182:185], v[44:47]
	v_mfma_f32_16x16x32_bf16 v[40:43], v[140:143], v[182:185], v[40:43]
	v_mfma_f32_16x16x32_bf16 v[28:31], v[132:135], v[190:193], v[28:31]
	v_mfma_f32_16x16x32_bf16 v[24:27], v[140:143], v[190:193], v[24:27]
	s_add_u32 s48, s48, 0x40080
	s_addc_u32 s49, s49, 0
	s_waitcnt lgkmcnt(0)
	v_mfma_f32_16x16x32_bf16 v[12:15], v[132:135], v[198:201], v[12:15]
	s_add_i32 s50, s50, s58
	s_mov_b32 m0, s50
	v_mfma_f32_16x16x32_bf16 v[8:11], v[140:143], v[198:201], v[8:11]
	s_barrier
	global_load_lds_dwordx4 v146, s[48:49]
	s_add_i32 m0, s50, 0x2000
	s_waitcnt vmcnt(5)
	global_load_lds_dwordx4 v150, s[48:49]
	s_barrier
	v_mfma_f32_16x16x32_bf16 v[52:55], v[202:205], v[168:171], v[52:55]
	v_mfma_f32_16x16x32_bf16 v[48:51], v[210:213], v[168:171], v[48:51]
	v_mfma_f32_16x16x32_bf16 v[36:39], v[202:205], v[176:179], v[36:39]
	v_mfma_f32_16x16x32_bf16 v[32:35], v[210:213], v[176:179], v[32:35]
	v_mfma_f32_16x16x32_bf16 v[20:23], v[202:205], v[186:189], v[20:23]
	v_mfma_f32_16x16x32_bf16 v[16:19], v[210:213], v[186:189], v[16:19]
	v_mfma_f32_16x16x32_bf16 v[4:7], v[202:205], v[194:197], v[4:7]
	v_mfma_f32_16x16x32_bf16 v[0:3], v[210:213], v[194:197], v[0:3]
	v_mfma_f32_16x16x32_bf16 v[52:55], v[206:209], v[172:175], v[52:55]
	s_add_i32 s77, s77, 2
	s_add_u32 s46, s46, 0x100
	v_mfma_f32_16x16x32_bf16 v[48:51], v[214:217], v[172:175], v[48:51]
	s_addc_u32 s47, s47, 0
	s_add_u32 s75, s75, 0x100
	v_mfma_f32_16x16x32_bf16 v[36:39], v[206:209], v[182:185], v[36:39]
	s_addc_u32 s76, s76, 0
	s_add_u32 s48, s46, 0xfffc0080
	v_mfma_f32_16x16x32_bf16 v[32:35], v[214:217], v[182:185], v[32:35]
	s_addc_u32 s49, s47, -1
	s_cmp_eq_u32 s77, 12
	v_mfma_f32_16x16x32_bf16 v[20:23], v[206:209], v[190:193], v[20:23]
	s_cselect_b32 s51, s39, s49
	s_cselect_b32 s50, s73, s48
	v_mfma_f32_16x16x32_bf16 v[16:19], v[214:217], v[190:193], v[16:19]
	s_cselect_b32 s49, s25, s76
	s_cselect_b32 s48, s74, s75
	v_mfma_f32_16x16x32_bf16 v[4:7], v[206:209], v[198:201], v[4:7]
	s_add_i32 m0, s45, 0xc000
	v_mfma_f32_16x16x32_bf16 v[0:3], v[214:217], v[198:201], v[0:3]
	s_cmp_gt_u32 s77, 13
	s_barrier
; DI unsigned pk2(float a, float b) { f32x2 v = {a, b}; bf16x2_t r = __builtin_convertvector(v, bf16x2_t); return __builtin_bit_cast(unsigned, r); }
;     DI void operator()(const f32x4 (&acc)[2][2][4][2], const Unit& u, int wr, int wc, int fr, int fq) const {
;         const int row0 = u.pm * BM + wr * 64 + fr, col0 = u.pn * BM + wc * 32 + 8 * fq;
;         const float* gp = gate + (size_t)((u.pm * BM) >> 12) * NMODC + col0;
;         f32x4 gv[2][2];
; #pragma unroll
;         for (int bj = 0; bj < 2; ++bj)
; #pragma unroll
;             for (int n = 0; n < 2; ++n) gv[bj][n] = *(const f32x4*)(gp + bj * HALF + n * 4);
; #pragma unroll
;         for (int ai = 0; ai < 2; ++ai)
; #pragma unroll
;             for (int m = 0; m < 4; ++m) { const size_t ro = (size_t)(row0 + ai * HALF + m * 16) * DM + col0;
; #pragma unroll
;                 for (int bj = 0; bj < 2; ++bj) {
;                     const f32x4 x0 = *(const f32x4*)(base + ro + bj * HALF) + gv[bj][0] * acc[ai][bj][m][0], x1 = *(const f32x4*)(base + ro + bj * HALF + 4) + gv[bj][1] * acc[ai][bj][m][1];
;                     u32x4 w; w.x = pk2(x0.x, x0.y); w.y = pk2(x0.z, x0.w); w.z = pk2(x1.x, x1.y); w.w = pk2(x1.z, x1.w);
;                     *(u32x4*)(outb + ro + bj * HALF) = w; } }
	s_cbranch_scc0 .LBB0_724
	v_lshl_add_u32 v171, s44, 8, v162
	v_lshl_or_b32 v172, s72, 8, v164
	s_ashr_i32 s25, s44, 4
	s_mul_hi_i32 s39, s25, 0x6000
	s_mulk_i32 s25, 0x6000
	s_add_u32 s46, s63, s25
	s_addc_u32 s47, s64, s39
	v_lshlrev_b32_e32 v168, 2, v172
	v_lshlrev_b32_e32 v160, 12, v171
	v_lshlrev_b32_e32 v161, 11, v171
	global_load_dwordx4 v[128:131], v168, s[46:47]
	global_load_dwordx4 v[132:135], v168, s[46:47] offset:16
	global_load_dwordx4 v[136:139], v168, s[46:47] offset:512
	global_load_dwordx4 v[140:143], v168, s[46:47] offset:528
	v_lshl_add_u32 v160, v172, 2, v160
	v_lshl_add_u32 v161, v172, 1, v161
	s_mov_b32 s72, s24
	s_mov_b32 s44, s38
	s_mov_b64 s[48:49], s[42:43]
	s_mov_b64 s[46:47], s[40:41]
	global_load_dwordx4 v[184:187], v160, s[36:37]
	global_load_dwordx4 v[188:191], v160, s[36:37] offset:16
	global_load_dwordx4 v[192:195], v160, s[36:37] offset:512
	global_load_dwordx4 v[196:199], v160, s[36:37] offset:528
	v_add_u32_e32 v169, 0x10000, v160
	global_load_dwordx4 v[200:203], v169, s[36:37]
	global_load_dwordx4 v[204:207], v169, s[36:37] offset:16
	v_add_u32_e32 v169, 0x10000, v160
	global_load_dwordx4 v[208:211], v169, s[36:37] offset:512
	global_load_dwordx4 v[212:215], v169, s[36:37] offset:528
	v_add_u32_e32 v169, 0x20000, v160
	global_load_dwordx4 v[216:219], v169, s[36:37]
	global_load_dwordx4 v[220:223], v169, s[36:37] offset:16
	v_add_u32_e32 v169, 0x20000, v160
	global_load_dwordx4 v[224:227], v169, s[36:37] offset:512
	global_load_dwordx4 v[228:231], v169, s[36:37] offset:528
	v_add_u32_e32 v169, 0x30000, v160
	global_load_dwordx4 v[232:235], v169, s[36:37]
	global_load_dwordx4 v[236:239], v169, s[36:37] offset:16
	v_add_u32_e32 v169, 0x30000, v160
	global_load_dwordx4 v[240:243], v169, s[36:37] offset:512
	global_load_dwordx4 v[244:247], v169, s[36:37] offset:528
	s_waitcnt vmcnt(14)
	v_pk_fma_f32 v[124:125], v[124:125], v[128:129], v[184:185]
	v_pk_fma_f32 v[126:127], v[126:127], v[130:131], v[186:187]
	v_pk_fma_f32 v[120:121], v[120:121], v[132:133], v[188:189]
	v_pk_fma_f32 v[122:123], v[122:123], v[134:135], v[190:191]
	v_add_u32_e32 v169, 0x80000, v160
	global_load_dwordx4 v[184:187], v169, s[36:37]
	global_load_dwordx4 v[188:191], v169, s[36:37] offset:16
	v_cvt_pk_bf16_f32 v124, v124, v125
	v_cvt_pk_bf16_f32 v125, v126, v127
	v_cvt_pk_bf16_f32 v126, v120, v121
	v_cvt_pk_bf16_f32 v127, v122, v123
	global_store_dwordx4 v161, v[124:127], s[8:9]
	s_waitcnt vmcnt(15)
	v_pk_fma_f32 v[116:117], v[116:117], v[136:137], v[192:193]
	v_pk_fma_f32 v[118:119], v[118:119], v[138:139], v[194:195]
	v_pk_fma_f32 v[112:113], v[112:113], v[140:141], v[196:197]
	v_pk_fma_f32 v[114:115], v[114:115], v[142:143], v[198:199]
	v_add_u32_e32 v169, 0x80000, v160
	global_load_dwordx4 v[192:195], v169, s[36:37] offset:512
	global_load_dwordx4 v[196:199], v169, s[36:37] offset:528
	v_cvt_pk_bf16_f32 v116, v116, v117
	v_cvt_pk_bf16_f32 v117, v118, v119
	v_cvt_pk_bf16_f32 v118, v112, v113
	v_cvt_pk_bf16_f32 v119, v114, v115
	global_store_dwordx4 v161, v[116:119], s[8:9] offset:256
	s_waitcnt vmcnt(16)
	v_pk_fma_f32 v[108:109], v[108:109], v[128:129], v[200:201]
	v_pk_fma_f32 v[110:111], v[110:111], v[130:131], v[202:203]
	v_pk_fma_f32 v[104:105], v[104:105], v[132:133], v[204:205]
	v_pk_fma_f32 v[106:107], v[106:107], v[134:135], v[206:207]
	v_add_u32_e32 v169, 0x90000, v160
	global_load_dwordx4 v[200:203], v169, s[36:37]
	global_load_dwordx4 v[204:207], v169, s[36:37] offset:16
	v_cvt_pk_bf16_f32 v108, v108, v109
	v_cvt_pk_bf16_f32 v109, v110, v111
	v_cvt_pk_bf16_f32 v110, v104, v105
	v_cvt_pk_bf16_f32 v111, v106, v107
	v_add_u32_e32 v170, 0x8000, v161
	global_store_dwordx4 v170, v[108:111], s[8:9]
	s_waitcnt vmcnt(17)
	v_pk_fma_f32 v[100:101], v[100:101], v[136:137], v[208:209]
	v_pk_fma_f32 v[102:103], v[102:103], v[138:139], v[210:211]
	v_pk_fma_f32 v[96:97], v[96:97], v[140:141], v[212:213]
	v_pk_fma_f32 v[98:99], v[98:99], v[142:143], v[214:215]
	v_add_u32_e32 v169, 0x90000, v160
	global_load_dwordx4 v[208:211], v169, s[36:37] offset:512
	global_load_dwordx4 v[212:215], v169, s[36:37] offset:528
	v_cvt_pk_bf16_f32 v100, v100, v101
	v_cvt_pk_bf16_f32 v101, v102, v103
	v_cvt_pk_bf16_f32 v102, v96, v97
	v_cvt_pk_bf16_f32 v103, v98, v99
	v_add_u32_e32 v170, 0x8000, v161
	global_store_dwordx4 v170, v[100:103], s[8:9] offset:256
	s_waitcnt vmcnt(18)
	v_pk_fma_f32 v[92:93], v[92:93], v[128:129], v[216:217]
	v_pk_fma_f32 v[94:95], v[94:95], v[130:131], v[218:219]
	v_pk_fma_f32 v[88:89], v[88:89], v[132:133], v[220:221]
	v_pk_fma_f32 v[90:91], v[90:91], v[134:135], v[222:223]
	v_add_u32_e32 v169, 0xa0000, v160
	global_load_dwordx4 v[216:219], v169, s[36:37]
	global_load_dwordx4 v[220:223], v169, s[36:37] offset:16
	v_cvt_pk_bf16_f32 v92, v92, v93
	v_cvt_pk_bf16_f32 v93, v94, v95
	v_cvt_pk_bf16_f32 v94, v88, v89
	v_cvt_pk_bf16_f32 v95, v90, v91
	v_add_u32_e32 v170, 0x10000, v161
	global_store_dwordx4 v170, v[92:95], s[8:9]
	s_waitcnt vmcnt(19)
	v_pk_fma_f32 v[84:85], v[84:85], v[136:137], v[224:225]
	v_pk_fma_f32 v[86:87], v[86:87], v[138:139], v[226:227]
	v_pk_fma_f32 v[80:81], v[80:81], v[140:141], v[228:229]
	v_pk_fma_f32 v[82:83], v[82:83], v[142:143], v[230:231]
	v_add_u32_e32 v169, 0xa0000, v160
	global_load_dwordx4 v[224:227], v169, s[36:37] offset:512
	global_load_dwordx4 v[228:231], v169, s[36:37] offset:528
	v_cvt_pk_bf16_f32 v84, v84, v85
	v_cvt_pk_bf16_f32 v85, v86, v87
	v_cvt_pk_bf16_f32 v86, v80, v81
	v_cvt_pk_bf16_f32 v87, v82, v83
	v_add_u32_e32 v170, 0x10000, v161
	global_store_dwordx4 v170, v[84:87], s[8:9] offset:256
	s_waitcnt vmcnt(20)
; DI unsigned pk2(float a, float b) { f32x2 v = {a, b}; bf16x2_t r = __builtin_convertvector(v, bf16x2_t); return __builtin_bit_cast(unsigned, r); }
; template <class Epi>
; DI void gemm_phase(LAS unsigned char* lds, const Gemm g, const StaticOrder& S, const Epi& E) {
;     ...
;         if (!has_next) break;
; #pragma unroll
;         for (int a = 0; a < 2; ++a)
; #pragma unroll
;             for (int b = 0; b < 2; ++b)
; #pragma unroll
;                 for (int m = 0; m < 4; ++m)
; #pragma unroll
;                     for (int n = 0; n < 2; ++n) acc[a][b][m][n] = (f32x4){0.f, 0.f, 0.f, 0.f};
;         cur = nxt; cA = nA; cB = nB; ++ui;
;     }
;     DI void operator()(const f32x4 (&acc)[2][2][4][2], const Unit& u, int wr, int wc, int fr, int fq) const {
;     ...
; #pragma unroll
;         for (int ai = 0; ai < 2; ++ai)
; #pragma unroll
;             for (int m = 0; m < 4; ++m) { const size_t ro = (size_t)(row0 + ai * HALF + m * 16) * DM + col0;
; #pragma unroll
;                 for (int bj = 0; bj < 2; ++bj) {
;                     const f32x4 x0 = *(const f32x4*)(base + ro + bj * HALF) + gv[bj][0] * acc[ai][bj][m][0], x1 = *(const f32x4*)(base + ro + bj * HALF + 4) + gv[bj][1] * acc[ai][bj][m][1];
;                     u32x4 w; w.x = pk2(x0.x, x0.y); w.y = pk2(x0.z, x0.w); w.z = pk2(x1.x, x1.y); w.w = pk2(x1.z, x1.w);
;                     *(u32x4*)(outb + ro + bj * HALF) = w; } }
	v_pk_fma_f32 v[76:77], v[76:77], v[128:129], v[232:233]
	v_pk_fma_f32 v[78:79], v[78:79], v[130:131], v[234:235]
	v_pk_fma_f32 v[72:73], v[72:73], v[132:133], v[236:237]
	v_pk_fma_f32 v[74:75], v[74:75], v[134:135], v[238:239]
	v_add_u32_e32 v169, 0xb0000, v160
	global_load_dwordx4 v[232:235], v169, s[36:37]
	global_load_dwordx4 v[236:239], v169, s[36:37] offset:16
	v_cvt_pk_bf16_f32 v76, v76, v77
	v_cvt_pk_bf16_f32 v77, v78, v79
	v_cvt_pk_bf16_f32 v78, v72, v73
	v_cvt_pk_bf16_f32 v79, v74, v75
	v_add_u32_e32 v170, 0x18000, v161
	global_store_dwordx4 v170, v[76:79], s[8:9]
	s_waitcnt vmcnt(21)
	v_pk_fma_f32 v[68:69], v[68:69], v[136:137], v[240:241]
	v_pk_fma_f32 v[70:71], v[70:71], v[138:139], v[242:243]
	v_pk_fma_f32 v[64:65], v[64:65], v[140:141], v[244:245]
	v_pk_fma_f32 v[66:67], v[66:67], v[142:143], v[246:247]
	v_add_u32_e32 v169, 0xb0000, v160
	global_load_dwordx4 v[240:243], v169, s[36:37] offset:512
	global_load_dwordx4 v[244:247], v169, s[36:37] offset:528
	v_cvt_pk_bf16_f32 v68, v68, v69
	v_cvt_pk_bf16_f32 v69, v70, v71
	v_cvt_pk_bf16_f32 v70, v64, v65
	v_cvt_pk_bf16_f32 v71, v66, v67
	v_add_u32_e32 v170, 0x18000, v161
	global_store_dwordx4 v170, v[68:71], s[8:9] offset:256
	s_waitcnt vmcnt(22)
	v_pk_fma_f32 v[60:61], v[60:61], v[128:129], v[184:185]
	v_pk_fma_f32 v[62:63], v[62:63], v[130:131], v[186:187]
	v_pk_fma_f32 v[56:57], v[56:57], v[132:133], v[188:189]
	v_pk_fma_f32 v[58:59], v[58:59], v[134:135], v[190:191]
	v_cvt_pk_bf16_f32 v60, v60, v61
	v_cvt_pk_bf16_f32 v61, v62, v63
	v_cvt_pk_bf16_f32 v62, v56, v57
	v_cvt_pk_bf16_f32 v63, v58, v59
	v_add_u32_e32 v170, 0x40000, v161
	global_store_dwordx4 v170, v[60:63], s[8:9]
	s_waitcnt vmcnt(20)
	v_pk_fma_f32 v[52:53], v[52:53], v[136:137], v[192:193]
	v_pk_fma_f32 v[54:55], v[54:55], v[138:139], v[194:195]
	v_pk_fma_f32 v[48:49], v[48:49], v[140:141], v[196:197]
	v_pk_fma_f32 v[50:51], v[50:51], v[142:143], v[198:199]
	v_cvt_pk_bf16_f32 v52, v52, v53
	v_cvt_pk_bf16_f32 v53, v54, v55
	v_cvt_pk_bf16_f32 v54, v48, v49
	v_cvt_pk_bf16_f32 v55, v50, v51
	v_add_u32_e32 v170, 0x40000, v161
	global_store_dwordx4 v170, v[52:55], s[8:9] offset:256
	s_waitcnt vmcnt(18)
	v_pk_fma_f32 v[44:45], v[44:45], v[128:129], v[200:201]
	v_pk_fma_f32 v[46:47], v[46:47], v[130:131], v[202:203]
	v_pk_fma_f32 v[40:41], v[40:41], v[132:133], v[204:205]
	v_pk_fma_f32 v[42:43], v[42:43], v[134:135], v[206:207]
	v_cvt_pk_bf16_f32 v44, v44, v45
	v_cvt_pk_bf16_f32 v45, v46, v47
	v_cvt_pk_bf16_f32 v46, v40, v41
	v_cvt_pk_bf16_f32 v47, v42, v43
	v_add_u32_e32 v170, 0x48000, v161
	global_store_dwordx4 v170, v[44:47], s[8:9]
	s_waitcnt vmcnt(16)
	v_pk_fma_f32 v[36:37], v[36:37], v[136:137], v[208:209]
	v_pk_fma_f32 v[38:39], v[38:39], v[138:139], v[210:211]
	v_pk_fma_f32 v[32:33], v[32:33], v[140:141], v[212:213]
	v_pk_fma_f32 v[34:35], v[34:35], v[142:143], v[214:215]
	v_cvt_pk_bf16_f32 v36, v36, v37
	v_cvt_pk_bf16_f32 v37, v38, v39
	v_cvt_pk_bf16_f32 v38, v32, v33
	v_cvt_pk_bf16_f32 v39, v34, v35
	v_add_u32_e32 v170, 0x48000, v161
	global_store_dwordx4 v170, v[36:39], s[8:9] offset:256
	s_waitcnt vmcnt(14)
	v_pk_fma_f32 v[28:29], v[28:29], v[128:129], v[216:217]
	v_pk_fma_f32 v[30:31], v[30:31], v[130:131], v[218:219]
	v_pk_fma_f32 v[24:25], v[24:25], v[132:133], v[220:221]
	v_pk_fma_f32 v[26:27], v[26:27], v[134:135], v[222:223]
	v_cvt_pk_bf16_f32 v28, v28, v29
	v_cvt_pk_bf16_f32 v29, v30, v31
	v_cvt_pk_bf16_f32 v30, v24, v25
	v_cvt_pk_bf16_f32 v31, v26, v27
	v_add_u32_e32 v170, 0x50000, v161
	global_store_dwordx4 v170, v[28:31], s[8:9]
	s_waitcnt vmcnt(12)
	v_pk_fma_f32 v[20:21], v[20:21], v[136:137], v[224:225]
	v_pk_fma_f32 v[22:23], v[22:23], v[138:139], v[226:227]
	v_pk_fma_f32 v[16:17], v[16:17], v[140:141], v[228:229]
	v_pk_fma_f32 v[18:19], v[18:19], v[142:143], v[230:231]
	v_cvt_pk_bf16_f32 v20, v20, v21
	v_cvt_pk_bf16_f32 v21, v22, v23
	v_cvt_pk_bf16_f32 v22, v16, v17
	v_cvt_pk_bf16_f32 v23, v18, v19
	v_add_u32_e32 v170, 0x50000, v161
	global_store_dwordx4 v170, v[20:23], s[8:9] offset:256
	s_waitcnt vmcnt(10)
	v_pk_fma_f32 v[12:13], v[12:13], v[128:129], v[232:233]
	v_pk_fma_f32 v[14:15], v[14:15], v[130:131], v[234:235]
	v_pk_fma_f32 v[8:9], v[8:9], v[132:133], v[236:237]
	v_pk_fma_f32 v[10:11], v[10:11], v[134:135], v[238:239]
	v_cvt_pk_bf16_f32 v12, v12, v13
	v_cvt_pk_bf16_f32 v13, v14, v15
	v_cvt_pk_bf16_f32 v14, v8, v9
	v_cvt_pk_bf16_f32 v15, v10, v11
	v_add_u32_e32 v170, 0x58000, v161
	global_store_dwordx4 v170, v[12:15], s[8:9]
	s_waitcnt vmcnt(8)
	v_pk_fma_f32 v[4:5], v[4:5], v[136:137], v[240:241]
	v_pk_fma_f32 v[6:7], v[6:7], v[138:139], v[242:243]
	v_pk_fma_f32 v[0:1], v[0:1], v[140:141], v[244:245]
	v_pk_fma_f32 v[2:3], v[2:3], v[142:143], v[246:247]
	v_cvt_pk_bf16_f32 v4, v4, v5
	v_cvt_pk_bf16_f32 v5, v6, v7
	v_cvt_pk_bf16_f32 v6, v0, v1
	v_cvt_pk_bf16_f32 v7, v2, v3
	v_add_u32_e32 v170, 0x58000, v161
	global_store_dwordx4 v170, v[4:7], s[8:9] offset:256
	s_and_b64 vcc, exec, s[4:5]
	s_cbranch_vccz .LBB0_717
	s_waitcnt vmcnt(0)
	s_cmpk_gt_u32 s52, 0xff
	s_cbranch_scc1 .LBB0_728
	s_barrier

; #define PG8_STAGE(bufoff, gbase, voff) do { _Pragma("unroll") for (int _i = 0; _i < 2; ++_i) \
;         __builtin_amdgcn_global_load_lds((const unsigned*)((const char*)(gbase) + (voff)[_i]), (LAS unsigned*)(lds + (bufoff) + ldsw + _i * 8192), 16, 0, 0); } while (0)
; #define PG8_LDA(dst, b, h) do { _Pragma("unroll") for (int m = 0; m < 4; ++m) _Pragma("unroll") for (int k = 0; k < 2; ++k) dst[m][k] = *(const LAS bf16x8*)(lds + PG8_SA(b, h) + aoff + m * 2048 + k * 1024); } while (0)
; #define PG8_LDB(dst, b, h) do { _Pragma("unroll") for (int n = 0; n < 2; ++n) _Pragma("unroll") for (int k = 0; k < 2; ++k) dst[n][k] = *(const LAS bf16x8*)(lds + PG8_SB(b, h) + boff + n * 2048 + k * 1024); } while (0)
; #define PG8_MMA(ai, bj, At, Bt) do { __builtin_amdgcn_s_setprio(1); _Pragma("unroll") for (int m = 0; m < 4; ++m) _Pragma("unroll") for (int n = 0; n < 2; ++n) _Pragma("unroll") for (int k = 0; k < 2; ++k) \
;         acc[ai][bj][m][n] = __builtin_amdgcn_mfma_f32_16x16x32_bf16(Bt[n][k], At[m][k], acc[ai][bj][m][n], 0, 0, 0); __builtin_amdgcn_s_setprio(0); } while (0)
; template <class Epi>
; DI void gemm_phase(LAS unsigned char* lds, const Gemm g, const StaticOrder& S, const Epi& E) {
;     ...
;         const bool has_next = S.next(ui + 1, nxt);
;         const char* nA = has_next ? (const char*)g.A + (size_t)nxt.pm * tstep : cA; const char* nB = has_next ? (const char*)g.Bt + (size_t)nxt.pn * tstep : cB;
;         for (int t = 0; t < nt; t += 2) {
;             const bool last = (t == nt - 2);
;             const char* a1 = cA + (size_t)(t + 1) * kstep;
;             const char* a2 = last ? nA : cA + (size_t)(t + 2) * kstep; const char* b2 = last ? nB : cB + (size_t)(t + 2) * kstep;
;             const char* a3 = a2 + kstep; const char* b3 = b2 + kstep;
;             PG8_LDB(B0, 0, 0); PG8_SCHED; PG8_LDA(At, 0, 0); PG8_STAGE(PG8_SA(1, 1), a1 + hstep, voffA);
;             PG8_WAIT_L(8); PG8_BAR; PG8_WAIT_L(0); PG8_MMA(0, 0, At, B0); PG8_BAR; PG8_SCHED;
;             PG8_LDB(B1, 0, 1); PG8_STAGE(PG8_SB(0, 0), b2, voffB);
;             PG8_BAR; PG8_WAIT_L(0); PG8_MMA(0, 1, At, B1); PG8_BAR;
;             PG8_LDA(At, 0, 1); PG8_STAGE(PG8_SA(0, 0), a2, voffA);
;             PG8_BAR; PG8_WAIT_L(0); PG8_MMA(1, 0, At, B0); PG8_BAR; PG8_SCHED;
;             PG8_STAGE(PG8_SB(0, 1), b2 + hstep, voffB);
;             PG8_WAIT_V(6); PG8_BAR; PG8_MMA(1, 1, At, B1); PG8_BAR;
.LBB0_848:
	s_ashr_i32 s17, s16, 31
	v_cmp_lt_i64_e32 vcc, s[18:19], v[140:141]
	s_lshl_b64 s[18:19], s[16:17], 19
	s_add_u32 s18, s41, s18
	s_addc_u32 s19, s42, s19
	s_and_b64 s[20:21], vcc, exec
	s_cselect_b32 s17, s19, s25
	s_cselect_b32 s59, s18, s24
	s_ashr_i32 s15, s14, 31
	s_lshl_b64 s[20:21], s[14:15], 19
	s_add_u32 s20, s43, s20
	s_addc_u32 s21, s44, s21
	s_and_b64 s[38:39], vcc, exec
	s_cselect_b32 s15, s21, s37
	s_cselect_b32 s60, s20, s36
	s_add_u32 s24, s24, 0x40080
	s_addc_u32 s25, s25, 0
	s_add_u32 s61, s36, 0x100
	s_addc_u32 s62, s37, 0
	s_mov_b32 s63, -2
	v_add_u32_e32 v253, 0x18000, v147
	v_add_u32_e32 v252, 0x1c000, v147
	ds_read_b128 v[152:155], v149
	ds_read_b128 v[156:159], v149 offset:1024
	ds_read_b128 v[160:163], v149 offset:2048
	ds_read_b128 v[164:167], v149 offset:3072
	s_add_u32 s36, s24, 0xfffc0080
	s_addc_u32 s37, s25, -1
	s_cmp_eq_u32 s63, 12
	s_cselect_b32 s39, s17, s37
	s_cselect_b32 s38, s59, s36
	s_cselect_b32 s37, s15, s62
	s_cselect_b32 s36, s60, s61
	s_add_i32 m0, s23, 0xc000
	ds_read_b128 v[168:171], v150
	ds_read_b128 v[172:175], v150 offset:1024
	ds_read_b128 v[176:179], v150 offset:2048
	ds_read_b128 v[182:185], v150 offset:3072
	ds_read_b128 v[186:189], v150 offset:4096
	ds_read_b128 v[190:193], v150 offset:5120
	ds_read_b128 v[194:197], v150 offset:6144
	global_load_lds_dwordx4 v136, s[24:25]
	s_add_i32 m0, s23, 0xe000
	ds_read_b128 v[198:201], v150 offset:7168
	global_load_lds_dwordx4 v138, s[24:25]
	s_waitcnt lgkmcnt(8)
	s_barrier
	s_waitcnt lgkmcnt(7)
	v_mfma_f32_16x16x32_bf16 v[124:127], v[152:155], v[168:171], 0
	v_mfma_f32_16x16x32_bf16 v[120:123], v[160:163], v[168:171], 0
	s_waitcnt lgkmcnt(5)
	v_mfma_f32_16x16x32_bf16 v[108:111], v[152:155], v[176:179], 0
	v_mfma_f32_16x16x32_bf16 v[104:107], v[160:163], v[176:179], 0
	s_waitcnt lgkmcnt(3)
	v_mfma_f32_16x16x32_bf16 v[92:95], v[152:155], v[186:189], 0
	v_mfma_f32_16x16x32_bf16 v[88:91], v[160:163], v[186:189], 0
	s_waitcnt lgkmcnt(1)
	v_mfma_f32_16x16x32_bf16 v[76:79], v[152:155], v[194:197], 0
	v_mfma_f32_16x16x32_bf16 v[72:75], v[160:163], v[194:197], 0
	v_mfma_f32_16x16x32_bf16 v[124:127], v[156:159], v[172:175], v[124:127]
	v_mfma_f32_16x16x32_bf16 v[120:123], v[164:167], v[172:175], v[120:123]
	v_mfma_f32_16x16x32_bf16 v[108:111], v[156:159], v[182:185], v[108:111]
	v_mfma_f32_16x16x32_bf16 v[104:107], v[164:167], v[182:185], v[104:107]
	v_mfma_f32_16x16x32_bf16 v[92:95], v[156:159], v[190:193], v[92:95]
	v_mfma_f32_16x16x32_bf16 v[88:91], v[164:167], v[190:193], v[88:91]
	s_add_i32 s64, s55, s45
	s_add_u32 s86, s36, s12
	s_waitcnt lgkmcnt(0)
	v_mfma_f32_16x16x32_bf16 v[76:79], v[156:159], v[198:201], v[76:79]
	s_addc_u32 s87, s37, s13
	s_mov_b32 m0, s64
	v_mfma_f32_16x16x32_bf16 v[72:75], v[164:167], v[198:201], v[72:75]
	s_barrier
	ds_read_b128 v[202:205], v151
	ds_read_b128 v[206:209], v151 offset:1024
	ds_read_b128 v[210:213], v151 offset:2048
	global_load_lds_dwordx4 v132, s[36:37]
	s_add_i32 m0, s64, 0x2000
	ds_read_b128 v[214:217], v151 offset:3072
	global_load_lds_dwordx4 v128, s[36:37]
	s_barrier
	s_waitcnt lgkmcnt(3)
	v_mfma_f32_16x16x32_bf16 v[116:119], v[202:205], v[168:171], 0
	s_waitcnt lgkmcnt(1)
	v_mfma_f32_16x16x32_bf16 v[112:115], v[210:213], v[168:171], 0
	v_mfma_f32_16x16x32_bf16 v[100:103], v[202:205], v[176:179], 0
	v_mfma_f32_16x16x32_bf16 v[96:99], v[210:213], v[176:179], 0
	v_mfma_f32_16x16x32_bf16 v[84:87], v[202:205], v[186:189], 0
	v_mfma_f32_16x16x32_bf16 v[80:83], v[210:213], v[186:189], 0
	v_mfma_f32_16x16x32_bf16 v[68:71], v[202:205], v[194:197], 0
	v_mfma_f32_16x16x32_bf16 v[64:67], v[210:213], v[194:197], 0
	v_mfma_f32_16x16x32_bf16 v[116:119], v[206:209], v[172:175], v[116:119]
	s_waitcnt lgkmcnt(0)
	v_mfma_f32_16x16x32_bf16 v[112:115], v[214:217], v[172:175], v[112:115]
	v_mfma_f32_16x16x32_bf16 v[100:103], v[206:209], v[182:185], v[100:103]
	v_mfma_f32_16x16x32_bf16 v[96:99], v[214:217], v[182:185], v[96:99]
	v_mfma_f32_16x16x32_bf16 v[84:87], v[206:209], v[190:193], v[84:87]
	v_mfma_f32_16x16x32_bf16 v[80:83], v[214:217], v[190:193], v[80:83]
	s_mov_b32 m0, s23
	s_add_u32 s88, s38, s12
	v_mfma_f32_16x16x32_bf16 v[68:71], v[206:209], v[198:201], v[68:71]
	s_addc_u32 s89, s39, s13
	v_mfma_f32_16x16x32_bf16 v[64:67], v[214:217], v[198:201], v[64:67]
	s_barrier
	ds_read_b128 v[168:171], v150 offset:16384
	ds_read_b128 v[172:175], v150 offset:17408
	ds_read_b128 v[176:179], v150 offset:18432
	ds_read_b128 v[182:185], v150 offset:19456
	ds_read_b128 v[186:189], v150 offset:20480
	ds_read_b128 v[190:193], v150 offset:21504
	ds_read_b128 v[194:197], v150 offset:22528
	global_load_lds_dwordx4 v134, s[38:39]
	s_mov_b32 m0, s48
	ds_read_b128 v[198:201], v150 offset:23552
	global_load_lds_dwordx4 v130, s[38:39]
	s_barrier
	s_waitcnt lgkmcnt(7)
	v_mfma_f32_16x16x32_bf16 v[60:63], v[152:155], v[168:171], 0
	v_mfma_f32_16x16x32_bf16 v[56:59], v[160:163], v[168:171], 0
	s_waitcnt lgkmcnt(5)
	v_mfma_f32_16x16x32_bf16 v[44:47], v[152:155], v[176:179], 0
	v_mfma_f32_16x16x32_bf16 v[40:43], v[160:163], v[176:179], 0
	s_waitcnt lgkmcnt(3)
	v_mfma_f32_16x16x32_bf16 v[28:31], v[152:155], v[186:189], 0
	v_mfma_f32_16x16x32_bf16 v[24:27], v[160:163], v[186:189], 0
	s_waitcnt lgkmcnt(1)
	v_mfma_f32_16x16x32_bf16 v[12:15], v[152:155], v[194:197], 0
	v_mfma_f32_16x16x32_bf16 v[8:11], v[160:163], v[194:197], 0
	v_mfma_f32_16x16x32_bf16 v[60:63], v[156:159], v[172:175], v[60:63]
	v_mfma_f32_16x16x32_bf16 v[56:59], v[164:167], v[172:175], v[56:59]
	v_mfma_f32_16x16x32_bf16 v[44:47], v[156:159], v[182:185], v[44:47]
	v_mfma_f32_16x16x32_bf16 v[40:43], v[164:167], v[182:185], v[40:43]
	v_mfma_f32_16x16x32_bf16 v[28:31], v[156:159], v[190:193], v[28:31]
	v_mfma_f32_16x16x32_bf16 v[24:27], v[164:167], v[190:193], v[24:27]
	s_add_u32 s64, s36, 0x40000
	s_addc_u32 s65, s37, 0
	s_waitcnt lgkmcnt(0)
	v_mfma_f32_16x16x32_bf16 v[12:15], v[156:159], v[198:201], v[12:15]
	s_add_i32 s66, s56, s45
	s_mov_b32 m0, s66
	v_mfma_f32_16x16x32_bf16 v[8:11], v[164:167], v[198:201], v[8:11]
	s_barrier
; #define PG8_STAGE(bufoff, gbase, voff) do { _Pragma("unroll") for (int _i = 0; _i < 2; ++_i) \
;         __builtin_amdgcn_global_load_lds((const unsigned*)((const char*)(gbase) + (voff)[_i]), (LAS unsigned*)(lds + (bufoff) + ldsw + _i * 8192), 16, 0, 0); } while (0)
; #define PG8_LDA(dst, b, h) do { _Pragma("unroll") for (int m = 0; m < 4; ++m) _Pragma("unroll") for (int k = 0; k < 2; ++k) dst[m][k] = *(const LAS bf16x8*)(lds + PG8_SA(b, h) + aoff + m * 2048 + k * 1024); } while (0)
; #define PG8_LDB(dst, b, h) do { _Pragma("unroll") for (int n = 0; n < 2; ++n) _Pragma("unroll") for (int k = 0; k < 2; ++k) dst[n][k] = *(const LAS bf16x8*)(lds + PG8_SB(b, h) + boff + n * 2048 + k * 1024); } while (0)
; #define PG8_MMA(ai, bj, At, Bt) do { __builtin_amdgcn_s_setprio(1); _Pragma("unroll") for (int m = 0; m < 4; ++m) _Pragma("unroll") for (int n = 0; n < 2; ++n) _Pragma("unroll") for (int k = 0; k < 2; ++k) \
;         acc[ai][bj][m][n] = __builtin_amdgcn_mfma_f32_16x16x32_bf16(Bt[n][k], At[m][k], acc[ai][bj][m][n], 0, 0, 0); __builtin_amdgcn_s_setprio(0); } while (0)
; #define PG8_WAIT_V(n) asm volatile("s_waitcnt vmcnt(" #n ")" ::: "memory")
; #define PG8_WAIT_L(n) asm volatile("s_waitcnt lgkmcnt(" #n ")" ::: "memory")
; #define PG8_BAR __builtin_amdgcn_s_barrier()
; #define PG8_SCHED __builtin_amdgcn_sched_barrier(0)
; template <class Epi>
; DI void gemm_phase(LAS unsigned char* lds, const Gemm g, const StaticOrder& S, const Epi& E) {
;     ...
;             PG8_WAIT_V(6); PG8_BAR; PG8_MMA(1, 1, At, B1); PG8_BAR;
;             PG8_LDB(B0, 1, 0); PG8_SCHED; PG8_LDA(At, 1, 0); PG8_STAGE(PG8_SA(0, 1), a2 + hstep, voffA);
;             PG8_WAIT_L(8); PG8_BAR; PG8_WAIT_L(0); PG8_MMA(0, 0, At, B0); PG8_BAR; PG8_SCHED;
;             PG8_LDB(B1, 1, 1); PG8_STAGE(PG8_SB(1, 0), b3, voffB);
;             PG8_BAR; PG8_WAIT_L(0); PG8_MMA(0, 1, At, B1); PG8_BAR;
;             PG8_LDA(At, 1, 1); PG8_STAGE(PG8_SA(1, 0), a3, voffA);
;             PG8_BAR; PG8_WAIT_L(0); PG8_MMA(1, 0, At, B0); PG8_BAR; PG8_SCHED;
;             PG8_STAGE(PG8_SB(1, 1), b3 + hstep, voffB);
;             PG8_WAIT_V(6); PG8_BAR; PG8_MMA(1, 1, At, B1); PG8_BAR;
	global_load_lds_dwordx4 v132, s[64:65]
	s_add_i32 m0, s66, 0x2000
	s_waitcnt vmcnt(5)
	global_load_lds_dwordx4 v128, s[64:65]
	s_barrier
	v_mfma_f32_16x16x32_bf16 v[52:55], v[202:205], v[168:171], 0
	v_mfma_f32_16x16x32_bf16 v[48:51], v[210:213], v[168:171], 0
	v_mfma_f32_16x16x32_bf16 v[36:39], v[202:205], v[176:179], 0
	v_mfma_f32_16x16x32_bf16 v[32:35], v[210:213], v[176:179], 0
	v_mfma_f32_16x16x32_bf16 v[20:23], v[202:205], v[186:189], 0
	v_mfma_f32_16x16x32_bf16 v[16:19], v[210:213], v[186:189], 0
	v_mfma_f32_16x16x32_bf16 v[4:7], v[202:205], v[194:197], 0
	v_mfma_f32_16x16x32_bf16 v[0:3], v[210:213], v[194:197], 0
	v_mfma_f32_16x16x32_bf16 v[52:55], v[206:209], v[172:175], v[52:55]
	v_mfma_f32_16x16x32_bf16 v[48:51], v[214:217], v[172:175], v[48:51]
	v_mfma_f32_16x16x32_bf16 v[36:39], v[206:209], v[182:185], v[36:39]
	v_mfma_f32_16x16x32_bf16 v[32:35], v[214:217], v[182:185], v[32:35]
	v_mfma_f32_16x16x32_bf16 v[20:23], v[206:209], v[190:193], v[20:23]
	v_mfma_f32_16x16x32_bf16 v[16:19], v[214:217], v[190:193], v[16:19]
	v_mfma_f32_16x16x32_bf16 v[4:7], v[206:209], v[198:201], v[4:7]
	s_add_i32 s64, 0, 0x18000
	v_mfma_f32_16x16x32_bf16 v[0:3], v[214:217], v[198:201], v[0:3]
	s_barrier
	ds_read_b128 v[152:155], v253
	ds_read_b128 v[156:159], v253 offset:1024
	ds_read_b128 v[160:163], v253 offset:2048
	ds_read_b128 v[164:167], v253 offset:3072
	s_add_u32 s38, s38, 0x40000
	s_addc_u32 s39, s39, 0
	s_mov_b32 m0, s49
	ds_read_b128 v[168:171], v150 offset:32768
	ds_read_b128 v[172:175], v150 offset:33792
	ds_read_b128 v[176:179], v150 offset:34816
	ds_read_b128 v[182:185], v150 offset:35840
	ds_read_b128 v[186:189], v150 offset:36864
	ds_read_b128 v[190:193], v150 offset:37888
	ds_read_b128 v[194:197], v150 offset:38912
	global_load_lds_dwordx4 v134, s[38:39]
	s_mov_b32 m0, s50
	ds_read_b128 v[198:201], v150 offset:39936
	global_load_lds_dwordx4 v130, s[38:39]
	s_waitcnt lgkmcnt(8)
	s_barrier
	s_waitcnt lgkmcnt(7)
	v_mfma_f32_16x16x32_bf16 v[124:127], v[152:155], v[168:171], v[124:127]
	v_mfma_f32_16x16x32_bf16 v[120:123], v[160:163], v[168:171], v[120:123]
	s_waitcnt lgkmcnt(5)
	v_mfma_f32_16x16x32_bf16 v[108:111], v[152:155], v[176:179], v[108:111]
	v_mfma_f32_16x16x32_bf16 v[104:107], v[160:163], v[176:179], v[104:107]
	s_waitcnt lgkmcnt(3)
	v_mfma_f32_16x16x32_bf16 v[92:95], v[152:155], v[186:189], v[92:95]
	v_mfma_f32_16x16x32_bf16 v[88:91], v[160:163], v[186:189], v[88:91]
	s_waitcnt lgkmcnt(1)
	v_mfma_f32_16x16x32_bf16 v[76:79], v[152:155], v[194:197], v[76:79]
	v_mfma_f32_16x16x32_bf16 v[72:75], v[160:163], v[194:197], v[72:75]
	v_mfma_f32_16x16x32_bf16 v[124:127], v[156:159], v[172:175], v[124:127]
	v_mfma_f32_16x16x32_bf16 v[120:123], v[164:167], v[172:175], v[120:123]
	v_mfma_f32_16x16x32_bf16 v[108:111], v[156:159], v[182:185], v[108:111]
	v_mfma_f32_16x16x32_bf16 v[104:107], v[164:167], v[182:185], v[104:107]
	v_mfma_f32_16x16x32_bf16 v[92:95], v[156:159], v[190:193], v[92:95]
	v_mfma_f32_16x16x32_bf16 v[88:91], v[164:167], v[190:193], v[88:91]
	s_add_i32 s38, 0, 0x1c000
	s_add_i32 s39, s64, s45
	s_waitcnt lgkmcnt(0)
	v_mfma_f32_16x16x32_bf16 v[76:79], v[156:159], v[198:201], v[76:79]
	s_mov_b32 m0, s39
	v_mfma_f32_16x16x32_bf16 v[72:75], v[164:167], v[198:201], v[72:75]
	s_barrier
	ds_read_b128 v[202:205], v252
	ds_read_b128 v[206:209], v252 offset:1024
	ds_read_b128 v[210:213], v252 offset:2048
	global_load_lds_dwordx4 v132, s[86:87]
	s_add_i32 m0, s39, 0x2000
	ds_read_b128 v[214:217], v252 offset:3072
	global_load_lds_dwordx4 v128, s[86:87]
	s_barrier
	s_waitcnt lgkmcnt(3)
	v_mfma_f32_16x16x32_bf16 v[116:119], v[202:205], v[168:171], v[116:119]
	s_waitcnt lgkmcnt(1)
	v_mfma_f32_16x16x32_bf16 v[112:115], v[210:213], v[168:171], v[112:115]
	v_mfma_f32_16x16x32_bf16 v[100:103], v[202:205], v[176:179], v[100:103]
	v_mfma_f32_16x16x32_bf16 v[96:99], v[210:213], v[176:179], v[96:99]
	v_mfma_f32_16x16x32_bf16 v[84:87], v[202:205], v[186:189], v[84:87]
	v_mfma_f32_16x16x32_bf16 v[80:83], v[210:213], v[186:189], v[80:83]
	v_mfma_f32_16x16x32_bf16 v[68:71], v[202:205], v[194:197], v[68:71]
	v_mfma_f32_16x16x32_bf16 v[64:67], v[210:213], v[194:197], v[64:67]
	v_mfma_f32_16x16x32_bf16 v[116:119], v[206:209], v[172:175], v[116:119]
	s_waitcnt lgkmcnt(0)
	v_mfma_f32_16x16x32_bf16 v[112:115], v[214:217], v[172:175], v[112:115]
	v_mfma_f32_16x16x32_bf16 v[100:103], v[206:209], v[182:185], v[100:103]
	v_mfma_f32_16x16x32_bf16 v[96:99], v[214:217], v[182:185], v[96:99]
	v_mfma_f32_16x16x32_bf16 v[84:87], v[206:209], v[190:193], v[84:87]
	v_mfma_f32_16x16x32_bf16 v[80:83], v[214:217], v[190:193], v[80:83]
	v_mfma_f32_16x16x32_bf16 v[68:71], v[206:209], v[198:201], v[68:71]
	s_mov_b32 m0, s52
	v_mfma_f32_16x16x32_bf16 v[64:67], v[214:217], v[198:201], v[64:67]
	s_barrier
	ds_read_b128 v[168:171], v150 offset:49152
	ds_read_b128 v[172:175], v150 offset:50176
	ds_read_b128 v[176:179], v150 offset:51200
	ds_read_b128 v[182:185], v150 offset:52224
	ds_read_b128 v[186:189], v150 offset:53248
	ds_read_b128 v[190:193], v150 offset:54272
	ds_read_b128 v[194:197], v150 offset:55296
	global_load_lds_dwordx4 v134, s[88:89]
	s_mov_b32 m0, s53
	ds_read_b128 v[198:201], v150 offset:56320
	global_load_lds_dwordx4 v130, s[88:89]
	s_barrier
; #define PG8_STAGE(bufoff, gbase, voff) do { _Pragma("unroll") for (int _i = 0; _i < 2; ++_i) \
;         __builtin_amdgcn_global_load_lds((const unsigned*)((const char*)(gbase) + (voff)[_i]), (LAS unsigned*)(lds + (bufoff) + ldsw + _i * 8192), 16, 0, 0); } while (0)
; #define PG8_LDA(dst, b, h) do { _Pragma("unroll") for (int m = 0; m < 4; ++m) _Pragma("unroll") for (int k = 0; k < 2; ++k) dst[m][k] = *(const LAS bf16x8*)(lds + PG8_SA(b, h) + aoff + m * 2048 + k * 1024); } while (0)
; #define PG8_LDB(dst, b, h) do { _Pragma("unroll") for (int n = 0; n < 2; ++n) _Pragma("unroll") for (int k = 0; k < 2; ++k) dst[n][k] = *(const LAS bf16x8*)(lds + PG8_SB(b, h) + boff + n * 2048 + k * 1024); } while (0)
; #define PG8_MMA(ai, bj, At, Bt) do { __builtin_amdgcn_s_setprio(1); _Pragma("unroll") for (int m = 0; m < 4; ++m) _Pragma("unroll") for (int n = 0; n < 2; ++n) _Pragma("unroll") for (int k = 0; k < 2; ++k) \
;         acc[ai][bj][m][n] = __builtin_amdgcn_mfma_f32_16x16x32_bf16(Bt[n][k], At[m][k], acc[ai][bj][m][n], 0, 0, 0); __builtin_amdgcn_s_setprio(0); } while (0)
; #define PG8_WAIT_V(n) asm volatile("s_waitcnt vmcnt(" #n ")" ::: "memory")
; template <class Epi>
; DI void gemm_phase(LAS unsigned char* lds, const Gemm g, const StaticOrder& S, const Epi& E) {
;     ...
;             PG8_LDB(B0, 0, 0); PG8_SCHED; PG8_LDA(At, 0, 0); PG8_STAGE(PG8_SA(1, 1), a1 + hstep, voffA);
;             PG8_WAIT_L(8); PG8_BAR; PG8_WAIT_L(0); PG8_MMA(0, 0, At, B0); PG8_BAR; PG8_SCHED;
;             PG8_LDB(B1, 0, 1); PG8_STAGE(PG8_SB(0, 0), b2, voffB);
;             PG8_BAR; PG8_WAIT_L(0); PG8_MMA(0, 1, At, B1); PG8_BAR;
;             PG8_LDA(At, 0, 1); PG8_STAGE(PG8_SA(0, 0), a2, voffA);
;     ...
;             PG8_WAIT_V(6); PG8_BAR; PG8_MMA(1, 1, At, B1); PG8_BAR;
;             PG8_LDB(B0, 1, 0); PG8_SCHED; PG8_LDA(At, 1, 0); PG8_STAGE(PG8_SA(0, 1), a2 + hstep, voffA);
;             PG8_WAIT_L(8); PG8_BAR; PG8_WAIT_L(0); PG8_MMA(0, 0, At, B0); PG8_BAR; PG8_SCHED;
;             PG8_LDB(B1, 1, 1); PG8_STAGE(PG8_SB(1, 0), b3, voffB);
;             PG8_BAR; PG8_WAIT_L(0); PG8_MMA(0, 1, At, B1); PG8_BAR;
;             PG8_LDA(At, 1, 1); PG8_STAGE(PG8_SA(1, 0), a3, voffA);
;             PG8_BAR; PG8_WAIT_L(0); PG8_MMA(1, 0, At, B0); PG8_BAR; PG8_SCHED;
;             PG8_STAGE(PG8_SB(1, 1), b3 + hstep, voffB);
;             PG8_WAIT_V(6); PG8_BAR; PG8_MMA(1, 1, At, B1); PG8_BAR;
	s_waitcnt lgkmcnt(7)
	v_mfma_f32_16x16x32_bf16 v[60:63], v[152:155], v[168:171], v[60:63]
	v_mfma_f32_16x16x32_bf16 v[56:59], v[160:163], v[168:171], v[56:59]
	s_waitcnt lgkmcnt(5)
	v_mfma_f32_16x16x32_bf16 v[44:47], v[152:155], v[176:179], v[44:47]
	v_mfma_f32_16x16x32_bf16 v[40:43], v[160:163], v[176:179], v[40:43]
	s_waitcnt lgkmcnt(3)
	v_mfma_f32_16x16x32_bf16 v[28:31], v[152:155], v[186:189], v[28:31]
	v_mfma_f32_16x16x32_bf16 v[24:27], v[160:163], v[186:189], v[24:27]
	s_waitcnt lgkmcnt(1)
	v_mfma_f32_16x16x32_bf16 v[12:15], v[152:155], v[194:197], v[12:15]
	v_mfma_f32_16x16x32_bf16 v[8:11], v[160:163], v[194:197], v[8:11]
	v_mfma_f32_16x16x32_bf16 v[60:63], v[156:159], v[172:175], v[60:63]
	v_mfma_f32_16x16x32_bf16 v[56:59], v[164:167], v[172:175], v[56:59]
	v_mfma_f32_16x16x32_bf16 v[44:47], v[156:159], v[182:185], v[44:47]
	v_mfma_f32_16x16x32_bf16 v[40:43], v[164:167], v[182:185], v[40:43]
	v_mfma_f32_16x16x32_bf16 v[28:31], v[156:159], v[190:193], v[28:31]
	v_mfma_f32_16x16x32_bf16 v[24:27], v[164:167], v[190:193], v[24:27]
	s_add_u32 s36, s36, 0x40080
	s_addc_u32 s37, s37, 0
	s_waitcnt lgkmcnt(0)
	v_mfma_f32_16x16x32_bf16 v[12:15], v[156:159], v[198:201], v[12:15]
	s_add_i32 s38, s38, s45
	s_mov_b32 m0, s38
	v_mfma_f32_16x16x32_bf16 v[8:11], v[164:167], v[198:201], v[8:11]
	s_barrier
	global_load_lds_dwordx4 v132, s[36:37]
	s_add_i32 m0, s38, 0x2000
	s_waitcnt vmcnt(5)
	global_load_lds_dwordx4 v128, s[36:37]
	s_barrier
	v_mfma_f32_16x16x32_bf16 v[52:55], v[202:205], v[168:171], v[52:55]
	v_mfma_f32_16x16x32_bf16 v[48:51], v[210:213], v[168:171], v[48:51]
	v_mfma_f32_16x16x32_bf16 v[36:39], v[202:205], v[176:179], v[36:39]
	v_mfma_f32_16x16x32_bf16 v[32:35], v[210:213], v[176:179], v[32:35]
	v_mfma_f32_16x16x32_bf16 v[20:23], v[202:205], v[186:189], v[20:23]
	v_mfma_f32_16x16x32_bf16 v[16:19], v[210:213], v[186:189], v[16:19]
	v_mfma_f32_16x16x32_bf16 v[4:7], v[202:205], v[194:197], v[4:7]
	v_mfma_f32_16x16x32_bf16 v[0:3], v[210:213], v[194:197], v[0:3]
	v_mfma_f32_16x16x32_bf16 v[52:55], v[206:209], v[172:175], v[52:55]
	s_add_i32 s63, s63, 2
	s_add_u32 s24, s24, 0x100
	v_mfma_f32_16x16x32_bf16 v[48:51], v[214:217], v[172:175], v[48:51]
	s_addc_u32 s25, s25, 0
	s_add_u32 s61, s61, 0x100
	v_mfma_f32_16x16x32_bf16 v[36:39], v[206:209], v[182:185], v[36:39]
	s_addc_u32 s62, s62, 0
	s_add_u32 s36, s24, 0xfffc0080
	v_mfma_f32_16x16x32_bf16 v[32:35], v[214:217], v[182:185], v[32:35]
	s_addc_u32 s37, s25, -1
	s_cmp_eq_u32 s63, 12
	v_mfma_f32_16x16x32_bf16 v[20:23], v[206:209], v[190:193], v[20:23]
	s_cselect_b32 s39, s17, s37
	s_cselect_b32 s38, s59, s36
	v_mfma_f32_16x16x32_bf16 v[16:19], v[214:217], v[190:193], v[16:19]
	s_cselect_b32 s37, s15, s62
	s_cselect_b32 s36, s60, s61
	v_mfma_f32_16x16x32_bf16 v[4:7], v[206:209], v[198:201], v[4:7]
	s_add_i32 m0, s23, 0xc000
	v_mfma_f32_16x16x32_bf16 v[0:3], v[214:217], v[198:201], v[0:3]
	s_cmp_gt_u32 s63, 13
	s_barrier
.LBB0_849:
	ds_read_b128 v[152:155], v149
	ds_read_b128 v[156:159], v149 offset:1024
	ds_read_b128 v[160:163], v149 offset:2048
	ds_read_b128 v[164:167], v149 offset:3072
	ds_read_b128 v[168:171], v150
	ds_read_b128 v[172:175], v150 offset:1024
	ds_read_b128 v[176:179], v150 offset:2048
	ds_read_b128 v[182:185], v150 offset:3072
	ds_read_b128 v[186:189], v150 offset:4096
	ds_read_b128 v[190:193], v150 offset:5120
	ds_read_b128 v[194:197], v150 offset:6144
	global_load_lds_dwordx4 v136, s[24:25]
	s_add_i32 m0, s23, 0xe000
	ds_read_b128 v[198:201], v150 offset:7168
	global_load_lds_dwordx4 v138, s[24:25]
	s_waitcnt lgkmcnt(8)
	s_barrier
	s_waitcnt lgkmcnt(7)
	v_mfma_f32_16x16x32_bf16 v[124:127], v[152:155], v[168:171], v[124:127]
	v_mfma_f32_16x16x32_bf16 v[120:123], v[160:163], v[168:171], v[120:123]
	s_waitcnt lgkmcnt(5)
	v_mfma_f32_16x16x32_bf16 v[108:111], v[152:155], v[176:179], v[108:111]
	v_mfma_f32_16x16x32_bf16 v[104:107], v[160:163], v[176:179], v[104:107]
	s_waitcnt lgkmcnt(3)
	v_mfma_f32_16x16x32_bf16 v[92:95], v[152:155], v[186:189], v[92:95]
	v_mfma_f32_16x16x32_bf16 v[88:91], v[160:163], v[186:189], v[88:91]
	s_waitcnt lgkmcnt(1)
	v_mfma_f32_16x16x32_bf16 v[76:79], v[152:155], v[194:197], v[76:79]
	v_mfma_f32_16x16x32_bf16 v[72:75], v[160:163], v[194:197], v[72:75]
	v_mfma_f32_16x16x32_bf16 v[124:127], v[156:159], v[172:175], v[124:127]
	v_mfma_f32_16x16x32_bf16 v[120:123], v[164:167], v[172:175], v[120:123]
	v_mfma_f32_16x16x32_bf16 v[108:111], v[156:159], v[182:185], v[108:111]
	v_mfma_f32_16x16x32_bf16 v[104:107], v[164:167], v[182:185], v[104:107]
	v_mfma_f32_16x16x32_bf16 v[92:95], v[156:159], v[190:193], v[92:95]
	v_mfma_f32_16x16x32_bf16 v[88:91], v[164:167], v[190:193], v[88:91]
	s_add_i32 s64, s55, s45
	s_add_u32 s86, s36, s12
	s_waitcnt lgkmcnt(0)
	v_mfma_f32_16x16x32_bf16 v[76:79], v[156:159], v[198:201], v[76:79]
	s_addc_u32 s87, s37, s13
	s_mov_b32 m0, s64
	v_mfma_f32_16x16x32_bf16 v[72:75], v[164:167], v[198:201], v[72:75]
	s_barrier
	ds_read_b128 v[202:205], v151
	ds_read_b128 v[206:209], v151 offset:1024
	ds_read_b128 v[210:213], v151 offset:2048
	global_load_lds_dwordx4 v132, s[36:37]
	s_add_i32 m0, s64, 0x2000
	ds_read_b128 v[214:217], v151 offset:3072
	global_load_lds_dwordx4 v128, s[36:37]
	s_barrier
; #define PG8_STAGE(bufoff, gbase, voff) do { _Pragma("unroll") for (int _i = 0; _i < 2; ++_i) \
;         __builtin_amdgcn_global_load_lds((const unsigned*)((const char*)(gbase) + (voff)[_i]), (LAS unsigned*)(lds + (bufoff) + ldsw + _i * 8192), 16, 0, 0); } while (0)
; #define PG8_LDA(dst, b, h) do { _Pragma("unroll") for (int m = 0; m < 4; ++m) _Pragma("unroll") for (int k = 0; k < 2; ++k) dst[m][k] = *(const LAS bf16x8*)(lds + PG8_SA(b, h) + aoff + m * 2048 + k * 1024); } while (0)
; #define PG8_LDB(dst, b, h) do { _Pragma("unroll") for (int n = 0; n < 2; ++n) _Pragma("unroll") for (int k = 0; k < 2; ++k) dst[n][k] = *(const LAS bf16x8*)(lds + PG8_SB(b, h) + boff + n * 2048 + k * 1024); } while (0)
; #define PG8_MMA(ai, bj, At, Bt) do { __builtin_amdgcn_s_setprio(1); _Pragma("unroll") for (int m = 0; m < 4; ++m) _Pragma("unroll") for (int n = 0; n < 2; ++n) _Pragma("unroll") for (int k = 0; k < 2; ++k) \
;         acc[ai][bj][m][n] = __builtin_amdgcn_mfma_f32_16x16x32_bf16(Bt[n][k], At[m][k], acc[ai][bj][m][n], 0, 0, 0); __builtin_amdgcn_s_setprio(0); } while (0)
; #define PG8_WAIT_V(n) asm volatile("s_waitcnt vmcnt(" #n ")" ::: "memory")
; #define PG8_WAIT_L(n) asm volatile("s_waitcnt lgkmcnt(" #n ")" ::: "memory")
; template <class Epi>
; DI void gemm_phase(LAS unsigned char* lds, const Gemm g, const StaticOrder& S, const Epi& E) {
;     ...
;             PG8_LDB(B1, 0, 1); PG8_STAGE(PG8_SB(0, 0), b2, voffB);
;             PG8_BAR; PG8_WAIT_L(0); PG8_MMA(0, 1, At, B1); PG8_BAR;
;             PG8_LDA(At, 0, 1); PG8_STAGE(PG8_SA(0, 0), a2, voffA);
;             PG8_BAR; PG8_WAIT_L(0); PG8_MMA(1, 0, At, B0); PG8_BAR; PG8_SCHED;
;             PG8_STAGE(PG8_SB(0, 1), b2 + hstep, voffB);
;             PG8_WAIT_V(6); PG8_BAR; PG8_MMA(1, 1, At, B1); PG8_BAR;
;             PG8_LDB(B0, 1, 0); PG8_SCHED; PG8_LDA(At, 1, 0); PG8_STAGE(PG8_SA(0, 1), a2 + hstep, voffA);
;             PG8_WAIT_L(8); PG8_BAR; PG8_WAIT_L(0); PG8_MMA(0, 0, At, B0); PG8_BAR; PG8_SCHED;
;             PG8_LDB(B1, 1, 1); PG8_STAGE(PG8_SB(1, 0), b3, voffB);
;             PG8_BAR; PG8_WAIT_L(0); PG8_MMA(0, 1, At, B1); PG8_BAR;
;             PG8_LDA(At, 1, 1); PG8_STAGE(PG8_SA(1, 0), a3, voffA);
;             PG8_BAR; PG8_WAIT_L(0); PG8_MMA(1, 0, At, B0); PG8_BAR; PG8_SCHED;
;             PG8_STAGE(PG8_SB(1, 1), b3 + hstep, voffB);
;             PG8_WAIT_V(6); PG8_BAR; PG8_MMA(1, 1, At, B1); PG8_BAR;
	s_waitcnt lgkmcnt(3)
	v_mfma_f32_16x16x32_bf16 v[116:119], v[202:205], v[168:171], v[116:119]
	s_waitcnt lgkmcnt(1)
	v_mfma_f32_16x16x32_bf16 v[112:115], v[210:213], v[168:171], v[112:115]
	v_mfma_f32_16x16x32_bf16 v[100:103], v[202:205], v[176:179], v[100:103]
	v_mfma_f32_16x16x32_bf16 v[96:99], v[210:213], v[176:179], v[96:99]
	v_mfma_f32_16x16x32_bf16 v[84:87], v[202:205], v[186:189], v[84:87]
	v_mfma_f32_16x16x32_bf16 v[80:83], v[210:213], v[186:189], v[80:83]
	v_mfma_f32_16x16x32_bf16 v[68:71], v[202:205], v[194:197], v[68:71]
	v_mfma_f32_16x16x32_bf16 v[64:67], v[210:213], v[194:197], v[64:67]
	v_mfma_f32_16x16x32_bf16 v[116:119], v[206:209], v[172:175], v[116:119]
	s_waitcnt lgkmcnt(0)
	v_mfma_f32_16x16x32_bf16 v[112:115], v[214:217], v[172:175], v[112:115]
	v_mfma_f32_16x16x32_bf16 v[100:103], v[206:209], v[182:185], v[100:103]
	v_mfma_f32_16x16x32_bf16 v[96:99], v[214:217], v[182:185], v[96:99]
	v_mfma_f32_16x16x32_bf16 v[84:87], v[206:209], v[190:193], v[84:87]
	v_mfma_f32_16x16x32_bf16 v[80:83], v[214:217], v[190:193], v[80:83]
	s_mov_b32 m0, s23
	s_add_u32 s88, s38, s12
	v_mfma_f32_16x16x32_bf16 v[68:71], v[206:209], v[198:201], v[68:71]
	s_addc_u32 s89, s39, s13
	v_mfma_f32_16x16x32_bf16 v[64:67], v[214:217], v[198:201], v[64:67]
	s_barrier
	ds_read_b128 v[168:171], v150 offset:16384
	ds_read_b128 v[172:175], v150 offset:17408
	ds_read_b128 v[176:179], v150 offset:18432
	ds_read_b128 v[182:185], v150 offset:19456
	ds_read_b128 v[186:189], v150 offset:20480
	ds_read_b128 v[190:193], v150 offset:21504
	ds_read_b128 v[194:197], v150 offset:22528
	global_load_lds_dwordx4 v134, s[38:39]
	s_mov_b32 m0, s48
	ds_read_b128 v[198:201], v150 offset:23552
	global_load_lds_dwordx4 v130, s[38:39]
	s_barrier
	s_waitcnt lgkmcnt(7)
	v_mfma_f32_16x16x32_bf16 v[60:63], v[152:155], v[168:171], v[60:63]
	v_mfma_f32_16x16x32_bf16 v[56:59], v[160:163], v[168:171], v[56:59]
	s_waitcnt lgkmcnt(5)
	v_mfma_f32_16x16x32_bf16 v[44:47], v[152:155], v[176:179], v[44:47]
	v_mfma_f32_16x16x32_bf16 v[40:43], v[160:163], v[176:179], v[40:43]
	s_waitcnt lgkmcnt(3)
	v_mfma_f32_16x16x32_bf16 v[28:31], v[152:155], v[186:189], v[28:31]
	v_mfma_f32_16x16x32_bf16 v[24:27], v[160:163], v[186:189], v[24:27]
	s_waitcnt lgkmcnt(1)
	v_mfma_f32_16x16x32_bf16 v[12:15], v[152:155], v[194:197], v[12:15]
	v_mfma_f32_16x16x32_bf16 v[8:11], v[160:163], v[194:197], v[8:11]
	v_mfma_f32_16x16x32_bf16 v[60:63], v[156:159], v[172:175], v[60:63]
	v_mfma_f32_16x16x32_bf16 v[56:59], v[164:167], v[172:175], v[56:59]
	v_mfma_f32_16x16x32_bf16 v[44:47], v[156:159], v[182:185], v[44:47]
	v_mfma_f32_16x16x32_bf16 v[40:43], v[164:167], v[182:185], v[40:43]
	v_mfma_f32_16x16x32_bf16 v[28:31], v[156:159], v[190:193], v[28:31]
	v_mfma_f32_16x16x32_bf16 v[24:27], v[164:167], v[190:193], v[24:27]
	s_add_u32 s64, s36, 0x40000
	s_addc_u32 s65, s37, 0
	s_waitcnt lgkmcnt(0)
	v_mfma_f32_16x16x32_bf16 v[12:15], v[156:159], v[198:201], v[12:15]
	s_add_i32 s66, s56, s45
	s_mov_b32 m0, s66
	v_mfma_f32_16x16x32_bf16 v[8:11], v[164:167], v[198:201], v[8:11]
	s_barrier
	global_load_lds_dwordx4 v132, s[64:65]
	s_add_i32 m0, s66, 0x2000
	s_waitcnt vmcnt(5)
	global_load_lds_dwordx4 v128, s[64:65]
	s_barrier
	v_mfma_f32_16x16x32_bf16 v[52:55], v[202:205], v[168:171], v[52:55]
	v_mfma_f32_16x16x32_bf16 v[48:51], v[210:213], v[168:171], v[48:51]
	v_mfma_f32_16x16x32_bf16 v[36:39], v[202:205], v[176:179], v[36:39]
	v_mfma_f32_16x16x32_bf16 v[32:35], v[210:213], v[176:179], v[32:35]
	v_mfma_f32_16x16x32_bf16 v[20:23], v[202:205], v[186:189], v[20:23]
	v_mfma_f32_16x16x32_bf16 v[16:19], v[210:213], v[186:189], v[16:19]
	v_mfma_f32_16x16x32_bf16 v[4:7], v[202:205], v[194:197], v[4:7]
	v_mfma_f32_16x16x32_bf16 v[0:3], v[210:213], v[194:197], v[0:3]
	v_mfma_f32_16x16x32_bf16 v[52:55], v[206:209], v[172:175], v[52:55]
	v_mfma_f32_16x16x32_bf16 v[48:51], v[214:217], v[172:175], v[48:51]
	v_mfma_f32_16x16x32_bf16 v[36:39], v[206:209], v[182:185], v[36:39]
	v_mfma_f32_16x16x32_bf16 v[32:35], v[214:217], v[182:185], v[32:35]
	v_mfma_f32_16x16x32_bf16 v[20:23], v[206:209], v[190:193], v[20:23]
	v_mfma_f32_16x16x32_bf16 v[16:19], v[214:217], v[190:193], v[16:19]
	v_mfma_f32_16x16x32_bf16 v[4:7], v[206:209], v[198:201], v[4:7]
	s_add_i32 s64, 0, 0x18000
	v_mfma_f32_16x16x32_bf16 v[0:3], v[214:217], v[198:201], v[0:3]
	s_barrier
	ds_read_b128 v[152:155], v253
	ds_read_b128 v[156:159], v253 offset:1024
	ds_read_b128 v[160:163], v253 offset:2048
	ds_read_b128 v[164:167], v253 offset:3072
	s_add_u32 s38, s38, 0x40000
	s_addc_u32 s39, s39, 0
	s_mov_b32 m0, s49
	ds_read_b128 v[168:171], v150 offset:32768
	ds_read_b128 v[172:175], v150 offset:33792
	ds_read_b128 v[176:179], v150 offset:34816
	ds_read_b128 v[182:185], v150 offset:35840
	ds_read_b128 v[186:189], v150 offset:36864
	ds_read_b128 v[190:193], v150 offset:37888
	ds_read_b128 v[194:197], v150 offset:38912
	global_load_lds_dwordx4 v134, s[38:39]
	s_mov_b32 m0, s50
	ds_read_b128 v[198:201], v150 offset:39936
	global_load_lds_dwordx4 v130, s[38:39]
	s_waitcnt lgkmcnt(8)
	s_barrier
; #define PG8_STAGE(bufoff, gbase, voff) do { _Pragma("unroll") for (int _i = 0; _i < 2; ++_i) \
;         __builtin_amdgcn_global_load_lds((const unsigned*)((const char*)(gbase) + (voff)[_i]), (LAS unsigned*)(lds + (bufoff) + ldsw + _i * 8192), 16, 0, 0); } while (0)
; #define PG8_LDA(dst, b, h) do { _Pragma("unroll") for (int m = 0; m < 4; ++m) _Pragma("unroll") for (int k = 0; k < 2; ++k) dst[m][k] = *(const LAS bf16x8*)(lds + PG8_SA(b, h) + aoff + m * 2048 + k * 1024); } while (0)
; #define PG8_LDB(dst, b, h) do { _Pragma("unroll") for (int n = 0; n < 2; ++n) _Pragma("unroll") for (int k = 0; k < 2; ++k) dst[n][k] = *(const LAS bf16x8*)(lds + PG8_SB(b, h) + boff + n * 2048 + k * 1024); } while (0)
; #define PG8_MMA(ai, bj, At, Bt) do { __builtin_amdgcn_s_setprio(1); _Pragma("unroll") for (int m = 0; m < 4; ++m) _Pragma("unroll") for (int n = 0; n < 2; ++n) _Pragma("unroll") for (int k = 0; k < 2; ++k) \
;         acc[ai][bj][m][n] = __builtin_amdgcn_mfma_f32_16x16x32_bf16(Bt[n][k], At[m][k], acc[ai][bj][m][n], 0, 0, 0); __builtin_amdgcn_s_setprio(0); } while (0)
; #define PG8_WAIT_V(n) asm volatile("s_waitcnt vmcnt(" #n ")" ::: "memory")
; #define PG8_WAIT_L(n) asm volatile("s_waitcnt lgkmcnt(" #n ")" ::: "memory")
; #define PG8_BAR __builtin_amdgcn_s_barrier()
; #define PG8_SCHED __builtin_amdgcn_sched_barrier(0)
; template <class Epi>
; DI void gemm_phase(LAS unsigned char* lds, const Gemm g, const StaticOrder& S, const Epi& E) {
;     ...
;             PG8_LDB(B0, 1, 0); PG8_SCHED; PG8_LDA(At, 1, 0); PG8_STAGE(PG8_SA(0, 1), a2 + hstep, voffA);
;             PG8_WAIT_L(8); PG8_BAR; PG8_WAIT_L(0); PG8_MMA(0, 0, At, B0); PG8_BAR; PG8_SCHED;
;             PG8_LDB(B1, 1, 1); PG8_STAGE(PG8_SB(1, 0), b3, voffB);
;             PG8_BAR; PG8_WAIT_L(0); PG8_MMA(0, 1, At, B1); PG8_BAR;
;             PG8_LDA(At, 1, 1); PG8_STAGE(PG8_SA(1, 0), a3, voffA);
;             PG8_BAR; PG8_WAIT_L(0); PG8_MMA(1, 0, At, B0); PG8_BAR; PG8_SCHED;
;             PG8_STAGE(PG8_SB(1, 1), b3 + hstep, voffB);
;             PG8_WAIT_V(6); PG8_BAR; PG8_MMA(1, 1, At, B1); PG8_BAR;
	s_waitcnt lgkmcnt(7)
	v_mfma_f32_16x16x32_bf16 v[124:127], v[152:155], v[168:171], v[124:127]
	v_mfma_f32_16x16x32_bf16 v[120:123], v[160:163], v[168:171], v[120:123]
	s_waitcnt lgkmcnt(5)
	v_mfma_f32_16x16x32_bf16 v[108:111], v[152:155], v[176:179], v[108:111]
	v_mfma_f32_16x16x32_bf16 v[104:107], v[160:163], v[176:179], v[104:107]
	s_waitcnt lgkmcnt(3)
	v_mfma_f32_16x16x32_bf16 v[92:95], v[152:155], v[186:189], v[92:95]
	v_mfma_f32_16x16x32_bf16 v[88:91], v[160:163], v[186:189], v[88:91]
	s_waitcnt lgkmcnt(1)
	v_mfma_f32_16x16x32_bf16 v[76:79], v[152:155], v[194:197], v[76:79]
	v_mfma_f32_16x16x32_bf16 v[72:75], v[160:163], v[194:197], v[72:75]
	v_mfma_f32_16x16x32_bf16 v[124:127], v[156:159], v[172:175], v[124:127]
	v_mfma_f32_16x16x32_bf16 v[120:123], v[164:167], v[172:175], v[120:123]
	v_mfma_f32_16x16x32_bf16 v[108:111], v[156:159], v[182:185], v[108:111]
	v_mfma_f32_16x16x32_bf16 v[104:107], v[164:167], v[182:185], v[104:107]
	v_mfma_f32_16x16x32_bf16 v[92:95], v[156:159], v[190:193], v[92:95]
	v_mfma_f32_16x16x32_bf16 v[88:91], v[164:167], v[190:193], v[88:91]
	s_add_i32 s38, 0, 0x1c000
	s_add_i32 s39, s64, s45
	s_waitcnt lgkmcnt(0)
	v_mfma_f32_16x16x32_bf16 v[76:79], v[156:159], v[198:201], v[76:79]
	s_mov_b32 m0, s39
	v_mfma_f32_16x16x32_bf16 v[72:75], v[164:167], v[198:201], v[72:75]
	s_barrier
	ds_read_b128 v[202:205], v252
	ds_read_b128 v[206:209], v252 offset:1024
	ds_read_b128 v[210:213], v252 offset:2048
	global_load_lds_dwordx4 v132, s[86:87]
	s_add_i32 m0, s39, 0x2000
	ds_read_b128 v[214:217], v252 offset:3072
	global_load_lds_dwordx4 v128, s[86:87]
	s_barrier
	s_waitcnt lgkmcnt(3)
	v_mfma_f32_16x16x32_bf16 v[116:119], v[202:205], v[168:171], v[116:119]
	s_waitcnt lgkmcnt(1)
	v_mfma_f32_16x16x32_bf16 v[112:115], v[210:213], v[168:171], v[112:115]
	v_mfma_f32_16x16x32_bf16 v[100:103], v[202:205], v[176:179], v[100:103]
	v_mfma_f32_16x16x32_bf16 v[96:99], v[210:213], v[176:179], v[96:99]
	v_mfma_f32_16x16x32_bf16 v[84:87], v[202:205], v[186:189], v[84:87]
	v_mfma_f32_16x16x32_bf16 v[80:83], v[210:213], v[186:189], v[80:83]
	v_mfma_f32_16x16x32_bf16 v[68:71], v[202:205], v[194:197], v[68:71]
	v_mfma_f32_16x16x32_bf16 v[64:67], v[210:213], v[194:197], v[64:67]
	v_mfma_f32_16x16x32_bf16 v[116:119], v[206:209], v[172:175], v[116:119]
	s_waitcnt lgkmcnt(0)
	v_mfma_f32_16x16x32_bf16 v[112:115], v[214:217], v[172:175], v[112:115]
	v_mfma_f32_16x16x32_bf16 v[100:103], v[206:209], v[182:185], v[100:103]
	v_mfma_f32_16x16x32_bf16 v[96:99], v[214:217], v[182:185], v[96:99]
	v_mfma_f32_16x16x32_bf16 v[84:87], v[206:209], v[190:193], v[84:87]
	v_mfma_f32_16x16x32_bf16 v[80:83], v[214:217], v[190:193], v[80:83]
	v_mfma_f32_16x16x32_bf16 v[68:71], v[206:209], v[198:201], v[68:71]
	s_mov_b32 m0, s52
	v_mfma_f32_16x16x32_bf16 v[64:67], v[214:217], v[198:201], v[64:67]
	s_barrier
	ds_read_b128 v[168:171], v150 offset:49152
	ds_read_b128 v[172:175], v150 offset:50176
	ds_read_b128 v[176:179], v150 offset:51200
	ds_read_b128 v[182:185], v150 offset:52224
	ds_read_b128 v[186:189], v150 offset:53248
	ds_read_b128 v[190:193], v150 offset:54272
	ds_read_b128 v[194:197], v150 offset:55296
	global_load_lds_dwordx4 v134, s[88:89]
	s_mov_b32 m0, s53
	ds_read_b128 v[198:201], v150 offset:56320
	global_load_lds_dwordx4 v130, s[88:89]
	s_barrier
	s_waitcnt lgkmcnt(7)
	v_mfma_f32_16x16x32_bf16 v[60:63], v[152:155], v[168:171], v[60:63]
	v_mfma_f32_16x16x32_bf16 v[56:59], v[160:163], v[168:171], v[56:59]
	s_waitcnt lgkmcnt(5)
	v_mfma_f32_16x16x32_bf16 v[44:47], v[152:155], v[176:179], v[44:47]
	v_mfma_f32_16x16x32_bf16 v[40:43], v[160:163], v[176:179], v[40:43]
	s_waitcnt lgkmcnt(3)
	v_mfma_f32_16x16x32_bf16 v[28:31], v[152:155], v[186:189], v[28:31]
	v_mfma_f32_16x16x32_bf16 v[24:27], v[160:163], v[186:189], v[24:27]
	s_waitcnt lgkmcnt(1)
	v_mfma_f32_16x16x32_bf16 v[12:15], v[152:155], v[194:197], v[12:15]
	v_mfma_f32_16x16x32_bf16 v[8:11], v[160:163], v[194:197], v[8:11]
	v_mfma_f32_16x16x32_bf16 v[60:63], v[156:159], v[172:175], v[60:63]
	v_mfma_f32_16x16x32_bf16 v[56:59], v[164:167], v[172:175], v[56:59]
	v_mfma_f32_16x16x32_bf16 v[44:47], v[156:159], v[182:185], v[44:47]
	v_mfma_f32_16x16x32_bf16 v[40:43], v[164:167], v[182:185], v[40:43]
	v_mfma_f32_16x16x32_bf16 v[28:31], v[156:159], v[190:193], v[28:31]
	v_mfma_f32_16x16x32_bf16 v[24:27], v[164:167], v[190:193], v[24:27]
	s_add_u32 s36, s36, 0x40080
	s_addc_u32 s37, s37, 0
	s_waitcnt lgkmcnt(0)
	v_mfma_f32_16x16x32_bf16 v[12:15], v[156:159], v[198:201], v[12:15]
	s_add_i32 s38, s38, s45
	s_mov_b32 m0, s38
	v_mfma_f32_16x16x32_bf16 v[8:11], v[164:167], v[198:201], v[8:11]
	s_barrier
	global_load_lds_dwordx4 v132, s[36:37]
	s_add_i32 m0, s38, 0x2000
	s_waitcnt vmcnt(5)
	global_load_lds_dwordx4 v128, s[36:37]
	s_barrier
	v_mfma_f32_16x16x32_bf16 v[52:55], v[202:205], v[168:171], v[52:55]
	v_mfma_f32_16x16x32_bf16 v[48:51], v[210:213], v[168:171], v[48:51]
	v_mfma_f32_16x16x32_bf16 v[36:39], v[202:205], v[176:179], v[36:39]
	v_mfma_f32_16x16x32_bf16 v[32:35], v[210:213], v[176:179], v[32:35]
	v_mfma_f32_16x16x32_bf16 v[20:23], v[202:205], v[186:189], v[20:23]
	v_mfma_f32_16x16x32_bf16 v[16:19], v[210:213], v[186:189], v[16:19]
	v_mfma_f32_16x16x32_bf16 v[4:7], v[202:205], v[194:197], v[4:7]
	v_mfma_f32_16x16x32_bf16 v[0:3], v[210:213], v[194:197], v[0:3]
	v_mfma_f32_16x16x32_bf16 v[52:55], v[206:209], v[172:175], v[52:55]
	s_add_i32 s63, s63, 2
	s_add_u32 s24, s24, 0x100
	v_mfma_f32_16x16x32_bf16 v[48:51], v[214:217], v[172:175], v[48:51]
	s_addc_u32 s25, s25, 0
	s_add_u32 s61, s61, 0x100
	v_mfma_f32_16x16x32_bf16 v[36:39], v[206:209], v[182:185], v[36:39]
	s_addc_u32 s62, s62, 0
	s_add_u32 s36, s24, 0xfffc0080
	v_mfma_f32_16x16x32_bf16 v[32:35], v[214:217], v[182:185], v[32:35]
	s_addc_u32 s37, s25, -1
	s_cmp_eq_u32 s63, 12
	v_mfma_f32_16x16x32_bf16 v[20:23], v[206:209], v[190:193], v[20:23]
	s_cselect_b32 s39, s17, s37
	s_cselect_b32 s38, s59, s36
	v_mfma_f32_16x16x32_bf16 v[16:19], v[214:217], v[190:193], v[16:19]
	s_cselect_b32 s37, s15, s62
	s_cselect_b32 s36, s60, s61
	v_mfma_f32_16x16x32_bf16 v[4:7], v[206:209], v[198:201], v[4:7]
	s_add_i32 m0, s23, 0xc000
	v_mfma_f32_16x16x32_bf16 v[0:3], v[214:217], v[198:201], v[0:3]
	s_cmp_gt_u32 s63, 13
	s_barrier
; DI unsigned pk2(float a, float b) { f32x2 v = {a, b}; bf16x2_t r = __builtin_convertvector(v, bf16x2_t); return __builtin_bit_cast(unsigned, r); }
; DI float siluf_(float x) { return x * __builtin_amdgcn_rcpf(1.f + __expf(-x)); }
;     DI void operator()(const f32x4 (&acc)[2][2][4][2], const Unit& u, int wr, int wc, int fr, int fq) const {
;         const int row0 = u.pm * BM + wr * 64 + fr, col0 = u.pn * HALF + wc * 32 + 8 * fq;
; #pragma unroll
;         for (int ai = 0; ai < 2; ++ai)
; #pragma unroll
;             for (int m = 0; m < 4; ++m) { bf16_t* rowp = O + (size_t)(row0 + ai * HALF + m * 16) * DFF + col0;
;                 f32x4 v0, v1;
; #pragma unroll
;                 for (int j = 0; j < 4; ++j) { v0[j] = siluf_(acc[ai][0][m][0][j]) * acc[ai][1][m][0][j]; v1[j] = siluf_(acc[ai][0][m][1][j]) * acc[ai][1][m][1][j]; }
;                 u32x4 w; w.x = pk2(v0[0], v0[1]); w.y = pk2(v0[2], v0[3]); w.z = pk2(v1[0], v1[1]); w.w = pk2(v1[2], v1[3]);
;                 *(u32x4*)rowp = w; }
	s_cbranch_scc0 .LBB0_849
	v_mul_f32_e32 v153, 0xbfb8aa3b, v124
	v_mul_f32_e32 v158, 0xbfb8aa3b, v120
	v_exp_f32_e32 v153, v153
	v_exp_f32_e32 v159, v158
	v_mul_f32_e32 v158, 0xbfb8aa3b, v125
	v_exp_f32_e32 v160, v158
	v_add_f32_e32 v153, 1.0, v153
	v_rcp_f32_e32 v158, v153
	v_add_f32_e32 v153, 1.0, v159
	v_add_f32_e32 v159, 1.0, v160
	v_rcp_f32_e32 v159, v159
	v_mul_f32_e32 v160, 0xbfb8aa3b, v121
	v_exp_f32_e32 v161, v160
	v_rcp_f32_e32 v160, v153
	v_pk_mul_f32 v[124:125], v[124:125], v[158:159]
	v_mul_f32_e32 v153, 0xbfb8aa3b, v127
	v_pk_mul_f32 v[116:117], v[124:125], v[116:117]
	v_add_f32_e32 v124, 1.0, v161
	v_mul_f32_e32 v125, 0xbfb8aa3b, v122
	v_rcp_f32_e32 v161, v124
	v_mul_f32_e32 v124, 0xbfb8aa3b, v126
	v_exp_f32_e32 v125, v125
	v_exp_f32_e32 v124, v124
	v_exp_f32_e32 v153, v153
	v_mul_f32_e32 v158, 0xbfb8aa3b, v123
	v_exp_f32_e32 v159, v158
	v_add_f32_e32 v125, 1.0, v125
	v_add_f32_e32 v124, 1.0, v124
	v_rcp_f32_e32 v158, v125
	v_add_f32_e32 v125, 1.0, v153
	v_rcp_f32_e32 v124, v124
	v_rcp_f32_e32 v125, v125
	v_add_f32_e32 v153, 1.0, v159
	v_rcp_f32_e32 v159, v153
	v_pk_mul_f32 v[120:121], v[120:121], v[160:161]
	v_lshl_or_b32 v154, s58, 7, v148
	v_pk_mul_f32 v[120:121], v[120:121], v[112:113]
	v_pk_mul_f32 v[112:113], v[126:127], v[124:125]
	v_lshl_add_u32 v152, s22, 8, v146
	v_ashrrev_i32_e32 v155, 31, v154
	v_mov_b64_e32 v[144:145], s[8:9]
	v_pk_mul_f32 v[118:119], v[112:113], v[118:119]
	v_pk_mul_f32 v[112:113], v[122:123], v[158:159]
	v_mad_i64_i32 v[156:157], s[24:25], v152, s57, v[144:145]
	v_pk_mul_f32 v[122:123], v[112:113], v[114:115]
	v_lshlrev_b64 v[112:113], 1, v[154:155]
	v_lshl_add_u64 v[124:125], v[156:157], 0, v[112:113]
	v_cvt_pk_bf16_f32 v114, v116, v117
	v_cvt_pk_bf16_f32 v115, v118, v119
	v_cvt_pk_bf16_f32 v116, v120, v121
	v_cvt_pk_bf16_f32 v117, v122, v123
	global_store_dwordx4 v[124:125], v[114:117], off
	v_mul_f32_e32 v118, 0xbfb8aa3b, v109
	v_exp_f32_e32 v118, v118
	v_mul_f32_e32 v116, 0xbfb8aa3b, v108
	v_mul_f32_e32 v117, 0xbfb8aa3b, v104
	v_exp_f32_e32 v116, v116
	v_exp_f32_e32 v117, v117
	v_or_b32_e32 v114, 16, v152
	v_mad_i64_i32 v[114:115], s[24:25], v114, s57, v[144:145]
	v_add_f32_e32 v116, 1.0, v116
	v_add_f32_e32 v119, 1.0, v117
	v_add_f32_e32 v117, 1.0, v118
	v_rcp_f32_e32 v116, v116
	v_rcp_f32_e32 v117, v117
	v_mul_f32_e32 v118, 0xbfb8aa3b, v105
	v_exp_f32_e32 v120, v118
	v_rcp_f32_e32 v118, v119
	v_pk_mul_f32 v[108:109], v[108:109], v[116:117]
	v_mul_f32_e32 v116, 0xbfb8aa3b, v111
	v_pk_mul_f32 v[100:101], v[108:109], v[100:101]
	v_add_f32_e32 v108, 1.0, v120
	v_rcp_f32_e32 v119, v108
	v_mul_f32_e32 v109, 0xbfb8aa3b, v106
	v_mul_f32_e32 v108, 0xbfb8aa3b, v110
	v_exp_f32_e32 v109, v109
	v_exp_f32_e32 v108, v108
	v_exp_f32_e32 v117, v116
	v_mul_f32_e32 v116, 0xbfb8aa3b, v107
	v_pk_mul_f32 v[104:105], v[104:105], v[118:119]
	v_exp_f32_e32 v118, v116
	v_add_f32_e32 v109, 1.0, v109
	v_add_f32_e32 v108, 1.0, v108
	v_rcp_f32_e32 v116, v109
	v_add_f32_e32 v109, 1.0, v117
	v_rcp_f32_e32 v108, v108
	v_rcp_f32_e32 v109, v109
	v_add_f32_e32 v117, 1.0, v118
	v_rcp_f32_e32 v117, v117
	v_pk_mul_f32 v[104:105], v[104:105], v[96:97]
	v_pk_mul_f32 v[96:97], v[110:111], v[108:109]
	v_lshl_add_u64 v[108:109], v[114:115], 0, v[112:113]
	v_pk_mul_f32 v[102:103], v[96:97], v[102:103]
	v_pk_mul_f32 v[96:97], v[106:107], v[116:117]
	s_and_b64 vcc, exec, s[4:5]
	v_pk_mul_f32 v[106:107], v[96:97], v[98:99]
	v_cvt_pk_bf16_f32 v96, v100, v101
	v_cvt_pk_bf16_f32 v97, v102, v103
	v_cvt_pk_bf16_f32 v98, v104, v105
	v_cvt_pk_bf16_f32 v99, v106, v107
	global_store_dwordx4 v[108:109], v[96:99], off
	v_mul_f32_e32 v100, 0xbfb8aa3b, v93
	v_exp_f32_e32 v100, v100
	v_mul_f32_e32 v98, 0xbfb8aa3b, v92
	v_mul_f32_e32 v99, 0xbfb8aa3b, v88
	v_exp_f32_e32 v98, v98
	v_exp_f32_e32 v99, v99
	v_or_b32_e32 v96, 32, v152
	v_mad_i64_i32 v[96:97], s[24:25], v96, s57, v[144:145]
	v_add_f32_e32 v98, 1.0, v98
	v_add_f32_e32 v101, 1.0, v99
	v_add_f32_e32 v99, 1.0, v100
	v_rcp_f32_e32 v98, v98
	v_rcp_f32_e32 v99, v99
	v_mul_f32_e32 v100, 0xbfb8aa3b, v89
	v_exp_f32_e32 v102, v100
	v_rcp_f32_e32 v100, v101
	v_pk_mul_f32 v[92:93], v[92:93], v[98:99]
	v_mul_f32_e32 v98, 0xbfb8aa3b, v95
	v_pk_mul_f32 v[84:85], v[92:93], v[84:85]
	v_add_f32_e32 v92, 1.0, v102
	v_rcp_f32_e32 v101, v92
	v_mul_f32_e32 v93, 0xbfb8aa3b, v90
	v_mul_f32_e32 v92, 0xbfb8aa3b, v94
	v_exp_f32_e32 v93, v93
	v_exp_f32_e32 v92, v92
	v_exp_f32_e32 v99, v98
	v_mul_f32_e32 v98, 0xbfb8aa3b, v91
	v_pk_mul_f32 v[88:89], v[88:89], v[100:101]
	v_exp_f32_e32 v100, v98
	v_add_f32_e32 v93, 1.0, v93
	v_add_f32_e32 v92, 1.0, v92
	v_rcp_f32_e32 v98, v93
	v_add_f32_e32 v93, 1.0, v99
	v_rcp_f32_e32 v92, v92
	v_rcp_f32_e32 v93, v93
	v_add_f32_e32 v99, 1.0, v100
	v_rcp_f32_e32 v99, v99
	v_pk_mul_f32 v[88:89], v[88:89], v[80:81]
	v_pk_mul_f32 v[80:81], v[94:95], v[92:93]
	v_lshl_add_u64 v[92:93], v[96:97], 0, v[112:113]
	v_pk_mul_f32 v[86:87], v[80:81], v[86:87]
	v_pk_mul_f32 v[80:81], v[90:91], v[98:99]
	s_mov_b32 s58, s14
	v_pk_mul_f32 v[90:91], v[80:81], v[82:83]
	v_cvt_pk_bf16_f32 v80, v84, v85
	v_cvt_pk_bf16_f32 v81, v86, v87
	v_cvt_pk_bf16_f32 v82, v88, v89
	v_cvt_pk_bf16_f32 v83, v90, v91
	global_store_dwordx4 v[92:93], v[80:83], off
	v_mul_f32_e32 v84, 0xbfb8aa3b, v77
	v_exp_f32_e32 v84, v84
	v_mul_f32_e32 v82, 0xbfb8aa3b, v76
	v_mul_f32_e32 v83, 0xbfb8aa3b, v72
	v_exp_f32_e32 v82, v82
	v_exp_f32_e32 v83, v83
	v_or_b32_e32 v80, 48, v152
	v_mad_i64_i32 v[80:81], s[24:25], v80, s57, v[144:145]
	v_add_f32_e32 v82, 1.0, v82
	v_add_f32_e32 v85, 1.0, v83
	v_add_f32_e32 v83, 1.0, v84
	v_rcp_f32_e32 v82, v82
	v_rcp_f32_e32 v83, v83
	v_mul_f32_e32 v84, 0xbfb8aa3b, v73
	v_exp_f32_e32 v86, v84
; DI unsigned pk2(float a, float b) { f32x2 v = {a, b}; bf16x2_t r = __builtin_convertvector(v, bf16x2_t); return __builtin_bit_cast(unsigned, r); }
; DI float siluf_(float x) { return x * __builtin_amdgcn_rcpf(1.f + __expf(-x)); }
;     DI void operator()(const f32x4 (&acc)[2][2][4][2], const Unit& u, int wr, int wc, int fr, int fq) const {
;     ...
;         for (int ai = 0; ai < 2; ++ai)
; #pragma unroll
;             for (int m = 0; m < 4; ++m) { bf16_t* rowp = O + (size_t)(row0 + ai * HALF + m * 16) * DFF + col0;
;                 f32x4 v0, v1;
; #pragma unroll
;                 for (int j = 0; j < 4; ++j) { v0[j] = siluf_(acc[ai][0][m][0][j]) * acc[ai][1][m][0][j]; v1[j] = siluf_(acc[ai][0][m][1][j]) * acc[ai][1][m][1][j]; }
;                 u32x4 w; w.x = pk2(v0[0], v0[1]); w.y = pk2(v0[2], v0[3]); w.z = pk2(v1[0], v1[1]); w.w = pk2(v1[2], v1[3]);
;                 *(u32x4*)rowp = w; }
	v_rcp_f32_e32 v84, v85
	v_pk_mul_f32 v[76:77], v[76:77], v[82:83]
	v_mul_f32_e32 v82, 0xbfb8aa3b, v79
	v_pk_mul_f32 v[68:69], v[76:77], v[68:69]
	v_add_f32_e32 v76, 1.0, v86
	v_rcp_f32_e32 v85, v76
	v_mul_f32_e32 v77, 0xbfb8aa3b, v74
	v_mul_f32_e32 v76, 0xbfb8aa3b, v78
	v_exp_f32_e32 v77, v77
	v_exp_f32_e32 v76, v76
	v_exp_f32_e32 v83, v82
	v_mul_f32_e32 v82, 0xbfb8aa3b, v75
	v_pk_mul_f32 v[72:73], v[72:73], v[84:85]
	v_exp_f32_e32 v84, v82
	v_add_f32_e32 v77, 1.0, v77
	v_add_f32_e32 v76, 1.0, v76
	v_rcp_f32_e32 v82, v77
	v_add_f32_e32 v77, 1.0, v83
	v_rcp_f32_e32 v76, v76
	v_rcp_f32_e32 v77, v77
	v_add_f32_e32 v83, 1.0, v84
	v_rcp_f32_e32 v83, v83
	v_pk_mul_f32 v[72:73], v[72:73], v[64:65]
	v_pk_mul_f32 v[64:65], v[78:79], v[76:77]
	v_lshl_add_u64 v[76:77], v[80:81], 0, v[112:113]
	v_pk_mul_f32 v[70:71], v[64:65], v[70:71]
	v_pk_mul_f32 v[64:65], v[74:75], v[82:83]
	s_mov_b32 s22, s16
	v_pk_mul_f32 v[74:75], v[64:65], v[66:67]
	v_cvt_pk_bf16_f32 v64, v68, v69
	v_cvt_pk_bf16_f32 v65, v70, v71
	v_cvt_pk_bf16_f32 v66, v72, v73
	v_cvt_pk_bf16_f32 v67, v74, v75
	global_store_dwordx4 v[76:77], v[64:67], off
	v_mul_f32_e32 v68, 0xbfb8aa3b, v61
	v_exp_f32_e32 v68, v68
	v_mul_f32_e32 v66, 0xbfb8aa3b, v60
	v_mul_f32_e32 v67, 0xbfb8aa3b, v56
	v_exp_f32_e32 v66, v66
	v_exp_f32_e32 v67, v67
	v_add_u32_e32 v64, 0x80, v152
	v_mad_i64_i32 v[64:65], s[24:25], v64, s57, v[144:145]
	v_add_f32_e32 v66, 1.0, v66
	v_add_f32_e32 v69, 1.0, v67
	v_add_f32_e32 v67, 1.0, v68
	v_rcp_f32_e32 v66, v66
	v_rcp_f32_e32 v67, v67
	v_mul_f32_e32 v68, 0xbfb8aa3b, v57
	v_exp_f32_e32 v70, v68
	v_rcp_f32_e32 v68, v69
	v_pk_mul_f32 v[60:61], v[60:61], v[66:67]
	v_mul_f32_e32 v66, 0xbfb8aa3b, v63
	v_pk_mul_f32 v[52:53], v[60:61], v[52:53]
	v_add_f32_e32 v60, 1.0, v70
	v_rcp_f32_e32 v69, v60
	v_mul_f32_e32 v61, 0xbfb8aa3b, v58
	v_mul_f32_e32 v60, 0xbfb8aa3b, v62
	v_exp_f32_e32 v61, v61
	v_exp_f32_e32 v60, v60
	v_exp_f32_e32 v67, v66
	v_mul_f32_e32 v66, 0xbfb8aa3b, v59
	v_pk_mul_f32 v[56:57], v[56:57], v[68:69]
	v_exp_f32_e32 v68, v66
	v_add_f32_e32 v61, 1.0, v61
	v_add_f32_e32 v60, 1.0, v60
	v_rcp_f32_e32 v66, v61
	v_add_f32_e32 v61, 1.0, v67
	v_rcp_f32_e32 v60, v60
	v_rcp_f32_e32 v61, v61
	v_add_f32_e32 v67, 1.0, v68
	v_rcp_f32_e32 v67, v67
	v_pk_mul_f32 v[56:57], v[56:57], v[48:49]
	v_pk_mul_f32 v[48:49], v[62:63], v[60:61]
	v_lshl_add_u64 v[60:61], v[64:65], 0, v[112:113]
	v_pk_mul_f32 v[54:55], v[48:49], v[54:55]
	v_pk_mul_f32 v[48:49], v[58:59], v[66:67]
	s_mov_b64 s[36:37], s[20:21]
	v_pk_mul_f32 v[58:59], v[48:49], v[50:51]
	v_cvt_pk_bf16_f32 v48, v52, v53
	v_cvt_pk_bf16_f32 v49, v54, v55
	v_cvt_pk_bf16_f32 v50, v56, v57
	v_cvt_pk_bf16_f32 v51, v58, v59
	global_store_dwordx4 v[60:61], v[48:51], off
	v_mul_f32_e32 v52, 0xbfb8aa3b, v45
	v_exp_f32_e32 v52, v52
	v_mul_f32_e32 v50, 0xbfb8aa3b, v44
	v_mul_f32_e32 v51, 0xbfb8aa3b, v40
	v_exp_f32_e32 v50, v50
	v_exp_f32_e32 v51, v51
	v_add_u32_e32 v48, 0x90, v152
	v_mad_i64_i32 v[48:49], s[24:25], v48, s57, v[144:145]
	v_add_f32_e32 v50, 1.0, v50
	v_add_f32_e32 v53, 1.0, v51
	v_add_f32_e32 v51, 1.0, v52
	v_rcp_f32_e32 v50, v50
	v_rcp_f32_e32 v51, v51
	v_mul_f32_e32 v52, 0xbfb8aa3b, v41
	v_exp_f32_e32 v54, v52
	v_rcp_f32_e32 v52, v53
	v_pk_mul_f32 v[44:45], v[44:45], v[50:51]
	v_mul_f32_e32 v50, 0xbfb8aa3b, v47
	v_pk_mul_f32 v[36:37], v[44:45], v[36:37]
	v_add_f32_e32 v44, 1.0, v54
	v_rcp_f32_e32 v53, v44
	v_mul_f32_e32 v45, 0xbfb8aa3b, v42
	v_mul_f32_e32 v44, 0xbfb8aa3b, v46
	v_exp_f32_e32 v45, v45
	v_exp_f32_e32 v44, v44
	v_exp_f32_e32 v51, v50
	v_mul_f32_e32 v50, 0xbfb8aa3b, v43
	v_pk_mul_f32 v[40:41], v[40:41], v[52:53]
	v_exp_f32_e32 v52, v50
	v_add_f32_e32 v45, 1.0, v45
	v_add_f32_e32 v44, 1.0, v44
	v_rcp_f32_e32 v50, v45
	v_add_f32_e32 v45, 1.0, v51
	v_rcp_f32_e32 v44, v44
; DI unsigned pk2(float a, float b) { f32x2 v = {a, b}; bf16x2_t r = __builtin_convertvector(v, bf16x2_t); return __builtin_bit_cast(unsigned, r); }
; DI float siluf_(float x) { return x * __builtin_amdgcn_rcpf(1.f + __expf(-x)); }
; template <class Epi>
; DI void gemm_phase(LAS unsigned char* lds, const Gemm g, const StaticOrder& S, const Epi& E) {
;     ...
;         if (!has_next) break;
; #pragma unroll
;         for (int a = 0; a < 2; ++a)
; #pragma unroll
;             for (int b = 0; b < 2; ++b)
; #pragma unroll
;                 for (int m = 0; m < 4; ++m)
; #pragma unroll
;                     for (int n = 0; n < 2; ++n) acc[a][b][m][n] = (f32x4){0.f, 0.f, 0.f, 0.f};
;         cur = nxt; cA = nA; cB = nB; ++ui;
;     }
;     DI void operator()(const f32x4 (&acc)[2][2][4][2], const Unit& u, int wr, int wc, int fr, int fq) const {
;     ...
;         for (int ai = 0; ai < 2; ++ai)
; #pragma unroll
;             for (int m = 0; m < 4; ++m) { bf16_t* rowp = O + (size_t)(row0 + ai * HALF + m * 16) * DFF + col0;
;                 f32x4 v0, v1;
; #pragma unroll
;                 for (int j = 0; j < 4; ++j) { v0[j] = siluf_(acc[ai][0][m][0][j]) * acc[ai][1][m][0][j]; v1[j] = siluf_(acc[ai][0][m][1][j]) * acc[ai][1][m][1][j]; }
;                 u32x4 w; w.x = pk2(v0[0], v0[1]); w.y = pk2(v0[2], v0[3]); w.z = pk2(v1[0], v1[1]); w.w = pk2(v1[2], v1[3]);
;                 *(u32x4*)rowp = w; }
	v_rcp_f32_e32 v45, v45
	v_add_f32_e32 v51, 1.0, v52
	v_rcp_f32_e32 v51, v51
	v_pk_mul_f32 v[40:41], v[40:41], v[32:33]
	v_pk_mul_f32 v[32:33], v[46:47], v[44:45]
	v_lshl_add_u64 v[44:45], v[48:49], 0, v[112:113]
	v_pk_mul_f32 v[38:39], v[32:33], v[38:39]
	v_pk_mul_f32 v[32:33], v[42:43], v[50:51]
	s_nop 0
	v_pk_mul_f32 v[42:43], v[32:33], v[34:35]
	v_cvt_pk_bf16_f32 v32, v36, v37
	v_cvt_pk_bf16_f32 v33, v38, v39
	v_cvt_pk_bf16_f32 v34, v40, v41
	v_cvt_pk_bf16_f32 v35, v42, v43
	global_store_dwordx4 v[44:45], v[32:35], off
	v_mul_f32_e32 v36, 0xbfb8aa3b, v29
	v_exp_f32_e32 v36, v36
	v_mul_f32_e32 v34, 0xbfb8aa3b, v28
	v_mul_f32_e32 v35, 0xbfb8aa3b, v24
	v_exp_f32_e32 v34, v34
	v_exp_f32_e32 v35, v35
	v_add_u32_e32 v32, 0xa0, v152
	v_mad_i64_i32 v[32:33], s[24:25], v32, s57, v[144:145]
	v_add_f32_e32 v34, 1.0, v34
	v_add_f32_e32 v37, 1.0, v35
	v_add_f32_e32 v35, 1.0, v36
	v_rcp_f32_e32 v34, v34
	v_rcp_f32_e32 v35, v35
	v_mul_f32_e32 v36, 0xbfb8aa3b, v25
	v_exp_f32_e32 v38, v36
	v_rcp_f32_e32 v36, v37
	v_pk_mul_f32 v[28:29], v[28:29], v[34:35]
	v_mul_f32_e32 v34, 0xbfb8aa3b, v31
	v_pk_mul_f32 v[20:21], v[28:29], v[20:21]
	v_add_f32_e32 v28, 1.0, v38
	v_rcp_f32_e32 v37, v28
	v_mul_f32_e32 v29, 0xbfb8aa3b, v26
	v_mul_f32_e32 v28, 0xbfb8aa3b, v30
	v_exp_f32_e32 v29, v29
	v_exp_f32_e32 v28, v28
	v_exp_f32_e32 v35, v34
	v_mul_f32_e32 v34, 0xbfb8aa3b, v27
	v_pk_mul_f32 v[24:25], v[24:25], v[36:37]
	v_exp_f32_e32 v36, v34
	v_add_f32_e32 v29, 1.0, v29
	v_add_f32_e32 v28, 1.0, v28
	v_rcp_f32_e32 v34, v29
	v_add_f32_e32 v29, 1.0, v35
	v_rcp_f32_e32 v28, v28
	v_rcp_f32_e32 v29, v29
	v_add_f32_e32 v35, 1.0, v36
	v_rcp_f32_e32 v35, v35
	v_pk_mul_f32 v[24:25], v[24:25], v[16:17]
	v_pk_mul_f32 v[16:17], v[30:31], v[28:29]
	v_lshl_add_u64 v[28:29], v[32:33], 0, v[112:113]
	v_pk_mul_f32 v[22:23], v[16:17], v[22:23]
	v_pk_mul_f32 v[16:17], v[26:27], v[34:35]
	s_nop 0
	v_pk_mul_f32 v[26:27], v[16:17], v[18:19]
	v_cvt_pk_bf16_f32 v16, v20, v21
	v_cvt_pk_bf16_f32 v17, v22, v23
	v_cvt_pk_bf16_f32 v18, v24, v25
	v_cvt_pk_bf16_f32 v19, v26, v27
	global_store_dwordx4 v[28:29], v[16:19], off
	v_mul_f32_e32 v20, 0xbfb8aa3b, v13
	v_exp_f32_e32 v20, v20
	v_mul_f32_e32 v18, 0xbfb8aa3b, v12
	v_mul_f32_e32 v19, 0xbfb8aa3b, v8
	v_exp_f32_e32 v18, v18
	v_exp_f32_e32 v19, v19
	v_add_u32_e32 v16, 0xb0, v152
	v_mad_i64_i32 v[16:17], s[24:25], v16, s57, v[144:145]
	v_add_f32_e32 v18, 1.0, v18
	v_add_f32_e32 v21, 1.0, v19
	v_add_f32_e32 v19, 1.0, v20
	v_rcp_f32_e32 v18, v18
	v_rcp_f32_e32 v19, v19
	v_mul_f32_e32 v20, 0xbfb8aa3b, v9
	v_exp_f32_e32 v22, v20
	v_rcp_f32_e32 v20, v21
	v_pk_mul_f32 v[12:13], v[12:13], v[18:19]
	v_mul_f32_e32 v18, 0xbfb8aa3b, v15
	v_pk_mul_f32 v[4:5], v[12:13], v[4:5]
	v_add_f32_e32 v12, 1.0, v22
	v_rcp_f32_e32 v21, v12
	v_mul_f32_e32 v13, 0xbfb8aa3b, v10
	v_mul_f32_e32 v12, 0xbfb8aa3b, v14
	v_exp_f32_e32 v13, v13
	v_exp_f32_e32 v12, v12
	v_exp_f32_e32 v19, v18
	v_mul_f32_e32 v18, 0xbfb8aa3b, v11
	v_pk_mul_f32 v[8:9], v[8:9], v[20:21]
	v_exp_f32_e32 v20, v18
	v_add_f32_e32 v13, 1.0, v13
	v_add_f32_e32 v12, 1.0, v12
	v_rcp_f32_e32 v18, v13
	v_add_f32_e32 v13, 1.0, v19
	v_rcp_f32_e32 v12, v12
	v_rcp_f32_e32 v13, v13
	v_add_f32_e32 v19, 1.0, v20
	v_rcp_f32_e32 v19, v19
	v_pk_mul_f32 v[8:9], v[8:9], v[0:1]
	v_pk_mul_f32 v[0:1], v[14:15], v[12:13]
	v_lshl_add_u64 v[12:13], v[16:17], 0, v[112:113]
	v_pk_mul_f32 v[6:7], v[0:1], v[6:7]
	v_pk_mul_f32 v[0:1], v[10:11], v[18:19]
	s_mov_b64 s[24:25], s[18:19]
	v_pk_mul_f32 v[10:11], v[0:1], v[2:3]
	v_cvt_pk_bf16_f32 v0, v4, v5
	v_cvt_pk_bf16_f32 v1, v6, v7
	v_cvt_pk_bf16_f32 v2, v8, v9
	v_cvt_pk_bf16_f32 v3, v10, v11
	global_store_dwordx4 v[12:13], v[0:3], off
	s_cbranch_vccz .LBB0_846
	s_waitcnt vmcnt(0)
	s_cmpk_gt_u32 s40, 0xff
	s_cbranch_scc1 .LBB0_853
	s_barrier

; #define PG8_STAGE(bufoff, gbase, voff) do { _Pragma("unroll") for (int _i = 0; _i < 2; ++_i) \
;         __builtin_amdgcn_global_load_lds((const unsigned*)((const char*)(gbase) + (voff)[_i]), (LAS unsigned*)(lds + (bufoff) + ldsw + _i * 8192), 16, 0, 0); } while (0)
; #define PG8_LDA(dst, b, h) do { _Pragma("unroll") for (int m = 0; m < 4; ++m) _Pragma("unroll") for (int k = 0; k < 2; ++k) dst[m][k] = *(const LAS bf16x8*)(lds + PG8_SA(b, h) + aoff + m * 2048 + k * 1024); } while (0)
; #define PG8_LDB(dst, b, h) do { _Pragma("unroll") for (int n = 0; n < 2; ++n) _Pragma("unroll") for (int k = 0; k < 2; ++k) dst[n][k] = *(const LAS bf16x8*)(lds + PG8_SB(b, h) + boff + n * 2048 + k * 1024); } while (0)
; #define PG8_MMA(ai, bj, At, Bt) do { __builtin_amdgcn_s_setprio(1); _Pragma("unroll") for (int m = 0; m < 4; ++m) _Pragma("unroll") for (int n = 0; n < 2; ++n) _Pragma("unroll") for (int k = 0; k < 2; ++k) \
;         acc[ai][bj][m][n] = __builtin_amdgcn_mfma_f32_16x16x32_bf16(Bt[n][k], At[m][k], acc[ai][bj][m][n], 0, 0, 0); __builtin_amdgcn_s_setprio(0); } while (0)
; template <class Epi>
; DI void gemm_phase(LAS unsigned char* lds, const Gemm g, const StaticOrder& S, const Epi& E) {
;     ...
;         const bool has_next = S.next(ui + 1, nxt);
;         const char* nA = has_next ? (const char*)g.A + (size_t)nxt.pm * tstep : cA; const char* nB = has_next ? (const char*)g.Bt + (size_t)nxt.pn * tstep : cB;
;         for (int t = 0; t < nt; t += 2) {
;             const bool last = (t == nt - 2);
;             const char* a1 = cA + (size_t)(t + 1) * kstep;
;             const char* a2 = last ? nA : cA + (size_t)(t + 2) * kstep; const char* b2 = last ? nB : cB + (size_t)(t + 2) * kstep;
;             const char* a3 = a2 + kstep; const char* b3 = b2 + kstep;
;             PG8_LDB(B0, 0, 0); PG8_SCHED; PG8_LDA(At, 0, 0); PG8_STAGE(PG8_SA(1, 1), a1 + hstep, voffA);
;             PG8_WAIT_L(8); PG8_BAR; PG8_WAIT_L(0); PG8_MMA(0, 0, At, B0); PG8_BAR; PG8_SCHED;
;             PG8_LDB(B1, 0, 1); PG8_STAGE(PG8_SB(0, 0), b2, voffB);
;             PG8_BAR; PG8_WAIT_L(0); PG8_MMA(0, 1, At, B1); PG8_BAR;
;             PG8_LDA(At, 0, 1); PG8_STAGE(PG8_SA(0, 0), a2, voffA);
;             PG8_BAR; PG8_WAIT_L(0); PG8_MMA(1, 0, At, B0); PG8_BAR; PG8_SCHED;
;             PG8_STAGE(PG8_SB(0, 1), b2 + hstep, voffB);
;             PG8_WAIT_V(6); PG8_BAR; PG8_MMA(1, 1, At, B1); PG8_BAR;
.LBB0_927:
	s_add_u32 s36, s36, 0xb0080
	s_addc_u32 s37, s37, 0
	s_add_u32 s71, s38, 0x100
	s_addc_u32 s72, s39, 0
	s_mov_b32 s73, -2
	v_add_u32_e32 v253, 0x18000, v171
	v_add_u32_e32 v252, 0x1c000, v171
	ds_read_b128 v[128:131], v173
	ds_read_b128 v[132:135], v173 offset:1024
	ds_read_b128 v[136:139], v173 offset:2048
	ds_read_b128 v[140:143], v173 offset:3072
	s_add_u32 s38, s36, 0xfff50080
	s_addc_u32 s39, s37, -1
	s_cmp_eq_u32 s73, 40
	s_cselect_b32 s41, s7, s39
	s_cselect_b32 s40, s6, s38
	s_cselect_b32 s39, s9, s72
	s_cselect_b32 s38, s8, s71
	s_add_i32 m0, s49, 0xc000
	ds_read_b128 v[144:147], v174
	ds_read_b128 v[164:167], v174 offset:1024
	ds_read_b128 v[176:179], v174 offset:2048
	ds_read_b128 v[182:185], v174 offset:3072
	ds_read_b128 v[186:189], v174 offset:4096
	ds_read_b128 v[190:193], v174 offset:5120
	ds_read_b128 v[194:197], v174 offset:6144
	global_load_lds_dwordx4 v156, s[36:37]
	s_add_i32 m0, s49, 0xe000
	ds_read_b128 v[198:201], v174 offset:7168
	global_load_lds_dwordx4 v158, s[36:37]
	s_waitcnt lgkmcnt(8)
	s_barrier
	s_waitcnt lgkmcnt(7)
	v_mfma_f32_16x16x32_bf16 v[124:127], v[128:131], v[144:147], 0
	v_mfma_f32_16x16x32_bf16 v[120:123], v[136:139], v[144:147], 0
	s_waitcnt lgkmcnt(5)
	v_mfma_f32_16x16x32_bf16 v[116:119], v[128:131], v[176:179], 0
	v_mfma_f32_16x16x32_bf16 v[108:111], v[136:139], v[176:179], 0
	s_waitcnt lgkmcnt(3)
	v_mfma_f32_16x16x32_bf16 v[92:95], v[128:131], v[186:189], 0
	v_mfma_f32_16x16x32_bf16 v[88:91], v[136:139], v[186:189], 0
	s_waitcnt lgkmcnt(1)
	v_mfma_f32_16x16x32_bf16 v[76:79], v[128:131], v[194:197], 0
	v_mfma_f32_16x16x32_bf16 v[72:75], v[136:139], v[194:197], 0
	v_mfma_f32_16x16x32_bf16 v[124:127], v[132:135], v[164:167], v[124:127]
	v_mfma_f32_16x16x32_bf16 v[120:123], v[140:143], v[164:167], v[120:123]
	v_mfma_f32_16x16x32_bf16 v[116:119], v[132:135], v[182:185], v[116:119]
	v_mfma_f32_16x16x32_bf16 v[108:111], v[140:143], v[182:185], v[108:111]
	v_mfma_f32_16x16x32_bf16 v[92:95], v[132:135], v[190:193], v[92:95]
	v_mfma_f32_16x16x32_bf16 v[88:91], v[140:143], v[190:193], v[88:91]
	s_add_i32 s74, s59, s48
	s_add_u32 s86, s38, s16
	s_waitcnt lgkmcnt(0)
	v_mfma_f32_16x16x32_bf16 v[76:79], v[132:135], v[198:201], v[76:79]
	s_addc_u32 s87, s39, s17
	s_mov_b32 m0, s74
	v_mfma_f32_16x16x32_bf16 v[72:75], v[140:143], v[198:201], v[72:75]
	s_barrier
	ds_read_b128 v[202:205], v175
	ds_read_b128 v[206:209], v175 offset:1024
	ds_read_b128 v[210:213], v175 offset:2048
	global_load_lds_dwordx4 v150, s[38:39]
	s_add_i32 m0, s74, 0x2000
	ds_read_b128 v[214:217], v175 offset:3072
	global_load_lds_dwordx4 v154, s[38:39]
	s_barrier
	s_waitcnt lgkmcnt(3)
	v_mfma_f32_16x16x32_bf16 v[112:115], v[202:205], v[144:147], 0
	s_waitcnt lgkmcnt(1)
	v_mfma_f32_16x16x32_bf16 v[104:107], v[210:213], v[144:147], 0
	v_mfma_f32_16x16x32_bf16 v[100:103], v[202:205], v[176:179], 0
	v_mfma_f32_16x16x32_bf16 v[96:99], v[210:213], v[176:179], 0
	v_mfma_f32_16x16x32_bf16 v[84:87], v[202:205], v[186:189], 0
	v_mfma_f32_16x16x32_bf16 v[80:83], v[210:213], v[186:189], 0
	v_mfma_f32_16x16x32_bf16 v[68:71], v[202:205], v[194:197], 0
	v_mfma_f32_16x16x32_bf16 v[64:67], v[210:213], v[194:197], 0
	v_mfma_f32_16x16x32_bf16 v[112:115], v[206:209], v[164:167], v[112:115]
	s_waitcnt lgkmcnt(0)
	v_mfma_f32_16x16x32_bf16 v[104:107], v[214:217], v[164:167], v[104:107]
	v_mfma_f32_16x16x32_bf16 v[100:103], v[206:209], v[182:185], v[100:103]
	v_mfma_f32_16x16x32_bf16 v[96:99], v[214:217], v[182:185], v[96:99]
	v_mfma_f32_16x16x32_bf16 v[84:87], v[206:209], v[190:193], v[84:87]
	v_mfma_f32_16x16x32_bf16 v[80:83], v[214:217], v[190:193], v[80:83]
	s_mov_b32 m0, s49
	s_add_u32 s88, s40, s16
	v_mfma_f32_16x16x32_bf16 v[68:71], v[206:209], v[198:201], v[68:71]
	s_addc_u32 s89, s41, s17
	v_mfma_f32_16x16x32_bf16 v[64:67], v[214:217], v[198:201], v[64:67]
	s_barrier
	ds_read_b128 v[144:147], v174 offset:16384
	ds_read_b128 v[164:167], v174 offset:17408
	ds_read_b128 v[176:179], v174 offset:18432
	ds_read_b128 v[182:185], v174 offset:19456
	ds_read_b128 v[186:189], v174 offset:20480
	ds_read_b128 v[190:193], v174 offset:21504
	ds_read_b128 v[194:197], v174 offset:22528
	global_load_lds_dwordx4 v148, s[40:41]
	s_mov_b32 m0, s50
	ds_read_b128 v[198:201], v174 offset:23552
	global_load_lds_dwordx4 v152, s[40:41]
	s_barrier
	s_waitcnt lgkmcnt(7)
	v_mfma_f32_16x16x32_bf16 v[60:63], v[128:131], v[144:147], 0
	v_mfma_f32_16x16x32_bf16 v[56:59], v[136:139], v[144:147], 0
	s_waitcnt lgkmcnt(5)
	v_mfma_f32_16x16x32_bf16 v[44:47], v[128:131], v[176:179], 0
	v_mfma_f32_16x16x32_bf16 v[40:43], v[136:139], v[176:179], 0
	s_waitcnt lgkmcnt(3)
	v_mfma_f32_16x16x32_bf16 v[36:39], v[128:131], v[186:189], 0
	v_mfma_f32_16x16x32_bf16 v[32:35], v[136:139], v[186:189], 0
	s_waitcnt lgkmcnt(1)
	v_mfma_f32_16x16x32_bf16 v[20:23], v[128:131], v[194:197], 0
	v_mfma_f32_16x16x32_bf16 v[16:19], v[136:139], v[194:197], 0
	v_mfma_f32_16x16x32_bf16 v[60:63], v[132:135], v[164:167], v[60:63]
	v_mfma_f32_16x16x32_bf16 v[56:59], v[140:143], v[164:167], v[56:59]
	v_mfma_f32_16x16x32_bf16 v[44:47], v[132:135], v[182:185], v[44:47]
	v_mfma_f32_16x16x32_bf16 v[40:43], v[140:143], v[182:185], v[40:43]
	v_mfma_f32_16x16x32_bf16 v[36:39], v[132:135], v[190:193], v[36:39]
	v_mfma_f32_16x16x32_bf16 v[32:35], v[140:143], v[190:193], v[32:35]
	s_add_u32 s74, s38, 0xb0000
	s_addc_u32 s75, s39, 0
	s_waitcnt lgkmcnt(0)
	v_mfma_f32_16x16x32_bf16 v[20:23], v[132:135], v[198:201], v[20:23]
	s_add_i32 s76, s60, s48
	s_mov_b32 m0, s76
	v_mfma_f32_16x16x32_bf16 v[16:19], v[140:143], v[198:201], v[16:19]
	s_barrier
	global_load_lds_dwordx4 v150, s[74:75]
	s_add_i32 m0, s76, 0x2000
	s_waitcnt vmcnt(5)
	global_load_lds_dwordx4 v154, s[74:75]
	s_barrier
; #define PG8_STAGE(bufoff, gbase, voff) do { _Pragma("unroll") for (int _i = 0; _i < 2; ++_i) \
;         __builtin_amdgcn_global_load_lds((const unsigned*)((const char*)(gbase) + (voff)[_i]), (LAS unsigned*)(lds + (bufoff) + ldsw + _i * 8192), 16, 0, 0); } while (0)
; #define PG8_LDA(dst, b, h) do { _Pragma("unroll") for (int m = 0; m < 4; ++m) _Pragma("unroll") for (int k = 0; k < 2; ++k) dst[m][k] = *(const LAS bf16x8*)(lds + PG8_SA(b, h) + aoff + m * 2048 + k * 1024); } while (0)
; #define PG8_LDB(dst, b, h) do { _Pragma("unroll") for (int n = 0; n < 2; ++n) _Pragma("unroll") for (int k = 0; k < 2; ++k) dst[n][k] = *(const LAS bf16x8*)(lds + PG8_SB(b, h) + boff + n * 2048 + k * 1024); } while (0)
; #define PG8_MMA(ai, bj, At, Bt) do { __builtin_amdgcn_s_setprio(1); _Pragma("unroll") for (int m = 0; m < 4; ++m) _Pragma("unroll") for (int n = 0; n < 2; ++n) _Pragma("unroll") for (int k = 0; k < 2; ++k) \
;         acc[ai][bj][m][n] = __builtin_amdgcn_mfma_f32_16x16x32_bf16(Bt[n][k], At[m][k], acc[ai][bj][m][n], 0, 0, 0); __builtin_amdgcn_s_setprio(0); } while (0)
; #define PG8_WAIT_V(n) asm volatile("s_waitcnt vmcnt(" #n ")" ::: "memory")
; #define PG8_WAIT_L(n) asm volatile("s_waitcnt lgkmcnt(" #n ")" ::: "memory")
; #define PG8_BAR __builtin_amdgcn_s_barrier()
; #define PG8_SCHED __builtin_amdgcn_sched_barrier(0)
; template <class Epi>
; DI void gemm_phase(LAS unsigned char* lds, const Gemm g, const StaticOrder& S, const Epi& E) {
;     ...
;             PG8_WAIT_V(6); PG8_BAR; PG8_MMA(1, 1, At, B1); PG8_BAR;
;             PG8_LDB(B0, 1, 0); PG8_SCHED; PG8_LDA(At, 1, 0); PG8_STAGE(PG8_SA(0, 1), a2 + hstep, voffA);
;             PG8_WAIT_L(8); PG8_BAR; PG8_WAIT_L(0); PG8_MMA(0, 0, At, B0); PG8_BAR; PG8_SCHED;
;             PG8_LDB(B1, 1, 1); PG8_STAGE(PG8_SB(1, 0), b3, voffB);
;             PG8_BAR; PG8_WAIT_L(0); PG8_MMA(0, 1, At, B1); PG8_BAR;
;             PG8_LDA(At, 1, 1); PG8_STAGE(PG8_SA(1, 0), a3, voffA);
;             PG8_BAR; PG8_WAIT_L(0); PG8_MMA(1, 0, At, B0); PG8_BAR; PG8_SCHED;
;             PG8_STAGE(PG8_SB(1, 1), b3 + hstep, voffB);
;             PG8_WAIT_V(6); PG8_BAR; PG8_MMA(1, 1, At, B1); PG8_BAR;
	v_mfma_f32_16x16x32_bf16 v[52:55], v[202:205], v[144:147], 0
	v_mfma_f32_16x16x32_bf16 v[48:51], v[210:213], v[144:147], 0
	v_mfma_f32_16x16x32_bf16 v[28:31], v[202:205], v[176:179], 0
	v_mfma_f32_16x16x32_bf16 v[24:27], v[210:213], v[176:179], 0
	v_mfma_f32_16x16x32_bf16 v[12:15], v[202:205], v[186:189], 0
	v_mfma_f32_16x16x32_bf16 v[8:11], v[210:213], v[186:189], 0
	v_mfma_f32_16x16x32_bf16 v[4:7], v[202:205], v[194:197], 0
	v_mfma_f32_16x16x32_bf16 v[0:3], v[210:213], v[194:197], 0
	v_mfma_f32_16x16x32_bf16 v[52:55], v[206:209], v[164:167], v[52:55]
	v_mfma_f32_16x16x32_bf16 v[48:51], v[214:217], v[164:167], v[48:51]
	v_mfma_f32_16x16x32_bf16 v[28:31], v[206:209], v[182:185], v[28:31]
	v_mfma_f32_16x16x32_bf16 v[24:27], v[214:217], v[182:185], v[24:27]
	v_mfma_f32_16x16x32_bf16 v[12:15], v[206:209], v[190:193], v[12:15]
	v_mfma_f32_16x16x32_bf16 v[8:11], v[214:217], v[190:193], v[8:11]
	v_mfma_f32_16x16x32_bf16 v[4:7], v[206:209], v[198:201], v[4:7]
	s_add_i32 s74, 0, 0x18000
	v_mfma_f32_16x16x32_bf16 v[0:3], v[214:217], v[198:201], v[0:3]
	s_barrier
	ds_read_b128 v[128:131], v253
	ds_read_b128 v[132:135], v253 offset:1024
	ds_read_b128 v[136:139], v253 offset:2048
	ds_read_b128 v[140:143], v253 offset:3072
	s_add_u32 s40, s40, 0xb0000
	s_addc_u32 s41, s41, 0
	s_mov_b32 m0, s51
	ds_read_b128 v[144:147], v174 offset:32768
	ds_read_b128 v[164:167], v174 offset:33792
	ds_read_b128 v[176:179], v174 offset:34816
	ds_read_b128 v[182:185], v174 offset:35840
	ds_read_b128 v[186:189], v174 offset:36864
	ds_read_b128 v[190:193], v174 offset:37888
	ds_read_b128 v[194:197], v174 offset:38912
	global_load_lds_dwordx4 v148, s[40:41]
	s_mov_b32 m0, s52
	ds_read_b128 v[198:201], v174 offset:39936
	global_load_lds_dwordx4 v152, s[40:41]
	s_waitcnt lgkmcnt(8)
	s_barrier
	s_waitcnt lgkmcnt(7)
	v_mfma_f32_16x16x32_bf16 v[124:127], v[128:131], v[144:147], v[124:127]
	v_mfma_f32_16x16x32_bf16 v[120:123], v[136:139], v[144:147], v[120:123]
	s_waitcnt lgkmcnt(5)
	v_mfma_f32_16x16x32_bf16 v[116:119], v[128:131], v[176:179], v[116:119]
	v_mfma_f32_16x16x32_bf16 v[108:111], v[136:139], v[176:179], v[108:111]
	s_waitcnt lgkmcnt(3)
	v_mfma_f32_16x16x32_bf16 v[92:95], v[128:131], v[186:189], v[92:95]
	v_mfma_f32_16x16x32_bf16 v[88:91], v[136:139], v[186:189], v[88:91]
	s_waitcnt lgkmcnt(1)
	v_mfma_f32_16x16x32_bf16 v[76:79], v[128:131], v[194:197], v[76:79]
	v_mfma_f32_16x16x32_bf16 v[72:75], v[136:139], v[194:197], v[72:75]
	v_mfma_f32_16x16x32_bf16 v[124:127], v[132:135], v[164:167], v[124:127]
	v_mfma_f32_16x16x32_bf16 v[120:123], v[140:143], v[164:167], v[120:123]
	v_mfma_f32_16x16x32_bf16 v[116:119], v[132:135], v[182:185], v[116:119]
	v_mfma_f32_16x16x32_bf16 v[108:111], v[140:143], v[182:185], v[108:111]
	v_mfma_f32_16x16x32_bf16 v[92:95], v[132:135], v[190:193], v[92:95]
	v_mfma_f32_16x16x32_bf16 v[88:91], v[140:143], v[190:193], v[88:91]
	s_add_i32 s40, 0, 0x1c000
	s_add_i32 s41, s74, s48
	s_waitcnt lgkmcnt(0)
	v_mfma_f32_16x16x32_bf16 v[76:79], v[132:135], v[198:201], v[76:79]
	s_mov_b32 m0, s41
	v_mfma_f32_16x16x32_bf16 v[72:75], v[140:143], v[198:201], v[72:75]
	s_barrier
	ds_read_b128 v[202:205], v252
	ds_read_b128 v[206:209], v252 offset:1024
	ds_read_b128 v[210:213], v252 offset:2048
	global_load_lds_dwordx4 v150, s[86:87]
	s_add_i32 m0, s41, 0x2000
	ds_read_b128 v[214:217], v252 offset:3072
	global_load_lds_dwordx4 v154, s[86:87]
	s_barrier
	s_waitcnt lgkmcnt(3)
	v_mfma_f32_16x16x32_bf16 v[112:115], v[202:205], v[144:147], v[112:115]
	s_waitcnt lgkmcnt(1)
	v_mfma_f32_16x16x32_bf16 v[104:107], v[210:213], v[144:147], v[104:107]
	v_mfma_f32_16x16x32_bf16 v[100:103], v[202:205], v[176:179], v[100:103]
	v_mfma_f32_16x16x32_bf16 v[96:99], v[210:213], v[176:179], v[96:99]
	v_mfma_f32_16x16x32_bf16 v[84:87], v[202:205], v[186:189], v[84:87]
	v_mfma_f32_16x16x32_bf16 v[80:83], v[210:213], v[186:189], v[80:83]
	v_mfma_f32_16x16x32_bf16 v[68:71], v[202:205], v[194:197], v[68:71]
	v_mfma_f32_16x16x32_bf16 v[64:67], v[210:213], v[194:197], v[64:67]
	v_mfma_f32_16x16x32_bf16 v[112:115], v[206:209], v[164:167], v[112:115]
	s_waitcnt lgkmcnt(0)
	v_mfma_f32_16x16x32_bf16 v[104:107], v[214:217], v[164:167], v[104:107]
	v_mfma_f32_16x16x32_bf16 v[100:103], v[206:209], v[182:185], v[100:103]
	v_mfma_f32_16x16x32_bf16 v[96:99], v[214:217], v[182:185], v[96:99]
	v_mfma_f32_16x16x32_bf16 v[84:87], v[206:209], v[190:193], v[84:87]
	v_mfma_f32_16x16x32_bf16 v[80:83], v[214:217], v[190:193], v[80:83]
	v_mfma_f32_16x16x32_bf16 v[68:71], v[206:209], v[198:201], v[68:71]
	s_mov_b32 m0, s56
	v_mfma_f32_16x16x32_bf16 v[64:67], v[214:217], v[198:201], v[64:67]
	s_barrier
	ds_read_b128 v[144:147], v174 offset:49152
	ds_read_b128 v[164:167], v174 offset:50176
	ds_read_b128 v[176:179], v174 offset:51200
	ds_read_b128 v[182:185], v174 offset:52224
	ds_read_b128 v[186:189], v174 offset:53248
	ds_read_b128 v[190:193], v174 offset:54272
	ds_read_b128 v[194:197], v174 offset:55296
	global_load_lds_dwordx4 v148, s[88:89]
	s_mov_b32 m0, s57
	ds_read_b128 v[198:201], v174 offset:56320
	global_load_lds_dwordx4 v152, s[88:89]
	s_barrier
; #define PG8_STAGE(bufoff, gbase, voff) do { _Pragma("unroll") for (int _i = 0; _i < 2; ++_i) \
;         __builtin_amdgcn_global_load_lds((const unsigned*)((const char*)(gbase) + (voff)[_i]), (LAS unsigned*)(lds + (bufoff) + ldsw + _i * 8192), 16, 0, 0); } while (0)
; #define PG8_LDA(dst, b, h) do { _Pragma("unroll") for (int m = 0; m < 4; ++m) _Pragma("unroll") for (int k = 0; k < 2; ++k) dst[m][k] = *(const LAS bf16x8*)(lds + PG8_SA(b, h) + aoff + m * 2048 + k * 1024); } while (0)
; #define PG8_LDB(dst, b, h) do { _Pragma("unroll") for (int n = 0; n < 2; ++n) _Pragma("unroll") for (int k = 0; k < 2; ++k) dst[n][k] = *(const LAS bf16x8*)(lds + PG8_SB(b, h) + boff + n * 2048 + k * 1024); } while (0)
; #define PG8_MMA(ai, bj, At, Bt) do { __builtin_amdgcn_s_setprio(1); _Pragma("unroll") for (int m = 0; m < 4; ++m) _Pragma("unroll") for (int n = 0; n < 2; ++n) _Pragma("unroll") for (int k = 0; k < 2; ++k) \
;         acc[ai][bj][m][n] = __builtin_amdgcn_mfma_f32_16x16x32_bf16(Bt[n][k], At[m][k], acc[ai][bj][m][n], 0, 0, 0); __builtin_amdgcn_s_setprio(0); } while (0)
; #define PG8_WAIT_V(n) asm volatile("s_waitcnt vmcnt(" #n ")" ::: "memory")
; template <class Epi>
; DI void gemm_phase(LAS unsigned char* lds, const Gemm g, const StaticOrder& S, const Epi& E) {
;     ...
;             PG8_LDB(B0, 0, 0); PG8_SCHED; PG8_LDA(At, 0, 0); PG8_STAGE(PG8_SA(1, 1), a1 + hstep, voffA);
;             PG8_WAIT_L(8); PG8_BAR; PG8_WAIT_L(0); PG8_MMA(0, 0, At, B0); PG8_BAR; PG8_SCHED;
;             PG8_LDB(B1, 0, 1); PG8_STAGE(PG8_SB(0, 0), b2, voffB);
;             PG8_BAR; PG8_WAIT_L(0); PG8_MMA(0, 1, At, B1); PG8_BAR;
;             PG8_LDA(At, 0, 1); PG8_STAGE(PG8_SA(0, 0), a2, voffA);
;     ...
;             PG8_WAIT_V(6); PG8_BAR; PG8_MMA(1, 1, At, B1); PG8_BAR;
;             PG8_LDB(B0, 1, 0); PG8_SCHED; PG8_LDA(At, 1, 0); PG8_STAGE(PG8_SA(0, 1), a2 + hstep, voffA);
;             PG8_WAIT_L(8); PG8_BAR; PG8_WAIT_L(0); PG8_MMA(0, 0, At, B0); PG8_BAR; PG8_SCHED;
;             PG8_LDB(B1, 1, 1); PG8_STAGE(PG8_SB(1, 0), b3, voffB);
;             PG8_BAR; PG8_WAIT_L(0); PG8_MMA(0, 1, At, B1); PG8_BAR;
;             PG8_LDA(At, 1, 1); PG8_STAGE(PG8_SA(1, 0), a3, voffA);
;             PG8_BAR; PG8_WAIT_L(0); PG8_MMA(1, 0, At, B0); PG8_BAR; PG8_SCHED;
;             PG8_STAGE(PG8_SB(1, 1), b3 + hstep, voffB);
;             PG8_WAIT_V(6); PG8_BAR; PG8_MMA(1, 1, At, B1); PG8_BAR;
	s_waitcnt lgkmcnt(7)
	v_mfma_f32_16x16x32_bf16 v[60:63], v[128:131], v[144:147], v[60:63]
	v_mfma_f32_16x16x32_bf16 v[56:59], v[136:139], v[144:147], v[56:59]
	s_waitcnt lgkmcnt(5)
	v_mfma_f32_16x16x32_bf16 v[44:47], v[128:131], v[176:179], v[44:47]
	v_mfma_f32_16x16x32_bf16 v[40:43], v[136:139], v[176:179], v[40:43]
	s_waitcnt lgkmcnt(3)
	v_mfma_f32_16x16x32_bf16 v[36:39], v[128:131], v[186:189], v[36:39]
	v_mfma_f32_16x16x32_bf16 v[32:35], v[136:139], v[186:189], v[32:35]
	s_waitcnt lgkmcnt(1)
	v_mfma_f32_16x16x32_bf16 v[20:23], v[128:131], v[194:197], v[20:23]
	v_mfma_f32_16x16x32_bf16 v[16:19], v[136:139], v[194:197], v[16:19]
	v_mfma_f32_16x16x32_bf16 v[60:63], v[132:135], v[164:167], v[60:63]
	v_mfma_f32_16x16x32_bf16 v[56:59], v[140:143], v[164:167], v[56:59]
	v_mfma_f32_16x16x32_bf16 v[44:47], v[132:135], v[182:185], v[44:47]
	v_mfma_f32_16x16x32_bf16 v[40:43], v[140:143], v[182:185], v[40:43]
	v_mfma_f32_16x16x32_bf16 v[36:39], v[132:135], v[190:193], v[36:39]
	v_mfma_f32_16x16x32_bf16 v[32:35], v[140:143], v[190:193], v[32:35]
	s_add_u32 s38, s38, 0xb0080
	s_addc_u32 s39, s39, 0
	s_waitcnt lgkmcnt(0)
	v_mfma_f32_16x16x32_bf16 v[20:23], v[132:135], v[198:201], v[20:23]
	s_add_i32 s40, s40, s48
	s_mov_b32 m0, s40
	v_mfma_f32_16x16x32_bf16 v[16:19], v[140:143], v[198:201], v[16:19]
	s_barrier
	global_load_lds_dwordx4 v150, s[38:39]
	s_add_i32 m0, s40, 0x2000
	s_waitcnt vmcnt(5)
	global_load_lds_dwordx4 v154, s[38:39]
	s_barrier
	v_mfma_f32_16x16x32_bf16 v[52:55], v[202:205], v[144:147], v[52:55]
	v_mfma_f32_16x16x32_bf16 v[48:51], v[210:213], v[144:147], v[48:51]
	v_mfma_f32_16x16x32_bf16 v[28:31], v[202:205], v[176:179], v[28:31]
	v_mfma_f32_16x16x32_bf16 v[24:27], v[210:213], v[176:179], v[24:27]
	v_mfma_f32_16x16x32_bf16 v[12:15], v[202:205], v[186:189], v[12:15]
	v_mfma_f32_16x16x32_bf16 v[8:11], v[210:213], v[186:189], v[8:11]
	v_mfma_f32_16x16x32_bf16 v[4:7], v[202:205], v[194:197], v[4:7]
	v_mfma_f32_16x16x32_bf16 v[0:3], v[210:213], v[194:197], v[0:3]
	v_mfma_f32_16x16x32_bf16 v[52:55], v[206:209], v[164:167], v[52:55]
	s_add_i32 s73, s73, 2
	s_add_u32 s36, s36, 0x100
	v_mfma_f32_16x16x32_bf16 v[48:51], v[214:217], v[164:167], v[48:51]
	s_addc_u32 s37, s37, 0
	s_add_u32 s71, s71, 0x100
	v_mfma_f32_16x16x32_bf16 v[28:31], v[206:209], v[182:185], v[28:31]
	s_addc_u32 s72, s72, 0
	s_add_u32 s38, s36, 0xfff50080
	v_mfma_f32_16x16x32_bf16 v[24:27], v[214:217], v[182:185], v[24:27]
	s_addc_u32 s39, s37, -1
	s_cmp_eq_u32 s73, 40
	v_mfma_f32_16x16x32_bf16 v[12:15], v[206:209], v[190:193], v[12:15]
	s_cselect_b32 s41, s7, s39
	s_cselect_b32 s40, s6, s38
	v_mfma_f32_16x16x32_bf16 v[8:11], v[214:217], v[190:193], v[8:11]
	s_cselect_b32 s39, s9, s72
	s_cselect_b32 s38, s8, s71
	v_mfma_f32_16x16x32_bf16 v[4:7], v[206:209], v[198:201], v[4:7]
	s_add_i32 m0, s49, 0xc000
	v_mfma_f32_16x16x32_bf16 v[0:3], v[214:217], v[198:201], v[0:3]
	s_cmp_gt_u32 s73, 41
	s_barrier
.LBB0_928:
	ds_read_b128 v[128:131], v173
	ds_read_b128 v[132:135], v173 offset:1024
	ds_read_b128 v[136:139], v173 offset:2048
	ds_read_b128 v[140:143], v173 offset:3072
	ds_read_b128 v[144:147], v174
	ds_read_b128 v[164:167], v174 offset:1024
	ds_read_b128 v[176:179], v174 offset:2048
	ds_read_b128 v[182:185], v174 offset:3072
	ds_read_b128 v[186:189], v174 offset:4096
	ds_read_b128 v[190:193], v174 offset:5120
	ds_read_b128 v[194:197], v174 offset:6144
	global_load_lds_dwordx4 v156, s[36:37]
	s_add_i32 m0, s49, 0xe000
	ds_read_b128 v[198:201], v174 offset:7168
	global_load_lds_dwordx4 v158, s[36:37]
	s_waitcnt lgkmcnt(8)
	s_barrier
	s_waitcnt lgkmcnt(7)
	v_mfma_f32_16x16x32_bf16 v[124:127], v[128:131], v[144:147], v[124:127]
	v_mfma_f32_16x16x32_bf16 v[120:123], v[136:139], v[144:147], v[120:123]
	s_waitcnt lgkmcnt(5)
	v_mfma_f32_16x16x32_bf16 v[116:119], v[128:131], v[176:179], v[116:119]
	v_mfma_f32_16x16x32_bf16 v[108:111], v[136:139], v[176:179], v[108:111]
	s_waitcnt lgkmcnt(3)
	v_mfma_f32_16x16x32_bf16 v[92:95], v[128:131], v[186:189], v[92:95]
	v_mfma_f32_16x16x32_bf16 v[88:91], v[136:139], v[186:189], v[88:91]
	s_waitcnt lgkmcnt(1)
	v_mfma_f32_16x16x32_bf16 v[76:79], v[128:131], v[194:197], v[76:79]
	v_mfma_f32_16x16x32_bf16 v[72:75], v[136:139], v[194:197], v[72:75]
	v_mfma_f32_16x16x32_bf16 v[124:127], v[132:135], v[164:167], v[124:127]
	v_mfma_f32_16x16x32_bf16 v[120:123], v[140:143], v[164:167], v[120:123]
	v_mfma_f32_16x16x32_bf16 v[116:119], v[132:135], v[182:185], v[116:119]
	v_mfma_f32_16x16x32_bf16 v[108:111], v[140:143], v[182:185], v[108:111]
	v_mfma_f32_16x16x32_bf16 v[92:95], v[132:135], v[190:193], v[92:95]
	v_mfma_f32_16x16x32_bf16 v[88:91], v[140:143], v[190:193], v[88:91]
	s_add_i32 s74, s59, s48
	s_add_u32 s86, s38, s16
	s_waitcnt lgkmcnt(0)
	v_mfma_f32_16x16x32_bf16 v[76:79], v[132:135], v[198:201], v[76:79]
	s_addc_u32 s87, s39, s17
	s_mov_b32 m0, s74
	v_mfma_f32_16x16x32_bf16 v[72:75], v[140:143], v[198:201], v[72:75]
	s_barrier
	ds_read_b128 v[202:205], v175
	ds_read_b128 v[206:209], v175 offset:1024
	ds_read_b128 v[210:213], v175 offset:2048
	global_load_lds_dwordx4 v150, s[38:39]
	s_add_i32 m0, s74, 0x2000
	ds_read_b128 v[214:217], v175 offset:3072
	global_load_lds_dwordx4 v154, s[38:39]
	s_barrier
; #define PG8_STAGE(bufoff, gbase, voff) do { _Pragma("unroll") for (int _i = 0; _i < 2; ++_i) \
;         __builtin_amdgcn_global_load_lds((const unsigned*)((const char*)(gbase) + (voff)[_i]), (LAS unsigned*)(lds + (bufoff) + ldsw + _i * 8192), 16, 0, 0); } while (0)
; #define PG8_LDA(dst, b, h) do { _Pragma("unroll") for (int m = 0; m < 4; ++m) _Pragma("unroll") for (int k = 0; k < 2; ++k) dst[m][k] = *(const LAS bf16x8*)(lds + PG8_SA(b, h) + aoff + m * 2048 + k * 1024); } while (0)
; #define PG8_LDB(dst, b, h) do { _Pragma("unroll") for (int n = 0; n < 2; ++n) _Pragma("unroll") for (int k = 0; k < 2; ++k) dst[n][k] = *(const LAS bf16x8*)(lds + PG8_SB(b, h) + boff + n * 2048 + k * 1024); } while (0)
; #define PG8_MMA(ai, bj, At, Bt) do { __builtin_amdgcn_s_setprio(1); _Pragma("unroll") for (int m = 0; m < 4; ++m) _Pragma("unroll") for (int n = 0; n < 2; ++n) _Pragma("unroll") for (int k = 0; k < 2; ++k) \
;         acc[ai][bj][m][n] = __builtin_amdgcn_mfma_f32_16x16x32_bf16(Bt[n][k], At[m][k], acc[ai][bj][m][n], 0, 0, 0); __builtin_amdgcn_s_setprio(0); } while (0)
; #define PG8_WAIT_V(n) asm volatile("s_waitcnt vmcnt(" #n ")" ::: "memory")
; #define PG8_WAIT_L(n) asm volatile("s_waitcnt lgkmcnt(" #n ")" ::: "memory")
; template <class Epi>
; DI void gemm_phase(LAS unsigned char* lds, const Gemm g, const StaticOrder& S, const Epi& E) {
;     ...
;             PG8_LDB(B1, 0, 1); PG8_STAGE(PG8_SB(0, 0), b2, voffB);
;             PG8_BAR; PG8_WAIT_L(0); PG8_MMA(0, 1, At, B1); PG8_BAR;
;             PG8_LDA(At, 0, 1); PG8_STAGE(PG8_SA(0, 0), a2, voffA);
;             PG8_BAR; PG8_WAIT_L(0); PG8_MMA(1, 0, At, B0); PG8_BAR; PG8_SCHED;
;             PG8_STAGE(PG8_SB(0, 1), b2 + hstep, voffB);
;             PG8_WAIT_V(6); PG8_BAR; PG8_MMA(1, 1, At, B1); PG8_BAR;
;             PG8_LDB(B0, 1, 0); PG8_SCHED; PG8_LDA(At, 1, 0); PG8_STAGE(PG8_SA(0, 1), a2 + hstep, voffA);
;             PG8_WAIT_L(8); PG8_BAR; PG8_WAIT_L(0); PG8_MMA(0, 0, At, B0); PG8_BAR; PG8_SCHED;
;             PG8_LDB(B1, 1, 1); PG8_STAGE(PG8_SB(1, 0), b3, voffB);
;             PG8_BAR; PG8_WAIT_L(0); PG8_MMA(0, 1, At, B1); PG8_BAR;
;             PG8_LDA(At, 1, 1); PG8_STAGE(PG8_SA(1, 0), a3, voffA);
;             PG8_BAR; PG8_WAIT_L(0); PG8_MMA(1, 0, At, B0); PG8_BAR; PG8_SCHED;
;             PG8_STAGE(PG8_SB(1, 1), b3 + hstep, voffB);
;             PG8_WAIT_V(6); PG8_BAR; PG8_MMA(1, 1, At, B1); PG8_BAR;
	s_waitcnt lgkmcnt(3)
	v_mfma_f32_16x16x32_bf16 v[112:115], v[202:205], v[144:147], v[112:115]
	s_waitcnt lgkmcnt(1)
	v_mfma_f32_16x16x32_bf16 v[104:107], v[210:213], v[144:147], v[104:107]
	v_mfma_f32_16x16x32_bf16 v[100:103], v[202:205], v[176:179], v[100:103]
	v_mfma_f32_16x16x32_bf16 v[96:99], v[210:213], v[176:179], v[96:99]
	v_mfma_f32_16x16x32_bf16 v[84:87], v[202:205], v[186:189], v[84:87]
	v_mfma_f32_16x16x32_bf16 v[80:83], v[210:213], v[186:189], v[80:83]
	v_mfma_f32_16x16x32_bf16 v[68:71], v[202:205], v[194:197], v[68:71]
	v_mfma_f32_16x16x32_bf16 v[64:67], v[210:213], v[194:197], v[64:67]
	v_mfma_f32_16x16x32_bf16 v[112:115], v[206:209], v[164:167], v[112:115]
	s_waitcnt lgkmcnt(0)
	v_mfma_f32_16x16x32_bf16 v[104:107], v[214:217], v[164:167], v[104:107]
	v_mfma_f32_16x16x32_bf16 v[100:103], v[206:209], v[182:185], v[100:103]
	v_mfma_f32_16x16x32_bf16 v[96:99], v[214:217], v[182:185], v[96:99]
	v_mfma_f32_16x16x32_bf16 v[84:87], v[206:209], v[190:193], v[84:87]
	v_mfma_f32_16x16x32_bf16 v[80:83], v[214:217], v[190:193], v[80:83]
	s_mov_b32 m0, s49
	s_add_u32 s88, s40, s16
	v_mfma_f32_16x16x32_bf16 v[68:71], v[206:209], v[198:201], v[68:71]
	s_addc_u32 s89, s41, s17
	v_mfma_f32_16x16x32_bf16 v[64:67], v[214:217], v[198:201], v[64:67]
	s_barrier
	ds_read_b128 v[144:147], v174 offset:16384
	ds_read_b128 v[164:167], v174 offset:17408
	ds_read_b128 v[176:179], v174 offset:18432
	ds_read_b128 v[182:185], v174 offset:19456
	ds_read_b128 v[186:189], v174 offset:20480
	ds_read_b128 v[190:193], v174 offset:21504
	ds_read_b128 v[194:197], v174 offset:22528
	global_load_lds_dwordx4 v148, s[40:41]
	s_mov_b32 m0, s50
	ds_read_b128 v[198:201], v174 offset:23552
	global_load_lds_dwordx4 v152, s[40:41]
	s_barrier
	s_waitcnt lgkmcnt(7)
	v_mfma_f32_16x16x32_bf16 v[60:63], v[128:131], v[144:147], v[60:63]
	v_mfma_f32_16x16x32_bf16 v[56:59], v[136:139], v[144:147], v[56:59]
	s_waitcnt lgkmcnt(5)
	v_mfma_f32_16x16x32_bf16 v[44:47], v[128:131], v[176:179], v[44:47]
	v_mfma_f32_16x16x32_bf16 v[40:43], v[136:139], v[176:179], v[40:43]
	s_waitcnt lgkmcnt(3)
	v_mfma_f32_16x16x32_bf16 v[36:39], v[128:131], v[186:189], v[36:39]
	v_mfma_f32_16x16x32_bf16 v[32:35], v[136:139], v[186:189], v[32:35]
	s_waitcnt lgkmcnt(1)
	v_mfma_f32_16x16x32_bf16 v[20:23], v[128:131], v[194:197], v[20:23]
	v_mfma_f32_16x16x32_bf16 v[16:19], v[136:139], v[194:197], v[16:19]
	v_mfma_f32_16x16x32_bf16 v[60:63], v[132:135], v[164:167], v[60:63]
	v_mfma_f32_16x16x32_bf16 v[56:59], v[140:143], v[164:167], v[56:59]
	v_mfma_f32_16x16x32_bf16 v[44:47], v[132:135], v[182:185], v[44:47]
	v_mfma_f32_16x16x32_bf16 v[40:43], v[140:143], v[182:185], v[40:43]
	v_mfma_f32_16x16x32_bf16 v[36:39], v[132:135], v[190:193], v[36:39]
	v_mfma_f32_16x16x32_bf16 v[32:35], v[140:143], v[190:193], v[32:35]
	s_add_u32 s74, s38, 0xb0000
	s_addc_u32 s75, s39, 0
	s_waitcnt lgkmcnt(0)
	v_mfma_f32_16x16x32_bf16 v[20:23], v[132:135], v[198:201], v[20:23]
	s_add_i32 s76, s60, s48
	s_mov_b32 m0, s76
	v_mfma_f32_16x16x32_bf16 v[16:19], v[140:143], v[198:201], v[16:19]
	s_barrier
	global_load_lds_dwordx4 v150, s[74:75]
	s_add_i32 m0, s76, 0x2000
	s_waitcnt vmcnt(5)
	global_load_lds_dwordx4 v154, s[74:75]
	s_barrier
	v_mfma_f32_16x16x32_bf16 v[52:55], v[202:205], v[144:147], v[52:55]
	v_mfma_f32_16x16x32_bf16 v[48:51], v[210:213], v[144:147], v[48:51]
	v_mfma_f32_16x16x32_bf16 v[28:31], v[202:205], v[176:179], v[28:31]
	v_mfma_f32_16x16x32_bf16 v[24:27], v[210:213], v[176:179], v[24:27]
	v_mfma_f32_16x16x32_bf16 v[12:15], v[202:205], v[186:189], v[12:15]
	v_mfma_f32_16x16x32_bf16 v[8:11], v[210:213], v[186:189], v[8:11]
	v_mfma_f32_16x16x32_bf16 v[4:7], v[202:205], v[194:197], v[4:7]
	v_mfma_f32_16x16x32_bf16 v[0:3], v[210:213], v[194:197], v[0:3]
	v_mfma_f32_16x16x32_bf16 v[52:55], v[206:209], v[164:167], v[52:55]
	v_mfma_f32_16x16x32_bf16 v[48:51], v[214:217], v[164:167], v[48:51]
	v_mfma_f32_16x16x32_bf16 v[28:31], v[206:209], v[182:185], v[28:31]
	v_mfma_f32_16x16x32_bf16 v[24:27], v[214:217], v[182:185], v[24:27]
	v_mfma_f32_16x16x32_bf16 v[12:15], v[206:209], v[190:193], v[12:15]
	v_mfma_f32_16x16x32_bf16 v[8:11], v[214:217], v[190:193], v[8:11]
	v_mfma_f32_16x16x32_bf16 v[4:7], v[206:209], v[198:201], v[4:7]
	s_add_i32 s74, 0, 0x18000
	v_mfma_f32_16x16x32_bf16 v[0:3], v[214:217], v[198:201], v[0:3]
	s_barrier
	ds_read_b128 v[128:131], v253
	ds_read_b128 v[132:135], v253 offset:1024
	ds_read_b128 v[136:139], v253 offset:2048
	ds_read_b128 v[140:143], v253 offset:3072
	s_add_u32 s40, s40, 0xb0000
	s_addc_u32 s41, s41, 0
	s_mov_b32 m0, s51
	ds_read_b128 v[144:147], v174 offset:32768
	ds_read_b128 v[164:167], v174 offset:33792
	ds_read_b128 v[176:179], v174 offset:34816
	ds_read_b128 v[182:185], v174 offset:35840
	ds_read_b128 v[186:189], v174 offset:36864
	ds_read_b128 v[190:193], v174 offset:37888
	ds_read_b128 v[194:197], v174 offset:38912
	global_load_lds_dwordx4 v148, s[40:41]
	s_mov_b32 m0, s52
	ds_read_b128 v[198:201], v174 offset:39936
	global_load_lds_dwordx4 v152, s[40:41]
	s_waitcnt lgkmcnt(8)
	s_barrier
; #define PG8_STAGE(bufoff, gbase, voff) do { _Pragma("unroll") for (int _i = 0; _i < 2; ++_i) \
;         __builtin_amdgcn_global_load_lds((const unsigned*)((const char*)(gbase) + (voff)[_i]), (LAS unsigned*)(lds + (bufoff) + ldsw + _i * 8192), 16, 0, 0); } while (0)
; #define PG8_LDA(dst, b, h) do { _Pragma("unroll") for (int m = 0; m < 4; ++m) _Pragma("unroll") for (int k = 0; k < 2; ++k) dst[m][k] = *(const LAS bf16x8*)(lds + PG8_SA(b, h) + aoff + m * 2048 + k * 1024); } while (0)
; #define PG8_LDB(dst, b, h) do { _Pragma("unroll") for (int n = 0; n < 2; ++n) _Pragma("unroll") for (int k = 0; k < 2; ++k) dst[n][k] = *(const LAS bf16x8*)(lds + PG8_SB(b, h) + boff + n * 2048 + k * 1024); } while (0)
; #define PG8_MMA(ai, bj, At, Bt) do { __builtin_amdgcn_s_setprio(1); _Pragma("unroll") for (int m = 0; m < 4; ++m) _Pragma("unroll") for (int n = 0; n < 2; ++n) _Pragma("unroll") for (int k = 0; k < 2; ++k) \
;         acc[ai][bj][m][n] = __builtin_amdgcn_mfma_f32_16x16x32_bf16(Bt[n][k], At[m][k], acc[ai][bj][m][n], 0, 0, 0); __builtin_amdgcn_s_setprio(0); } while (0)
; #define PG8_WAIT_V(n) asm volatile("s_waitcnt vmcnt(" #n ")" ::: "memory")
; #define PG8_WAIT_L(n) asm volatile("s_waitcnt lgkmcnt(" #n ")" ::: "memory")
; #define PG8_BAR __builtin_amdgcn_s_barrier()
; #define PG8_SCHED __builtin_amdgcn_sched_barrier(0)
; template <class Epi>
; DI void gemm_phase(LAS unsigned char* lds, const Gemm g, const StaticOrder& S, const Epi& E) {
;     ...
;             PG8_LDB(B0, 1, 0); PG8_SCHED; PG8_LDA(At, 1, 0); PG8_STAGE(PG8_SA(0, 1), a2 + hstep, voffA);
;             PG8_WAIT_L(8); PG8_BAR; PG8_WAIT_L(0); PG8_MMA(0, 0, At, B0); PG8_BAR; PG8_SCHED;
;             PG8_LDB(B1, 1, 1); PG8_STAGE(PG8_SB(1, 0), b3, voffB);
;             PG8_BAR; PG8_WAIT_L(0); PG8_MMA(0, 1, At, B1); PG8_BAR;
;             PG8_LDA(At, 1, 1); PG8_STAGE(PG8_SA(1, 0), a3, voffA);
;             PG8_BAR; PG8_WAIT_L(0); PG8_MMA(1, 0, At, B0); PG8_BAR; PG8_SCHED;
;             PG8_STAGE(PG8_SB(1, 1), b3 + hstep, voffB);
;             PG8_WAIT_V(6); PG8_BAR; PG8_MMA(1, 1, At, B1); PG8_BAR;
	s_waitcnt lgkmcnt(7)
	v_mfma_f32_16x16x32_bf16 v[124:127], v[128:131], v[144:147], v[124:127]
	v_mfma_f32_16x16x32_bf16 v[120:123], v[136:139], v[144:147], v[120:123]
	s_waitcnt lgkmcnt(5)
	v_mfma_f32_16x16x32_bf16 v[116:119], v[128:131], v[176:179], v[116:119]
	v_mfma_f32_16x16x32_bf16 v[108:111], v[136:139], v[176:179], v[108:111]
	s_waitcnt lgkmcnt(3)
	v_mfma_f32_16x16x32_bf16 v[92:95], v[128:131], v[186:189], v[92:95]
	v_mfma_f32_16x16x32_bf16 v[88:91], v[136:139], v[186:189], v[88:91]
	s_waitcnt lgkmcnt(1)
	v_mfma_f32_16x16x32_bf16 v[76:79], v[128:131], v[194:197], v[76:79]
	v_mfma_f32_16x16x32_bf16 v[72:75], v[136:139], v[194:197], v[72:75]
	v_mfma_f32_16x16x32_bf16 v[124:127], v[132:135], v[164:167], v[124:127]
	v_mfma_f32_16x16x32_bf16 v[120:123], v[140:143], v[164:167], v[120:123]
	v_mfma_f32_16x16x32_bf16 v[116:119], v[132:135], v[182:185], v[116:119]
	v_mfma_f32_16x16x32_bf16 v[108:111], v[140:143], v[182:185], v[108:111]
	v_mfma_f32_16x16x32_bf16 v[92:95], v[132:135], v[190:193], v[92:95]
	v_mfma_f32_16x16x32_bf16 v[88:91], v[140:143], v[190:193], v[88:91]
	s_add_i32 s40, 0, 0x1c000
	s_add_i32 s41, s74, s48
	s_waitcnt lgkmcnt(0)
	v_mfma_f32_16x16x32_bf16 v[76:79], v[132:135], v[198:201], v[76:79]
	s_mov_b32 m0, s41
	v_mfma_f32_16x16x32_bf16 v[72:75], v[140:143], v[198:201], v[72:75]
	s_barrier
	ds_read_b128 v[202:205], v252
	ds_read_b128 v[206:209], v252 offset:1024
	ds_read_b128 v[210:213], v252 offset:2048
	global_load_lds_dwordx4 v150, s[86:87]
	s_add_i32 m0, s41, 0x2000
	ds_read_b128 v[214:217], v252 offset:3072
	global_load_lds_dwordx4 v154, s[86:87]
	s_barrier
	s_waitcnt lgkmcnt(3)
	v_mfma_f32_16x16x32_bf16 v[112:115], v[202:205], v[144:147], v[112:115]
	s_waitcnt lgkmcnt(1)
	v_mfma_f32_16x16x32_bf16 v[104:107], v[210:213], v[144:147], v[104:107]
	v_mfma_f32_16x16x32_bf16 v[100:103], v[202:205], v[176:179], v[100:103]
	v_mfma_f32_16x16x32_bf16 v[96:99], v[210:213], v[176:179], v[96:99]
	v_mfma_f32_16x16x32_bf16 v[84:87], v[202:205], v[186:189], v[84:87]
	v_mfma_f32_16x16x32_bf16 v[80:83], v[210:213], v[186:189], v[80:83]
	v_mfma_f32_16x16x32_bf16 v[68:71], v[202:205], v[194:197], v[68:71]
	v_mfma_f32_16x16x32_bf16 v[64:67], v[210:213], v[194:197], v[64:67]
	v_mfma_f32_16x16x32_bf16 v[112:115], v[206:209], v[164:167], v[112:115]
	s_waitcnt lgkmcnt(0)
	v_mfma_f32_16x16x32_bf16 v[104:107], v[214:217], v[164:167], v[104:107]
	v_mfma_f32_16x16x32_bf16 v[100:103], v[206:209], v[182:185], v[100:103]
	v_mfma_f32_16x16x32_bf16 v[96:99], v[214:217], v[182:185], v[96:99]
	v_mfma_f32_16x16x32_bf16 v[84:87], v[206:209], v[190:193], v[84:87]
	v_mfma_f32_16x16x32_bf16 v[80:83], v[214:217], v[190:193], v[80:83]
	v_mfma_f32_16x16x32_bf16 v[68:71], v[206:209], v[198:201], v[68:71]
	s_mov_b32 m0, s56
	v_mfma_f32_16x16x32_bf16 v[64:67], v[214:217], v[198:201], v[64:67]
	s_barrier
	ds_read_b128 v[144:147], v174 offset:49152
	ds_read_b128 v[164:167], v174 offset:50176
	ds_read_b128 v[176:179], v174 offset:51200
	ds_read_b128 v[182:185], v174 offset:52224
	ds_read_b128 v[186:189], v174 offset:53248
	ds_read_b128 v[190:193], v174 offset:54272
	ds_read_b128 v[194:197], v174 offset:55296
	global_load_lds_dwordx4 v148, s[88:89]
	s_mov_b32 m0, s57
	ds_read_b128 v[198:201], v174 offset:56320
	global_load_lds_dwordx4 v152, s[88:89]
	s_barrier
	s_waitcnt lgkmcnt(7)
	v_mfma_f32_16x16x32_bf16 v[60:63], v[128:131], v[144:147], v[60:63]
	v_mfma_f32_16x16x32_bf16 v[56:59], v[136:139], v[144:147], v[56:59]
	s_waitcnt lgkmcnt(5)
	v_mfma_f32_16x16x32_bf16 v[44:47], v[128:131], v[176:179], v[44:47]
	v_mfma_f32_16x16x32_bf16 v[40:43], v[136:139], v[176:179], v[40:43]
	s_waitcnt lgkmcnt(3)
	v_mfma_f32_16x16x32_bf16 v[36:39], v[128:131], v[186:189], v[36:39]
	v_mfma_f32_16x16x32_bf16 v[32:35], v[136:139], v[186:189], v[32:35]
	s_waitcnt lgkmcnt(1)
	v_mfma_f32_16x16x32_bf16 v[20:23], v[128:131], v[194:197], v[20:23]
	v_mfma_f32_16x16x32_bf16 v[16:19], v[136:139], v[194:197], v[16:19]
	v_mfma_f32_16x16x32_bf16 v[60:63], v[132:135], v[164:167], v[60:63]
	v_mfma_f32_16x16x32_bf16 v[56:59], v[140:143], v[164:167], v[56:59]
	v_mfma_f32_16x16x32_bf16 v[44:47], v[132:135], v[182:185], v[44:47]
	v_mfma_f32_16x16x32_bf16 v[40:43], v[140:143], v[182:185], v[40:43]
	v_mfma_f32_16x16x32_bf16 v[36:39], v[132:135], v[190:193], v[36:39]
	v_mfma_f32_16x16x32_bf16 v[32:35], v[140:143], v[190:193], v[32:35]
	s_add_u32 s38, s38, 0xb0080
	s_addc_u32 s39, s39, 0
	s_waitcnt lgkmcnt(0)
	v_mfma_f32_16x16x32_bf16 v[20:23], v[132:135], v[198:201], v[20:23]
	s_add_i32 s40, s40, s48
	s_mov_b32 m0, s40
	v_mfma_f32_16x16x32_bf16 v[16:19], v[140:143], v[198:201], v[16:19]
	s_barrier
	global_load_lds_dwordx4 v150, s[38:39]
	s_add_i32 m0, s40, 0x2000
	s_waitcnt vmcnt(5)
	global_load_lds_dwordx4 v154, s[38:39]
	s_barrier
	v_mfma_f32_16x16x32_bf16 v[52:55], v[202:205], v[144:147], v[52:55]
	v_mfma_f32_16x16x32_bf16 v[48:51], v[210:213], v[144:147], v[48:51]
	v_mfma_f32_16x16x32_bf16 v[28:31], v[202:205], v[176:179], v[28:31]
	v_mfma_f32_16x16x32_bf16 v[24:27], v[210:213], v[176:179], v[24:27]
	v_mfma_f32_16x16x32_bf16 v[12:15], v[202:205], v[186:189], v[12:15]
	v_mfma_f32_16x16x32_bf16 v[8:11], v[210:213], v[186:189], v[8:11]
	v_mfma_f32_16x16x32_bf16 v[4:7], v[202:205], v[194:197], v[4:7]
	v_mfma_f32_16x16x32_bf16 v[0:3], v[210:213], v[194:197], v[0:3]
	v_mfma_f32_16x16x32_bf16 v[52:55], v[206:209], v[164:167], v[52:55]
	s_add_i32 s73, s73, 2
	s_add_u32 s36, s36, 0x100
	v_mfma_f32_16x16x32_bf16 v[48:51], v[214:217], v[164:167], v[48:51]
	s_addc_u32 s37, s37, 0
	s_add_u32 s71, s71, 0x100
	v_mfma_f32_16x16x32_bf16 v[28:31], v[206:209], v[182:185], v[28:31]
	s_addc_u32 s72, s72, 0
	s_add_u32 s38, s36, 0xfff50080
	v_mfma_f32_16x16x32_bf16 v[24:27], v[214:217], v[182:185], v[24:27]
	s_addc_u32 s39, s37, -1
	s_cmp_eq_u32 s73, 40
	v_mfma_f32_16x16x32_bf16 v[12:15], v[206:209], v[190:193], v[12:15]
	s_cselect_b32 s41, s7, s39
	s_cselect_b32 s40, s6, s38
	v_mfma_f32_16x16x32_bf16 v[8:11], v[214:217], v[190:193], v[8:11]
	s_cselect_b32 s39, s9, s72
	s_cselect_b32 s38, s8, s71
	v_mfma_f32_16x16x32_bf16 v[4:7], v[206:209], v[198:201], v[4:7]
	s_add_i32 m0, s49, 0xc000
	v_mfma_f32_16x16x32_bf16 v[0:3], v[214:217], v[198:201], v[0:3]
	s_cmp_gt_u32 s73, 41
	s_barrier
; DI unsigned pk2(float a, float b) { f32x2 v = {a, b}; bf16x2_t r = __builtin_convertvector(v, bf16x2_t); return __builtin_bit_cast(unsigned, r); }
; DI float bflo(unsigned u) { return __uint_as_float(u << 16); }
; DI float bfhi(unsigned u) { return __uint_as_float(u & 0xffff0000u); }
;     DI void operator()(const f32x4 (&acc)[2][2][4][2], const Unit& u, int wr, int wc, int fr, int fq) const {
;         const int row0 = u.pm * BM + wr * 64 + fr, col0 = u.pn * BM + wc * 32 + 8 * fq;
;         const float* gp = gate + (size_t)((u.pm * BM) >> 12) * NMODC + col0;
;         f32x4 gv[2][2];
; #pragma unroll
;         for (int bj = 0; bj < 2; ++bj)
; #pragma unroll
;             for (int n = 0; n < 2; ++n) gv[bj][n] = *(const f32x4*)(gp + bj * HALF + n * 4);
; #pragma unroll
;         for (int ai = 0; ai < 2; ++ai)
; #pragma unroll
;             for (int m = 0; m < 4; ++m) { const size_t ro = (size_t)(row0 + ai * HALF + m * 16) * DM + col0;
; #pragma unroll
;                 for (int bj = 0; bj < 2; ++bj) {
;                     const u32x4 q = *(const u32x4*)(xb + ro + bj * HALF);
;                     const f32x4 b0 = {bflo(q.x), bfhi(q.x), bflo(q.y), bfhi(q.y)}, b1 = {bflo(q.z), bfhi(q.z), bflo(q.w), bfhi(q.w)};
;                     const f32x4 x0 = b0 + gv[bj][0] * acc[ai][bj][m][0], x1 = b1 + gv[bj][1] * acc[ai][bj][m][1];
;                     u32x4 w; w.x = pk2(x0.x, x0.y); w.y = pk2(x0.z, x0.w); w.z = pk2(x1.x, x1.y); w.w = pk2(x1.z, x1.w);
;                     *(u32x4*)(xb + ro + bj * HALF) = w; } }
	s_cbranch_scc0 .LBB0_928
	v_lshl_add_u32 v147, s67, 8, v170
	v_lshl_or_b32 v164, s70, 8, v172
	s_ashr_i32 s36, s67, 4
	s_mul_hi_i32 s37, s36, 0x6000
	s_mulk_i32 s36, 0x6000
	s_add_u32 s36, s54, s36
	s_addc_u32 s37, s55, s37
	v_lshlrev_b32_e32 v145, 2, v164
	v_lshlrev_b32_e32 v144, 11, v147
	global_load_dwordx4 v[128:131], v145, s[36:37]
	global_load_dwordx4 v[132:135], v145, s[36:37] offset:16
	global_load_dwordx4 v[136:139], v145, s[36:37] offset:512
	global_load_dwordx4 v[140:143], v145, s[36:37] offset:528
	v_lshl_add_u32 v144, v164, 1, v144
	s_mov_b32 s70, s65
	s_mov_b32 s67, s66
	s_mov_b64 s[38:39], s[8:9]
	s_mov_b64 s[36:37], s[6:7]
	global_load_dwordx4 v[184:187], v144, s[14:15]
	global_load_dwordx4 v[188:191], v144, s[14:15] offset:256
	v_add_u32_e32 v146, 0x8000, v144
	global_load_dwordx4 v[192:195], v146, s[14:15]
	global_load_dwordx4 v[196:199], v146, s[14:15] offset:256
	v_add_u32_e32 v146, 0x10000, v144
	global_load_dwordx4 v[200:203], v146, s[14:15]
	global_load_dwordx4 v[204:207], v146, s[14:15] offset:256
	v_add_u32_e32 v146, 0x18000, v144
	global_load_dwordx4 v[208:211], v146, s[14:15]
	global_load_dwordx4 v[212:215], v146, s[14:15] offset:256
	v_add_u32_e32 v146, 0x40000, v144
	global_load_dwordx4 v[216:219], v146, s[14:15]
	global_load_dwordx4 v[220:223], v146, s[14:15] offset:256
	v_add_u32_e32 v146, 0x48000, v144
	global_load_dwordx4 v[224:227], v146, s[14:15]
	global_load_dwordx4 v[228:231], v146, s[14:15] offset:256
	v_add_u32_e32 v146, 0x50000, v144
	global_load_dwordx4 v[232:235], v146, s[14:15]
	global_load_dwordx4 v[236:239], v146, s[14:15] offset:256
	v_add_u32_e32 v146, 0x58000, v144
	global_load_dwordx4 v[240:243], v146, s[14:15]
	global_load_dwordx4 v[244:247], v146, s[14:15] offset:256
	s_waitcnt vmcnt(15)
	v_lshlrev_b32_e32 v248, 16, v184
	v_and_b32_e32 v249, 0xffff0000, v184
	v_lshlrev_b32_e32 v250, 16, v185
	v_and_b32_e32 v251, 0xffff0000, v185
	v_lshlrev_b32_e32 v252, 16, v186
	v_and_b32_e32 v253, 0xffff0000, v186
	v_lshlrev_b32_e32 v254, 16, v187
	v_and_b32_e32 v255, 0xffff0000, v187
	v_pk_fma_f32 v[124:125], v[124:125], v[128:129], v[248:249]
	v_pk_fma_f32 v[126:127], v[126:127], v[130:131], v[250:251]
	v_pk_fma_f32 v[120:121], v[120:121], v[132:133], v[252:253]
	v_pk_fma_f32 v[122:123], v[122:123], v[134:135], v[254:255]
	v_cvt_pk_bf16_f32 v124, v124, v125
	v_cvt_pk_bf16_f32 v125, v126, v127
	v_cvt_pk_bf16_f32 v126, v120, v121
	v_cvt_pk_bf16_f32 v127, v122, v123
	global_store_dwordx4 v144, v[124:127], s[14:15]
	s_waitcnt vmcnt(15)
	v_lshlrev_b32_e32 v248, 16, v188
	v_and_b32_e32 v249, 0xffff0000, v188
	v_lshlrev_b32_e32 v250, 16, v189
	v_and_b32_e32 v251, 0xffff0000, v189
	v_lshlrev_b32_e32 v252, 16, v190
	v_and_b32_e32 v253, 0xffff0000, v190
	v_lshlrev_b32_e32 v254, 16, v191
	v_and_b32_e32 v255, 0xffff0000, v191
	v_pk_fma_f32 v[112:113], v[112:113], v[136:137], v[248:249]
	v_pk_fma_f32 v[114:115], v[114:115], v[138:139], v[250:251]
	v_pk_fma_f32 v[104:105], v[104:105], v[140:141], v[252:253]
	v_pk_fma_f32 v[106:107], v[106:107], v[142:143], v[254:255]
	v_cvt_pk_bf16_f32 v112, v112, v113
	v_cvt_pk_bf16_f32 v113, v114, v115
	v_cvt_pk_bf16_f32 v114, v104, v105
	v_cvt_pk_bf16_f32 v115, v106, v107
	global_store_dwordx4 v144, v[112:115], s[14:15] offset:256
	s_waitcnt vmcnt(15)
	v_lshlrev_b32_e32 v248, 16, v192
	v_and_b32_e32 v249, 0xffff0000, v192
	v_lshlrev_b32_e32 v250, 16, v193
	v_and_b32_e32 v251, 0xffff0000, v193
	v_lshlrev_b32_e32 v252, 16, v194
	v_and_b32_e32 v253, 0xffff0000, v194
	v_lshlrev_b32_e32 v254, 16, v195
	v_and_b32_e32 v255, 0xffff0000, v195
	v_pk_fma_f32 v[116:117], v[116:117], v[128:129], v[248:249]
	v_pk_fma_f32 v[118:119], v[118:119], v[130:131], v[250:251]
	v_pk_fma_f32 v[108:109], v[108:109], v[132:133], v[252:253]
	v_pk_fma_f32 v[110:111], v[110:111], v[134:135], v[254:255]
	v_cvt_pk_bf16_f32 v116, v116, v117
	v_cvt_pk_bf16_f32 v117, v118, v119
	v_cvt_pk_bf16_f32 v118, v108, v109
	v_cvt_pk_bf16_f32 v119, v110, v111
	v_add_u32_e32 v146, 0x8000, v144
	global_store_dwordx4 v146, v[116:119], s[14:15]
	s_waitcnt vmcnt(15)
	v_lshlrev_b32_e32 v248, 16, v196
	v_and_b32_e32 v249, 0xffff0000, v196
	v_lshlrev_b32_e32 v250, 16, v197
	v_and_b32_e32 v251, 0xffff0000, v197
	v_lshlrev_b32_e32 v252, 16, v198
	v_and_b32_e32 v253, 0xffff0000, v198
	v_lshlrev_b32_e32 v254, 16, v199
	v_and_b32_e32 v255, 0xffff0000, v199
	v_pk_fma_f32 v[100:101], v[100:101], v[136:137], v[248:249]
	v_pk_fma_f32 v[102:103], v[102:103], v[138:139], v[250:251]
	v_pk_fma_f32 v[96:97], v[96:97], v[140:141], v[252:253]
	v_pk_fma_f32 v[98:99], v[98:99], v[142:143], v[254:255]
	v_cvt_pk_bf16_f32 v100, v100, v101
	v_cvt_pk_bf16_f32 v101, v102, v103
	v_cvt_pk_bf16_f32 v102, v96, v97
	v_cvt_pk_bf16_f32 v103, v98, v99
	v_add_u32_e32 v146, 0x8000, v144
	global_store_dwordx4 v146, v[100:103], s[14:15] offset:256
	s_waitcnt vmcnt(15)
	v_lshlrev_b32_e32 v248, 16, v200
	v_and_b32_e32 v249, 0xffff0000, v200
	v_lshlrev_b32_e32 v250, 16, v201
	v_and_b32_e32 v251, 0xffff0000, v201
	v_lshlrev_b32_e32 v252, 16, v202
	v_and_b32_e32 v253, 0xffff0000, v202
	v_lshlrev_b32_e32 v254, 16, v203
	v_and_b32_e32 v255, 0xffff0000, v203
	v_pk_fma_f32 v[92:93], v[92:93], v[128:129], v[248:249]
	v_pk_fma_f32 v[94:95], v[94:95], v[130:131], v[250:251]
	v_pk_fma_f32 v[88:89], v[88:89], v[132:133], v[252:253]
	v_pk_fma_f32 v[90:91], v[90:91], v[134:135], v[254:255]
	v_cvt_pk_bf16_f32 v92, v92, v93
	v_cvt_pk_bf16_f32 v93, v94, v95
	v_cvt_pk_bf16_f32 v94, v88, v89
	v_cvt_pk_bf16_f32 v95, v90, v91
	v_add_u32_e32 v146, 0x10000, v144
	global_store_dwordx4 v146, v[92:95], s[14:15]
	s_waitcnt vmcnt(15)
; DI unsigned pk2(float a, float b) { f32x2 v = {a, b}; bf16x2_t r = __builtin_convertvector(v, bf16x2_t); return __builtin_bit_cast(unsigned, r); }
; DI float bflo(unsigned u) { return __uint_as_float(u << 16); }
; DI float bfhi(unsigned u) { return __uint_as_float(u & 0xffff0000u); }
;     DI void operator()(const f32x4 (&acc)[2][2][4][2], const Unit& u, int wr, int wc, int fr, int fq) const {
;     ...
;             for (int m = 0; m < 4; ++m) { const size_t ro = (size_t)(row0 + ai * HALF + m * 16) * DM + col0;
; #pragma unroll
;                 for (int bj = 0; bj < 2; ++bj) {
;                     const u32x4 q = *(const u32x4*)(xb + ro + bj * HALF);
;                     const f32x4 b0 = {bflo(q.x), bfhi(q.x), bflo(q.y), bfhi(q.y)}, b1 = {bflo(q.z), bfhi(q.z), bflo(q.w), bfhi(q.w)};
;                     const f32x4 x0 = b0 + gv[bj][0] * acc[ai][bj][m][0], x1 = b1 + gv[bj][1] * acc[ai][bj][m][1];
;                     u32x4 w; w.x = pk2(x0.x, x0.y); w.y = pk2(x0.z, x0.w); w.z = pk2(x1.x, x1.y); w.w = pk2(x1.z, x1.w);
;                     *(u32x4*)(xb + ro + bj * HALF) = w; } }
	v_lshlrev_b32_e32 v248, 16, v204
	v_and_b32_e32 v249, 0xffff0000, v204
	v_lshlrev_b32_e32 v250, 16, v205
	v_and_b32_e32 v251, 0xffff0000, v205
	v_lshlrev_b32_e32 v252, 16, v206
	v_and_b32_e32 v253, 0xffff0000, v206
	v_lshlrev_b32_e32 v254, 16, v207
	v_and_b32_e32 v255, 0xffff0000, v207
	v_pk_fma_f32 v[84:85], v[84:85], v[136:137], v[248:249]
	v_pk_fma_f32 v[86:87], v[86:87], v[138:139], v[250:251]
	v_pk_fma_f32 v[80:81], v[80:81], v[140:141], v[252:253]
	v_pk_fma_f32 v[82:83], v[82:83], v[142:143], v[254:255]
	v_cvt_pk_bf16_f32 v84, v84, v85
	v_cvt_pk_bf16_f32 v85, v86, v87
	v_cvt_pk_bf16_f32 v86, v80, v81
	v_cvt_pk_bf16_f32 v87, v82, v83
	v_add_u32_e32 v146, 0x10000, v144
	global_store_dwordx4 v146, v[84:87], s[14:15] offset:256
	s_waitcnt vmcnt(15)
	v_lshlrev_b32_e32 v248, 16, v208
	v_and_b32_e32 v249, 0xffff0000, v208
	v_lshlrev_b32_e32 v250, 16, v209
	v_and_b32_e32 v251, 0xffff0000, v209
	v_lshlrev_b32_e32 v252, 16, v210
	v_and_b32_e32 v253, 0xffff0000, v210
	v_lshlrev_b32_e32 v254, 16, v211
	v_and_b32_e32 v255, 0xffff0000, v211
	v_pk_fma_f32 v[76:77], v[76:77], v[128:129], v[248:249]
	v_pk_fma_f32 v[78:79], v[78:79], v[130:131], v[250:251]
	v_pk_fma_f32 v[72:73], v[72:73], v[132:133], v[252:253]
	v_pk_fma_f32 v[74:75], v[74:75], v[134:135], v[254:255]
	v_cvt_pk_bf16_f32 v76, v76, v77
	v_cvt_pk_bf16_f32 v77, v78, v79
	v_cvt_pk_bf16_f32 v78, v72, v73
	v_cvt_pk_bf16_f32 v79, v74, v75
	v_add_u32_e32 v146, 0x18000, v144
	global_store_dwordx4 v146, v[76:79], s[14:15]
	s_waitcnt vmcnt(15)
	v_lshlrev_b32_e32 v248, 16, v212
	v_and_b32_e32 v249, 0xffff0000, v212
	v_lshlrev_b32_e32 v250, 16, v213
	v_and_b32_e32 v251, 0xffff0000, v213
	v_lshlrev_b32_e32 v252, 16, v214
	v_and_b32_e32 v253, 0xffff0000, v214
	v_lshlrev_b32_e32 v254, 16, v215
	v_and_b32_e32 v255, 0xffff0000, v215
	v_pk_fma_f32 v[68:69], v[68:69], v[136:137], v[248:249]
	v_pk_fma_f32 v[70:71], v[70:71], v[138:139], v[250:251]
	v_pk_fma_f32 v[64:65], v[64:65], v[140:141], v[252:253]
	v_pk_fma_f32 v[66:67], v[66:67], v[142:143], v[254:255]
	v_cvt_pk_bf16_f32 v68, v68, v69
	v_cvt_pk_bf16_f32 v69, v70, v71
	v_cvt_pk_bf16_f32 v70, v64, v65
	v_cvt_pk_bf16_f32 v71, v66, v67
	v_add_u32_e32 v146, 0x18000, v144
	global_store_dwordx4 v146, v[68:71], s[14:15] offset:256
	s_waitcnt vmcnt(15)
	v_lshlrev_b32_e32 v248, 16, v216
	v_and_b32_e32 v249, 0xffff0000, v216
	v_lshlrev_b32_e32 v250, 16, v217
	v_and_b32_e32 v251, 0xffff0000, v217
	v_lshlrev_b32_e32 v252, 16, v218
	v_and_b32_e32 v253, 0xffff0000, v218
	v_lshlrev_b32_e32 v254, 16, v219
	v_and_b32_e32 v255, 0xffff0000, v219
	v_pk_fma_f32 v[60:61], v[60:61], v[128:129], v[248:249]
	v_pk_fma_f32 v[62:63], v[62:63], v[130:131], v[250:251]
	v_pk_fma_f32 v[56:57], v[56:57], v[132:133], v[252:253]
	v_pk_fma_f32 v[58:59], v[58:59], v[134:135], v[254:255]
	v_cvt_pk_bf16_f32 v60, v60, v61
	v_cvt_pk_bf16_f32 v61, v62, v63
	v_cvt_pk_bf16_f32 v62, v56, v57
	v_cvt_pk_bf16_f32 v63, v58, v59
	v_add_u32_e32 v146, 0x40000, v144
	global_store_dwordx4 v146, v[60:63], s[14:15]
	s_waitcnt vmcnt(15)
	v_lshlrev_b32_e32 v248, 16, v220
	v_and_b32_e32 v249, 0xffff0000, v220
	v_lshlrev_b32_e32 v250, 16, v221
	v_and_b32_e32 v251, 0xffff0000, v221
	v_lshlrev_b32_e32 v252, 16, v222
	v_and_b32_e32 v253, 0xffff0000, v222
	v_lshlrev_b32_e32 v254, 16, v223
	v_and_b32_e32 v255, 0xffff0000, v223
	v_pk_fma_f32 v[52:53], v[52:53], v[136:137], v[248:249]
	v_pk_fma_f32 v[54:55], v[54:55], v[138:139], v[250:251]
	v_pk_fma_f32 v[48:49], v[48:49], v[140:141], v[252:253]
	v_pk_fma_f32 v[50:51], v[50:51], v[142:143], v[254:255]
	v_cvt_pk_bf16_f32 v52, v52, v53
	v_cvt_pk_bf16_f32 v53, v54, v55
	v_cvt_pk_bf16_f32 v54, v48, v49
	v_cvt_pk_bf16_f32 v55, v50, v51
	v_add_u32_e32 v146, 0x40000, v144
	global_store_dwordx4 v146, v[52:55], s[14:15] offset:256
	s_waitcnt vmcnt(15)
	v_lshlrev_b32_e32 v248, 16, v224
	v_and_b32_e32 v249, 0xffff0000, v224
	v_lshlrev_b32_e32 v250, 16, v225
	v_and_b32_e32 v251, 0xffff0000, v225
	v_lshlrev_b32_e32 v252, 16, v226
	v_and_b32_e32 v253, 0xffff0000, v226
	v_lshlrev_b32_e32 v254, 16, v227
	v_and_b32_e32 v255, 0xffff0000, v227
	v_pk_fma_f32 v[44:45], v[44:45], v[128:129], v[248:249]
	v_pk_fma_f32 v[46:47], v[46:47], v[130:131], v[250:251]
	v_pk_fma_f32 v[40:41], v[40:41], v[132:133], v[252:253]
	v_pk_fma_f32 v[42:43], v[42:43], v[134:135], v[254:255]
	v_cvt_pk_bf16_f32 v44, v44, v45
	v_cvt_pk_bf16_f32 v45, v46, v47
	v_cvt_pk_bf16_f32 v46, v40, v41
	v_cvt_pk_bf16_f32 v47, v42, v43
	v_add_u32_e32 v146, 0x48000, v144
	global_store_dwordx4 v146, v[44:47], s[14:15]
	s_waitcnt vmcnt(15)
; DI unsigned pk2(float a, float b) { f32x2 v = {a, b}; bf16x2_t r = __builtin_convertvector(v, bf16x2_t); return __builtin_bit_cast(unsigned, r); }
; DI float bflo(unsigned u) { return __uint_as_float(u << 16); }
; DI float bfhi(unsigned u) { return __uint_as_float(u & 0xffff0000u); }
; template <class Epi>
; DI void gemm_phase(LAS unsigned char* lds, const Gemm g, const StaticOrder& S, const Epi& E) {
;     ...
;         if (!has_next) break;
; #pragma unroll
;         for (int a = 0; a < 2; ++a)
; #pragma unroll
;             for (int b = 0; b < 2; ++b)
; #pragma unroll
;                 for (int m = 0; m < 4; ++m)
; #pragma unroll
;                     for (int n = 0; n < 2; ++n) acc[a][b][m][n] = (f32x4){0.f, 0.f, 0.f, 0.f};
;         cur = nxt; cA = nA; cB = nB; ++ui;
;     }
;     DI void operator()(const f32x4 (&acc)[2][2][4][2], const Unit& u, int wr, int wc, int fr, int fq) const {
;     ...
;             for (int m = 0; m < 4; ++m) { const size_t ro = (size_t)(row0 + ai * HALF + m * 16) * DM + col0;
; #pragma unroll
;                 for (int bj = 0; bj < 2; ++bj) {
;                     const u32x4 q = *(const u32x4*)(xb + ro + bj * HALF);
;                     const f32x4 b0 = {bflo(q.x), bfhi(q.x), bflo(q.y), bfhi(q.y)}, b1 = {bflo(q.z), bfhi(q.z), bflo(q.w), bfhi(q.w)};
;                     const f32x4 x0 = b0 + gv[bj][0] * acc[ai][bj][m][0], x1 = b1 + gv[bj][1] * acc[ai][bj][m][1];
;                     u32x4 w; w.x = pk2(x0.x, x0.y); w.y = pk2(x0.z, x0.w); w.z = pk2(x1.x, x1.y); w.w = pk2(x1.z, x1.w);
;                     *(u32x4*)(xb + ro + bj * HALF) = w; } }
	v_lshlrev_b32_e32 v248, 16, v228
	v_and_b32_e32 v249, 0xffff0000, v228
	v_lshlrev_b32_e32 v250, 16, v229
	v_and_b32_e32 v251, 0xffff0000, v229
	v_lshlrev_b32_e32 v252, 16, v230
	v_and_b32_e32 v253, 0xffff0000, v230
	v_lshlrev_b32_e32 v254, 16, v231
	v_and_b32_e32 v255, 0xffff0000, v231
	v_pk_fma_f32 v[28:29], v[28:29], v[136:137], v[248:249]
	v_pk_fma_f32 v[30:31], v[30:31], v[138:139], v[250:251]
	v_pk_fma_f32 v[24:25], v[24:25], v[140:141], v[252:253]
	v_pk_fma_f32 v[26:27], v[26:27], v[142:143], v[254:255]
	v_cvt_pk_bf16_f32 v28, v28, v29
	v_cvt_pk_bf16_f32 v29, v30, v31
	v_cvt_pk_bf16_f32 v30, v24, v25
	v_cvt_pk_bf16_f32 v31, v26, v27
	v_add_u32_e32 v146, 0x48000, v144
	global_store_dwordx4 v146, v[28:31], s[14:15] offset:256
	s_waitcnt vmcnt(15)
	v_lshlrev_b32_e32 v248, 16, v232
	v_and_b32_e32 v249, 0xffff0000, v232
	v_lshlrev_b32_e32 v250, 16, v233
	v_and_b32_e32 v251, 0xffff0000, v233
	v_lshlrev_b32_e32 v252, 16, v234
	v_and_b32_e32 v253, 0xffff0000, v234
	v_lshlrev_b32_e32 v254, 16, v235
	v_and_b32_e32 v255, 0xffff0000, v235
	v_pk_fma_f32 v[36:37], v[36:37], v[128:129], v[248:249]
	v_pk_fma_f32 v[38:39], v[38:39], v[130:131], v[250:251]
	v_pk_fma_f32 v[32:33], v[32:33], v[132:133], v[252:253]
	v_pk_fma_f32 v[34:35], v[34:35], v[134:135], v[254:255]
	v_cvt_pk_bf16_f32 v36, v36, v37
	v_cvt_pk_bf16_f32 v37, v38, v39
	v_cvt_pk_bf16_f32 v38, v32, v33
	v_cvt_pk_bf16_f32 v39, v34, v35
	v_add_u32_e32 v146, 0x50000, v144
	global_store_dwordx4 v146, v[36:39], s[14:15]
	s_waitcnt vmcnt(15)
	v_lshlrev_b32_e32 v248, 16, v236
	v_and_b32_e32 v249, 0xffff0000, v236
	v_lshlrev_b32_e32 v250, 16, v237
	v_and_b32_e32 v251, 0xffff0000, v237
	v_lshlrev_b32_e32 v252, 16, v238
	v_and_b32_e32 v253, 0xffff0000, v238
	v_lshlrev_b32_e32 v254, 16, v239
	v_and_b32_e32 v255, 0xffff0000, v239
	v_pk_fma_f32 v[12:13], v[12:13], v[136:137], v[248:249]
	v_pk_fma_f32 v[14:15], v[14:15], v[138:139], v[250:251]
	v_pk_fma_f32 v[8:9], v[8:9], v[140:141], v[252:253]
	v_pk_fma_f32 v[10:11], v[10:11], v[142:143], v[254:255]
	v_cvt_pk_bf16_f32 v12, v12, v13
	v_cvt_pk_bf16_f32 v13, v14, v15
	v_cvt_pk_bf16_f32 v14, v8, v9
	v_cvt_pk_bf16_f32 v15, v10, v11
	v_add_u32_e32 v146, 0x50000, v144
	global_store_dwordx4 v146, v[12:15], s[14:15] offset:256
	s_waitcnt vmcnt(15)
	v_lshlrev_b32_e32 v248, 16, v240
	v_and_b32_e32 v249, 0xffff0000, v240
	v_lshlrev_b32_e32 v250, 16, v241
	v_and_b32_e32 v251, 0xffff0000, v241
	v_lshlrev_b32_e32 v252, 16, v242
	v_and_b32_e32 v253, 0xffff0000, v242
	v_lshlrev_b32_e32 v254, 16, v243
	v_and_b32_e32 v255, 0xffff0000, v243
	v_pk_fma_f32 v[20:21], v[20:21], v[128:129], v[248:249]
	v_pk_fma_f32 v[22:23], v[22:23], v[130:131], v[250:251]
	v_pk_fma_f32 v[16:17], v[16:17], v[132:133], v[252:253]
	v_pk_fma_f32 v[18:19], v[18:19], v[134:135], v[254:255]
	v_cvt_pk_bf16_f32 v20, v20, v21
	v_cvt_pk_bf16_f32 v21, v22, v23
	v_cvt_pk_bf16_f32 v22, v16, v17
	v_cvt_pk_bf16_f32 v23, v18, v19
	v_add_u32_e32 v146, 0x58000, v144
	global_store_dwordx4 v146, v[20:23], s[14:15]
	s_waitcnt vmcnt(15)
	v_lshlrev_b32_e32 v248, 16, v244
	v_and_b32_e32 v249, 0xffff0000, v244
	v_lshlrev_b32_e32 v250, 16, v245
	v_and_b32_e32 v251, 0xffff0000, v245
	v_lshlrev_b32_e32 v252, 16, v246
	v_and_b32_e32 v253, 0xffff0000, v246
	v_lshlrev_b32_e32 v254, 16, v247
	v_and_b32_e32 v255, 0xffff0000, v247
	v_pk_fma_f32 v[4:5], v[4:5], v[136:137], v[248:249]
	v_pk_fma_f32 v[6:7], v[6:7], v[138:139], v[250:251]
	v_pk_fma_f32 v[0:1], v[0:1], v[140:141], v[252:253]
	v_pk_fma_f32 v[2:3], v[2:3], v[142:143], v[254:255]
	v_cvt_pk_bf16_f32 v4, v4, v5
	v_cvt_pk_bf16_f32 v5, v6, v7
	v_cvt_pk_bf16_f32 v6, v0, v1
	v_cvt_pk_bf16_f32 v7, v2, v3
	v_add_u32_e32 v146, 0x58000, v144
	global_store_dwordx4 v146, v[4:7], s[14:15] offset:256
	s_and_b64 vcc, exec, s[4:5]
	s_cbranch_vccz .LBB0_917
	s_waitcnt vmcnt(0)
	s_cmpk_gt_u32 s42, 0xff
	s_cbranch_scc1 .LBB0_932
	s_barrier
